# all M1 and M2 output stores write-through (adds the lru log-a/b rows, S5 end states and LRU aggregates to the KV / scan outputs)
# baseline (speedup 1.0000x reference)
; #define LAS __attribute__((address_space(3)))
; __device__ __forceinline__ unsigned pk2(float lo, float hi) { return pg8::cvt_pk_bf16(lo, hi); }
; __device__ __forceinline__ void lds_wait() { asm volatile("s_waitcnt lgkmcnt(0)" ::: "memory"); }
; #define MFMA16(X, Y, ACC) ACC = __builtin_amdgcn_mfma_f32_16x16x32_bf16(X, Y, ACC, 0, 0, 0)
; template <bool FULL> __device__ __forceinline__ void s5_group(const Args& a, int l, int tile, int g, LAS unsigned char* lds, int lane, int wave) {
;     ...
;     for (int tb = 0; tb < 4; ++tb) {
;         const bf16x8 uf = ufa[tb]; u32x2 uraw; if (FULL) uraw = urawa[tb];
; #pragma unroll
;         for (int kt = 0; kt < 8; ++kt) { f32x4 d = {0.f, 0.f, 0.f, 0.f}; MFMA16(bbf[kt], uf, d); *(LAS f32x4*)(bus + (fr * 132 + kt * 16 + 4 * fq) * 4) = d; }
;         lds_wait();
;         float bra[16], bia[16];
; #pragma unroll
;         for (int tt = 0; tt < 16; ++tt) { bra[tt] = *(const LAS float*)(bus + (tt * 132 + lane) * 4); bia[tt] = *(const LAS float*)(bus + (tt * 132 + 64 + lane) * 4); }
; #pragma unroll
;         for (int tt = 0; tt < 16; ++tt) {
;             const float br = bra[tt], bi = bia[tt];
;             const float nre = lbr * sre - lbi * sim + br, nim = lbr * sim + lbi * sre + bi; sre = nre; sim = nim;
;             if (FULL) { const unsigned pr = pk2(sre, sim);
;                 *(LAS bf16*)(sst + (tt * 136 + lane) * 2) = (bf16)(pr & 0xffffu); *(LAS bf16*)(sst + (tt * 136 + 64 + lane) * 2) = (bf16)(pr >> 16); }
;         }
.LBB0_1266:
	s_or_b64 exec, exec, s[0:1]
	s_waitcnt vmcnt(0)
	v_mfma_f32_16x16x32_bf16 v[72:75], v[4:7], v[44:47], 0
	v_mul_f32_e32 v115, 0, v71
	v_fma_f32 v116, v70, 0, -v115
	v_fmac_f32_e32 v115, 0, v70
	v_mfma_f32_16x16x32_bf16 v[80:83], v[0:3], v[44:47], 0
	v_add_u32_e32 v64, 0x60, v68
	s_nop 2
	ds_write_b128 v69, v[72:75]
	v_add_u32_e32 v65, 0x70, v68
	v_mfma_f32_16x16x32_bf16 v[84:87], v[12:15], v[44:47], 0
	v_add_u32_e32 v79, 0xc0, v68
	v_add_u32_e32 v112, 0xd0, v68
	v_add_u32_e32 v113, 0xe0, v68
	v_mfma_f32_16x16x32_bf16 v[88:91], v[8:11], v[44:47], 0
	ds_write_b128 v69, v[80:83] offset:64
	s_nop 2
	ds_write_b128 v69, v[84:87] offset:128
	s_nop 2
	ds_write_b128 v69, v[88:91] offset:192
	v_add_u32_e32 v114, 0xf0, v68
	v_mfma_f32_16x16x32_bf16 v[92:95], v[20:23], v[44:47], 0
	s_add_i32 s0, s27, s26
	s_ashr_i32 s1, s0, 31
	s_lshl_b64 s[0:1], s[0:1], 9
	v_mfma_f32_16x16x32_bf16 v[72:75], v[16:19], v[44:47], 0
	s_xor_b64 s[4:5], s[4:5], -1
	s_andn2_b64 vcc, exec, s[4:5]
	s_mov_b64 s[4:5], 0
	v_mfma_f32_16x16x32_bf16 v[80:83], v[28:31], v[44:47], 0
	ds_write_b128 v69, v[92:95] offset:256
	s_nop 2
	ds_write_b128 v69, v[72:75] offset:320
	s_nop 2
	ds_write_b128 v69, v[80:83] offset:384
	v_add_u32_e32 v72, 0x80, v68
	v_mfma_f32_16x16x32_bf16 v[44:47], v[24:27], v[44:47], 0
	v_add_u32_e32 v73, 0x90, v68
	v_add_u32_e32 v74, 0xa0, v68
	v_add_u32_e32 v75, 0xb0, v68
	s_nop 4
	ds_write_b128 v69, v[44:47] offset:448
	s_waitcnt lgkmcnt(0)
	ds_read2st64_b32 v[80:81], v68 offset1:1
	ds_read2_b32 v[82:83], v68 offset0:132 offset1:196
	v_add_u32_e32 v44, 32, v68
	ds_read2st64_b32 v[84:85], v44 offset0:4 offset1:5
	v_add_u32_e32 v45, 48, v68
	s_waitcnt lgkmcnt(2)
	v_add_f32_e32 v81, v115, v81
	v_add_f32_e32 v80, v116, v80
	v_mul_f32_e32 v115, v71, v81
	v_mul_f32_e32 v81, v70, v81
	v_fmac_f32_e32 v81, v71, v80
	v_fma_f32 v115, v70, v80, -v115
	s_waitcnt lgkmcnt(1)
	v_add_f32_e32 v80, v83, v81
	v_add_f32_e32 v82, v82, v115
	v_mul_f32_e32 v81, v71, v80
	v_fma_f32 v81, v70, v82, -v81
	v_mul_f32_e32 v82, v71, v82
	ds_read2st64_b32 v[86:87], v45 offset0:6 offset1:7
	v_fmac_f32_e32 v82, v70, v80
	s_waitcnt lgkmcnt(1)
	v_add_f32_e32 v80, v85, v82
	v_add_f32_e32 v81, v84, v81
	v_mul_f32_e32 v82, v71, v80
	v_add_u32_e32 v46, 64, v68
	v_fma_f32 v82, v70, v81, -v82
	v_mul_f32_e32 v81, v71, v81
	ds_read2st64_b32 v[88:89], v46 offset0:8 offset1:9
	v_fmac_f32_e32 v81, v70, v80
	s_waitcnt lgkmcnt(1)
	v_add_f32_e32 v80, v87, v81
	v_add_f32_e32 v82, v86, v82
	v_mul_f32_e32 v81, v71, v80
	v_add_u32_e32 v47, 0x50, v68
	v_fma_f32 v81, v70, v82, -v81
	v_mul_f32_e32 v82, v71, v82
	ds_read2st64_b32 v[90:91], v47 offset0:10 offset1:11
	v_fmac_f32_e32 v82, v70, v80
	s_waitcnt lgkmcnt(1)
	v_add_f32_e32 v80, v89, v82
	v_add_f32_e32 v81, v88, v81
	v_mul_f32_e32 v82, v71, v80
	v_fma_f32 v82, v70, v81, -v82
	v_mul_f32_e32 v81, v71, v81
	ds_read2st64_b32 v[92:93], v64 offset0:12 offset1:13
	v_fmac_f32_e32 v81, v70, v80
	s_waitcnt lgkmcnt(1)
	v_add_f32_e32 v80, v91, v81
	v_add_f32_e32 v82, v90, v82
	v_mul_f32_e32 v81, v71, v80
	v_fma_f32 v81, v70, v82, -v81
	v_mul_f32_e32 v82, v71, v82
	ds_read2st64_b32 v[94:95], v65 offset0:14 offset1:15
	v_fmac_f32_e32 v82, v70, v80
	s_waitcnt lgkmcnt(1)
	v_add_f32_e32 v80, v93, v82
	v_add_f32_e32 v81, v92, v81
	v_mul_f32_e32 v82, v71, v80
	v_fma_f32 v82, v70, v81, -v82
	v_mul_f32_e32 v81, v71, v81
	ds_read2st64_b32 v[96:97], v72 offset0:16 offset1:17
	v_fmac_f32_e32 v81, v70, v80
	s_waitcnt lgkmcnt(1)
	v_add_f32_e32 v80, v95, v81
	v_add_f32_e32 v82, v94, v82
	v_mul_f32_e32 v81, v71, v80
	v_fma_f32 v81, v70, v82, -v81
	v_mul_f32_e32 v82, v71, v82
	ds_read2st64_b32 v[98:99], v73 offset0:18 offset1:19
	v_fmac_f32_e32 v82, v70, v80
	s_waitcnt lgkmcnt(1)
	v_add_f32_e32 v80, v97, v82
	v_add_f32_e32 v81, v96, v81
	v_mul_f32_e32 v82, v71, v80
	v_fma_f32 v82, v70, v81, -v82
	v_mul_f32_e32 v81, v71, v81
	ds_read2st64_b32 v[100:101], v74 offset0:20 offset1:21
	v_fmac_f32_e32 v81, v70, v80
	s_waitcnt lgkmcnt(1)
	v_add_f32_e32 v80, v99, v81
	v_add_f32_e32 v82, v98, v82
	v_mul_f32_e32 v81, v71, v80
	v_fma_f32 v81, v70, v82, -v81
	v_mul_f32_e32 v82, v71, v82
	ds_read2st64_b32 v[102:103], v75 offset0:22 offset1:23
	v_fmac_f32_e32 v82, v70, v80
	s_waitcnt lgkmcnt(1)
	v_add_f32_e32 v80, v101, v82
	v_add_f32_e32 v81, v100, v81
	v_mul_f32_e32 v82, v71, v80
	v_fma_f32 v82, v70, v81, -v82
	v_mul_f32_e32 v81, v71, v81
	ds_read2st64_b32 v[104:105], v79 offset0:24 offset1:25
	v_fmac_f32_e32 v81, v70, v80
	s_waitcnt lgkmcnt(1)
	v_add_f32_e32 v80, v103, v81
	v_add_f32_e32 v82, v102, v82
	v_mul_f32_e32 v81, v71, v80
	ds_read2st64_b32 v[106:107], v112 offset0:26 offset1:27
	v_fma_f32 v81, v70, v82, -v81
	v_mul_f32_e32 v82, v71, v82
	v_fmac_f32_e32 v82, v70, v80
	s_waitcnt lgkmcnt(1)
	v_add_f32_e32 v80, v105, v82
	ds_read2st64_b32 v[108:109], v113 offset0:28 offset1:29
	v_add_f32_e32 v81, v104, v81
	v_mul_f32_e32 v82, v71, v80
	v_fma_f32 v82, v70, v81, -v82
	v_mul_f32_e32 v84, v71, v81
	s_waitcnt lgkmcnt(1)
	v_add_f32_e32 v88, v106, v82
	v_fmac_f32_e32 v84, v70, v80
	v_add_f32_e32 v89, v107, v84
	v_mul_f32_e32 v92, v71, v88
	ds_read2st64_b32 v[110:111], v114 offset0:30 offset1:31
	v_mul_f32_e32 v84, v71, v89
	v_fmac_f32_e32 v92, v70, v89
	v_mfma_f32_16x16x32_bf16 v[80:83], v[4:7], v[40:43], 0
	v_fma_f32 v90, v70, v88, -v84
	s_waitcnt lgkmcnt(1)
	v_add_f32_e32 v97, v109, v92
	v_add_f32_e32 v96, v108, v90
	v_mfma_f32_16x16x32_bf16 v[84:87], v[0:3], v[40:43], 0
	v_mul_f32_e32 v92, v71, v97
	v_fma_f32 v98, v70, v96, -v92
	v_mul_f32_e32 v100, v71, v96
	v_mfma_f32_16x16x32_bf16 v[88:91], v[12:15], v[40:43], 0
	s_waitcnt lgkmcnt(0)
	v_add_f32_e32 v108, v110, v98
	v_fmac_f32_e32 v100, v70, v97
	s_waitcnt lgkmcnt(0)
; #define LAS __attribute__((address_space(3)))
; __device__ __forceinline__ void lds_wait() { asm volatile("s_waitcnt lgkmcnt(0)" ::: "memory"); }
; #define MFMA16(X, Y, ACC) ACC = __builtin_amdgcn_mfma_f32_16x16x32_bf16(X, Y, ACC, 0, 0, 0)
; template <bool FULL> __device__ __forceinline__ void s5_group(const Args& a, int l, int tile, int g, LAS unsigned char* lds, int lane, int wave) {
;     ...
;         for (int kt = 0; kt < 8; ++kt) { f32x4 d = {0.f, 0.f, 0.f, 0.f}; MFMA16(bbf[kt], uf, d); *(LAS f32x4*)(bus + (fr * 132 + kt * 16 + 4 * fq) * 4) = d; }
;         lds_wait();
;         float bra[16], bia[16];
; #pragma unroll
;         for (int tt = 0; tt < 16; ++tt) { bra[tt] = *(const LAS float*)(bus + (tt * 132 + lane) * 4); bia[tt] = *(const LAS float*)(bus + (tt * 132 + 64 + lane) * 4); }
; #pragma unroll
;         for (int tt = 0; tt < 16; ++tt) {
;             const float br = bra[tt], bi = bia[tt];
;             const float nre = lbr * sre - lbi * sim + br, nim = lbr * sim + lbi * sre + bi; sre = nre; sim = nim;
	v_mfma_f32_16x16x32_bf16 v[92:95], v[8:11], v[40:43], 0
	ds_write_b128 v69, v[80:83]
	ds_write_b128 v69, v[84:87] offset:64
	s_nop 1
	ds_write_b128 v69, v[88:91] offset:128
	s_nop 2
	ds_write_b128 v69, v[92:95] offset:192
	v_add_f32_e32 v109, v111, v100
	v_mfma_f32_16x16x32_bf16 v[96:99], v[20:23], v[40:43], 0
	v_mul_f32_e32 v110, v71, v109
	v_fma_f32 v110, v70, v108, -v110
	v_mul_f32_e32 v108, v71, v108
	v_mfma_f32_16x16x32_bf16 v[80:83], v[16:19], v[40:43], 0
	v_fmac_f32_e32 v108, v70, v109
	v_mfma_f32_16x16x32_bf16 v[84:87], v[28:31], v[40:43], 0
	s_nop 1
	ds_write_b128 v69, v[96:99] offset:256
	s_nop 2
	ds_write_b128 v69, v[80:83] offset:320
	s_nop 0
	ds_write_b128 v69, v[84:87] offset:384
	v_mfma_f32_16x16x32_bf16 v[40:43], v[24:27], v[40:43], 0
	s_nop 7
	ds_write_b128 v69, v[40:43] offset:448
	s_waitcnt lgkmcnt(0)
	ds_read2st64_b32 v[40:41], v68 offset1:1
	ds_read2_b32 v[42:43], v68 offset0:132 offset1:196
	ds_read2st64_b32 v[80:81], v44 offset0:4 offset1:5
	ds_read2st64_b32 v[82:83], v45 offset0:6 offset1:7
	ds_read2st64_b32 v[84:85], v46 offset0:8 offset1:9
	ds_read2st64_b32 v[86:87], v47 offset0:10 offset1:11
	ds_read2st64_b32 v[88:89], v64 offset0:12 offset1:13
	ds_read2st64_b32 v[90:91], v65 offset0:14 offset1:15
	ds_read2st64_b32 v[92:93], v72 offset0:16 offset1:17
	ds_read2st64_b32 v[94:95], v73 offset0:18 offset1:19
	ds_read2st64_b32 v[96:97], v74 offset0:20 offset1:21
	ds_read2st64_b32 v[98:99], v75 offset0:22 offset1:23
	ds_read2st64_b32 v[100:101], v79 offset0:24 offset1:25
	ds_read2st64_b32 v[102:103], v112 offset0:26 offset1:27
	ds_read2st64_b32 v[104:105], v113 offset0:28 offset1:29
	ds_read2st64_b32 v[106:107], v114 offset0:30 offset1:31
	s_waitcnt lgkmcnt(14)
	v_add_f32_e32 v41, v108, v41
	v_add_f32_e32 v40, v110, v40
	v_mul_f32_e32 v108, v71, v41
	v_mul_f32_e32 v41, v70, v41
	v_fmac_f32_e32 v41, v71, v40
	v_fma_f32 v108, v70, v40, -v108
	v_add_f32_e32 v40, v43, v41
	v_add_f32_e32 v42, v42, v108
	v_mul_f32_e32 v41, v71, v40
	v_fma_f32 v41, v70, v42, -v41
	v_mul_f32_e32 v42, v71, v42
	v_fmac_f32_e32 v42, v70, v40
	s_waitcnt lgkmcnt(13)
	v_add_f32_e32 v40, v81, v42
	v_add_f32_e32 v41, v80, v41
	v_mul_f32_e32 v42, v71, v40
	v_fma_f32 v42, v70, v41, -v42
	v_mul_f32_e32 v41, v71, v41
	v_fmac_f32_e32 v41, v70, v40
	s_waitcnt lgkmcnt(12)
	v_add_f32_e32 v40, v83, v41
	v_add_f32_e32 v42, v82, v42
	v_mul_f32_e32 v41, v71, v40
	v_fma_f32 v41, v70, v42, -v41
	v_mul_f32_e32 v42, v71, v42
	v_fmac_f32_e32 v42, v70, v40
	s_waitcnt lgkmcnt(11)
	v_add_f32_e32 v40, v85, v42
	v_add_f32_e32 v41, v84, v41
	v_mul_f32_e32 v42, v71, v40
	v_fma_f32 v42, v70, v41, -v42
	v_mul_f32_e32 v41, v71, v41
	v_fmac_f32_e32 v41, v70, v40
	s_waitcnt lgkmcnt(10)
	v_add_f32_e32 v40, v87, v41
	v_add_f32_e32 v42, v86, v42
	v_mul_f32_e32 v41, v71, v40
	v_fma_f32 v41, v70, v42, -v41
	v_mul_f32_e32 v42, v71, v42
	v_fmac_f32_e32 v42, v70, v40
	s_waitcnt lgkmcnt(9)
	v_add_f32_e32 v40, v89, v42
	v_add_f32_e32 v41, v88, v41
	v_mul_f32_e32 v42, v71, v40
	v_fma_f32 v42, v70, v41, -v42
	v_mul_f32_e32 v41, v71, v41
	v_fmac_f32_e32 v41, v70, v40
	s_waitcnt lgkmcnt(8)
	v_add_f32_e32 v40, v91, v41
	v_add_f32_e32 v42, v90, v42
	v_mul_f32_e32 v41, v71, v40
	v_fma_f32 v41, v70, v42, -v41
	v_mul_f32_e32 v42, v71, v42
	v_fmac_f32_e32 v42, v70, v40
	s_waitcnt lgkmcnt(7)
	v_add_f32_e32 v40, v93, v42
	v_add_f32_e32 v41, v92, v41
	v_mul_f32_e32 v42, v71, v40
	v_fma_f32 v42, v70, v41, -v42
	v_mul_f32_e32 v41, v71, v41
	v_fmac_f32_e32 v41, v70, v40
	s_waitcnt lgkmcnt(6)
	v_add_f32_e32 v40, v95, v41
	v_add_f32_e32 v42, v94, v42
	v_mul_f32_e32 v41, v71, v40
	v_fma_f32 v41, v70, v42, -v41
	v_mul_f32_e32 v42, v71, v42
	v_fmac_f32_e32 v42, v70, v40
	s_waitcnt lgkmcnt(5)
	v_add_f32_e32 v40, v97, v42
	v_add_f32_e32 v41, v96, v41
	v_mul_f32_e32 v42, v71, v40
	v_fma_f32 v42, v70, v41, -v42
	v_mul_f32_e32 v41, v71, v41
	v_fmac_f32_e32 v41, v70, v40
	s_waitcnt lgkmcnt(4)
	v_add_f32_e32 v40, v99, v41
	v_add_f32_e32 v42, v98, v42
	v_mul_f32_e32 v41, v71, v40
	v_fma_f32 v41, v70, v42, -v41
	v_mul_f32_e32 v42, v71, v42
	v_fmac_f32_e32 v42, v70, v40
	s_waitcnt lgkmcnt(3)
	v_add_f32_e32 v40, v101, v42
	v_add_f32_e32 v41, v100, v41
	v_mul_f32_e32 v42, v71, v40
	v_fma_f32 v42, v70, v41, -v42
	v_mul_f32_e32 v80, v71, v41
	s_waitcnt lgkmcnt(2)
	v_add_f32_e32 v84, v102, v42
	v_fmac_f32_e32 v80, v70, v40
	v_add_f32_e32 v85, v103, v80
	v_mul_f32_e32 v88, v71, v84
	v_mul_f32_e32 v80, v71, v85
	v_fmac_f32_e32 v88, v70, v85
	v_mfma_f32_16x16x32_bf16 v[40:43], v[4:7], v[36:39], 0
	v_fma_f32 v86, v70, v84, -v80
	s_waitcnt lgkmcnt(1)
	v_add_f32_e32 v93, v105, v88
	v_add_f32_e32 v92, v104, v86
	v_mfma_f32_16x16x32_bf16 v[80:83], v[0:3], v[36:39], 0
	v_mul_f32_e32 v88, v71, v93
	v_fma_f32 v94, v70, v92, -v88
	v_mul_f32_e32 v96, v71, v92
	v_mfma_f32_16x16x32_bf16 v[84:87], v[12:15], v[36:39], 0
	s_waitcnt lgkmcnt(0)
	v_add_f32_e32 v104, v106, v94
	v_fmac_f32_e32 v96, v70, v93
	s_waitcnt lgkmcnt(0)
	v_mfma_f32_16x16x32_bf16 v[88:91], v[8:11], v[36:39], 0
	ds_write_b128 v69, v[40:43]
	ds_write_b128 v69, v[80:83] offset:64
	s_nop 1
	ds_write_b128 v69, v[84:87] offset:128
	s_nop 2
	ds_write_b128 v69, v[88:91] offset:192
	v_add_f32_e32 v105, v107, v96
	v_mfma_f32_16x16x32_bf16 v[92:95], v[20:23], v[36:39], 0
	v_mul_f32_e32 v106, v71, v105
	v_fma_f32 v106, v70, v104, -v106
	v_mul_f32_e32 v104, v71, v104
	v_mfma_f32_16x16x32_bf16 v[40:43], v[16:19], v[36:39], 0
	v_fmac_f32_e32 v104, v70, v105
	v_mfma_f32_16x16x32_bf16 v[80:83], v[28:31], v[36:39], 0
	s_nop 1
	ds_write_b128 v69, v[92:95] offset:256
	s_nop 2
	ds_write_b128 v69, v[40:43] offset:320
	s_nop 0
	ds_write_b128 v69, v[80:83] offset:384
	v_mfma_f32_16x16x32_bf16 v[36:39], v[24:27], v[36:39], 0
	v_mfma_f32_16x16x32_bf16 v[4:7], v[4:7], v[32:35], 0
	v_mfma_f32_16x16x32_bf16 v[0:3], v[0:3], v[32:35], 0
	s_nop 5
	ds_write_b128 v69, v[36:39] offset:448
	s_waitcnt lgkmcnt(0)
; #define LAS __attribute__((address_space(3)))
; __device__ __forceinline__ void lds_wait() { asm volatile("s_waitcnt lgkmcnt(0)" ::: "memory"); }
; #define MFMA16(X, Y, ACC) ACC = __builtin_amdgcn_mfma_f32_16x16x32_bf16(X, Y, ACC, 0, 0, 0)
; template <bool FULL> __device__ __forceinline__ void s5_group(const Args& a, int l, int tile, int g, LAS unsigned char* lds, int lane, int wave) {
;     ...
;         for (int kt = 0; kt < 8; ++kt) { f32x4 d = {0.f, 0.f, 0.f, 0.f}; MFMA16(bbf[kt], uf, d); *(LAS f32x4*)(bus + (fr * 132 + kt * 16 + 4 * fq) * 4) = d; }
;         lds_wait();
;         float bra[16], bia[16];
; #pragma unroll
;         for (int tt = 0; tt < 16; ++tt) { bra[tt] = *(const LAS float*)(bus + (tt * 132 + lane) * 4); bia[tt] = *(const LAS float*)(bus + (tt * 132 + 64 + lane) * 4); }
; #pragma unroll
;         for (int tt = 0; tt < 16; ++tt) {
;             const float br = bra[tt], bi = bia[tt];
;             const float nre = lbr * sre - lbi * sim + br, nim = lbr * sim + lbi * sre + bi; sre = nre; sim = nim;
	ds_read2st64_b32 v[36:37], v68 offset1:1
	ds_read2_b32 v[38:39], v68 offset0:132 offset1:196
	ds_read2st64_b32 v[40:41], v44 offset0:4 offset1:5
	ds_read2st64_b32 v[42:43], v45 offset0:6 offset1:7
	ds_read2st64_b32 v[80:81], v46 offset0:8 offset1:9
	ds_read2st64_b32 v[82:83], v47 offset0:10 offset1:11
	ds_read2st64_b32 v[84:85], v64 offset0:12 offset1:13
	ds_read2st64_b32 v[86:87], v65 offset0:14 offset1:15
	ds_read2st64_b32 v[88:89], v72 offset0:16 offset1:17
	ds_read2st64_b32 v[90:91], v73 offset0:18 offset1:19
	ds_read2st64_b32 v[92:93], v74 offset0:20 offset1:21
	ds_read2st64_b32 v[94:95], v75 offset0:22 offset1:23
	ds_read2st64_b32 v[96:97], v79 offset0:24 offset1:25
	ds_read2st64_b32 v[98:99], v112 offset0:26 offset1:27
	ds_read2st64_b32 v[100:101], v113 offset0:28 offset1:29
	ds_read2st64_b32 v[102:103], v114 offset0:30 offset1:31
	s_waitcnt lgkmcnt(14)
	v_add_f32_e32 v37, v104, v37
	v_add_f32_e32 v36, v106, v36
	v_mul_f32_e32 v104, v71, v37
	v_mul_f32_e32 v37, v70, v37
	v_fmac_f32_e32 v37, v71, v36
	v_fma_f32 v104, v70, v36, -v104
	v_add_f32_e32 v36, v39, v37
	v_add_f32_e32 v38, v38, v104
	v_mul_f32_e32 v37, v71, v36
	v_fma_f32 v37, v70, v38, -v37
	v_mul_f32_e32 v38, v71, v38
	v_fmac_f32_e32 v38, v70, v36
	s_waitcnt lgkmcnt(13)
	v_add_f32_e32 v36, v41, v38
	v_add_f32_e32 v37, v40, v37
	v_mul_f32_e32 v38, v71, v36
	v_fma_f32 v38, v70, v37, -v38
	v_mul_f32_e32 v37, v71, v37
	v_fmac_f32_e32 v37, v70, v36
	s_waitcnt lgkmcnt(12)
	v_add_f32_e32 v36, v43, v37
	v_add_f32_e32 v38, v42, v38
	v_mul_f32_e32 v37, v71, v36
	v_fma_f32 v37, v70, v38, -v37
	v_mul_f32_e32 v38, v71, v38
	v_fmac_f32_e32 v38, v70, v36
	s_waitcnt lgkmcnt(11)
	v_add_f32_e32 v36, v81, v38
	v_add_f32_e32 v37, v80, v37
	v_mul_f32_e32 v38, v71, v36
	v_fma_f32 v38, v70, v37, -v38
	v_mul_f32_e32 v37, v71, v37
	v_fmac_f32_e32 v37, v70, v36
	s_waitcnt lgkmcnt(10)
	v_add_f32_e32 v36, v83, v37
	v_add_f32_e32 v38, v82, v38
	v_mul_f32_e32 v37, v71, v36
	v_fma_f32 v37, v70, v38, -v37
	v_mul_f32_e32 v38, v71, v38
	v_fmac_f32_e32 v38, v70, v36
	s_waitcnt lgkmcnt(9)
	v_add_f32_e32 v36, v85, v38
	v_add_f32_e32 v37, v84, v37
	v_mul_f32_e32 v38, v71, v36
	v_fma_f32 v38, v70, v37, -v38
	v_mul_f32_e32 v37, v71, v37
	v_fmac_f32_e32 v37, v70, v36
	s_waitcnt lgkmcnt(8)
	v_add_f32_e32 v36, v87, v37
	v_add_f32_e32 v38, v86, v38
	v_mul_f32_e32 v37, v71, v36
	v_fma_f32 v37, v70, v38, -v37
	v_mul_f32_e32 v38, v71, v38
	v_fmac_f32_e32 v38, v70, v36
	s_waitcnt lgkmcnt(7)
	v_add_f32_e32 v36, v89, v38
	v_add_f32_e32 v37, v88, v37
	v_mul_f32_e32 v38, v71, v36
	v_fma_f32 v38, v70, v37, -v38
	v_mul_f32_e32 v37, v71, v37
	v_fmac_f32_e32 v37, v70, v36
	s_waitcnt lgkmcnt(6)
	v_add_f32_e32 v36, v91, v37
	v_add_f32_e32 v38, v90, v38
	v_mul_f32_e32 v37, v71, v36
	v_fma_f32 v37, v70, v38, -v37
	v_mul_f32_e32 v38, v71, v38
	v_fmac_f32_e32 v38, v70, v36
	s_waitcnt lgkmcnt(5)
	v_add_f32_e32 v36, v93, v38
	v_add_f32_e32 v37, v92, v37
	v_mul_f32_e32 v38, v71, v36
	v_fma_f32 v38, v70, v37, -v38
	v_mul_f32_e32 v37, v71, v37
	v_fmac_f32_e32 v37, v70, v36
	s_waitcnt lgkmcnt(4)
	v_add_f32_e32 v36, v95, v37
	v_add_f32_e32 v38, v94, v38
	v_mul_f32_e32 v37, v71, v36
	v_fma_f32 v37, v70, v38, -v37
	v_mul_f32_e32 v38, v71, v38
	v_fmac_f32_e32 v38, v70, v36
	s_waitcnt lgkmcnt(3)
	v_add_f32_e32 v36, v97, v38
	v_add_f32_e32 v37, v96, v37
	v_mul_f32_e32 v38, v71, v36
	v_fma_f32 v38, v70, v37, -v38
	v_mul_f32_e32 v37, v71, v37
	v_fmac_f32_e32 v37, v70, v36
	v_mfma_f32_16x16x32_bf16 v[12:15], v[12:15], v[32:35], 0
	s_waitcnt lgkmcnt(2)
	v_add_f32_e32 v36, v99, v37
	v_add_f32_e32 v38, v98, v38
	v_mul_f32_e32 v37, v71, v36
	v_mfma_f32_16x16x32_bf16 v[8:11], v[8:11], v[32:35], 0
	s_waitcnt lgkmcnt(0)
	ds_write_b128 v69, v[4:7]
	v_fma_f32 v37, v70, v38, -v37
	v_mfma_f32_16x16x32_bf16 v[20:23], v[20:23], v[32:35], 0
	v_mul_f32_e32 v38, v71, v38
	ds_write_b128 v69, v[0:3] offset:64
	ds_write_b128 v69, v[12:15] offset:128
	s_nop 1
	ds_write_b128 v69, v[8:11] offset:192
	v_fmac_f32_e32 v38, v70, v36
	v_mfma_f32_16x16x32_bf16 v[4:7], v[16:19], v[32:35], 0
	s_waitcnt lgkmcnt(5)
	v_add_f32_e32 v36, v101, v38
	v_add_f32_e32 v37, v100, v37
	v_mul_f32_e32 v38, v71, v36
	v_mfma_f32_16x16x32_bf16 v[0:3], v[28:31], v[32:35], 0
	ds_write_b128 v69, v[20:23] offset:256
	s_nop 1
	ds_write_b128 v69, v[4:7] offset:320
	s_nop 3
	ds_write_b128 v69, v[0:3] offset:384
	v_fma_f32 v38, v70, v37, -v38
	v_mfma_f32_16x16x32_bf16 v[0:3], v[24:27], v[32:35], 0
	v_mul_f32_e32 v37, v71, v37
	v_fmac_f32_e32 v37, v70, v36
	s_waitcnt lgkmcnt(7)
; #define LAS __attribute__((address_space(3)))
; __device__ __forceinline__ unsigned pk2(float lo, float hi) { return pg8::cvt_pk_bf16(lo, hi); }
; template <bool FULL> __device__ __forceinline__ void s5_group(const Args& a, int l, int tile, int g, LAS unsigned char* lds, int lane, int wave) {
;     ...
;         for (int tt = 0; tt < 16; ++tt) { bra[tt] = *(const LAS float*)(bus + (tt * 132 + lane) * 4); bia[tt] = *(const LAS float*)(bus + (tt * 132 + 64 + lane) * 4); }
; #pragma unroll
;         for (int tt = 0; tt < 16; ++tt) {
;             const float br = bra[tt], bi = bia[tt];
;             const float nre = lbr * sre - lbi * sim + br, nim = lbr * sim + lbi * sre + bi; sre = nre; sim = nim;
;             if (FULL) { const unsigned pr = pk2(sre, sim);
;                 *(LAS bf16*)(sst + (tt * 136 + lane) * 2) = (bf16)(pr & 0xffffu); *(LAS bf16*)(sst + (tt * 136 + 64 + lane) * 2) = (bf16)(pr >> 16); }
;         }
;     ...
;     if (!FULL) { E[((size_t)(tile * 16 + g) * 2 + 0) * 64 + lane] = sre; E[((size_t)(tile * 16 + g) * 2 + 1) * 64 + lane] = sim; }
	v_add_f32_e32 v36, v103, v37
	v_add_f32_e32 v38, v102, v38
	v_mul_f32_e32 v32, v71, v36
	s_nop 1
	ds_write_b128 v69, v[0:3] offset:448
	s_waitcnt lgkmcnt(0)
	ds_read2st64_b32 v[0:1], v68 offset1:1
	ds_read2_b32 v[2:3], v68 offset0:132 offset1:196
	ds_read2st64_b32 v[4:5], v44 offset0:4 offset1:5
	ds_read2st64_b32 v[6:7], v45 offset0:6 offset1:7
	ds_read2st64_b32 v[8:9], v46 offset0:8 offset1:9
	ds_read2st64_b32 v[10:11], v47 offset0:10 offset1:11
	ds_read2st64_b32 v[12:13], v64 offset0:12 offset1:13
	ds_read2st64_b32 v[14:15], v65 offset0:14 offset1:15
	ds_read2st64_b32 v[16:17], v72 offset0:16 offset1:17
	ds_read2st64_b32 v[18:19], v73 offset0:18 offset1:19
	ds_read2st64_b32 v[20:21], v74 offset0:20 offset1:21
	ds_read2st64_b32 v[22:23], v75 offset0:22 offset1:23
	ds_read2st64_b32 v[24:25], v79 offset0:24 offset1:25
	ds_read2st64_b32 v[26:27], v112 offset0:26 offset1:27
	ds_read2st64_b32 v[28:29], v113 offset0:28 offset1:29
	ds_read2st64_b32 v[30:31], v114 offset0:30 offset1:31
	v_fma_f32 v32, v70, v38, -v32
	s_waitcnt lgkmcnt(14)
	v_add_f32_e32 v0, v32, v0
	v_mul_f32_e32 v32, v71, v38
	v_fmac_f32_e32 v32, v70, v36
	v_add_f32_e32 v1, v32, v1
	v_mul_f32_e32 v32, v71, v1
	v_mul_f32_e32 v1, v70, v1
	v_fmac_f32_e32 v1, v71, v0
	v_fma_f32 v32, v70, v0, -v32
	v_add_f32_e32 v0, v3, v1
	v_add_f32_e32 v2, v2, v32
	v_mul_f32_e32 v1, v71, v0
	v_fma_f32 v1, v70, v2, -v1
	v_mul_f32_e32 v2, v71, v2
	v_fmac_f32_e32 v2, v70, v0
	s_waitcnt lgkmcnt(13)
	v_add_f32_e32 v0, v5, v2
	v_add_f32_e32 v1, v4, v1
	v_mul_f32_e32 v2, v71, v0
	v_fma_f32 v2, v70, v1, -v2
	v_mul_f32_e32 v1, v71, v1
	v_fmac_f32_e32 v1, v70, v0
	s_waitcnt lgkmcnt(12)
	v_add_f32_e32 v0, v7, v1
	v_add_f32_e32 v2, v6, v2
	v_mul_f32_e32 v1, v71, v0
	v_fma_f32 v1, v70, v2, -v1
	v_mul_f32_e32 v2, v71, v2
	v_fmac_f32_e32 v2, v70, v0
	s_waitcnt lgkmcnt(11)
	v_add_f32_e32 v0, v9, v2
	v_add_f32_e32 v1, v8, v1
	v_mul_f32_e32 v2, v71, v0
	v_fma_f32 v2, v70, v1, -v2
	v_mul_f32_e32 v1, v71, v1
	v_fmac_f32_e32 v1, v70, v0
	s_waitcnt lgkmcnt(10)
	v_add_f32_e32 v0, v11, v1
	v_add_f32_e32 v2, v10, v2
	v_mul_f32_e32 v1, v71, v0
	v_fma_f32 v1, v70, v2, -v1
	v_mul_f32_e32 v2, v71, v2
	v_fmac_f32_e32 v2, v70, v0
	s_waitcnt lgkmcnt(9)
	v_add_f32_e32 v0, v13, v2
	v_add_f32_e32 v1, v12, v1
	v_mul_f32_e32 v2, v71, v0
	v_fma_f32 v2, v70, v1, -v2
	v_mul_f32_e32 v1, v71, v1
	v_fmac_f32_e32 v1, v70, v0
	s_waitcnt lgkmcnt(8)
	v_add_f32_e32 v0, v15, v1
	v_add_f32_e32 v2, v14, v2
	v_mul_f32_e32 v1, v71, v0
	v_fma_f32 v1, v70, v2, -v1
	v_mul_f32_e32 v2, v71, v2
	v_fmac_f32_e32 v2, v70, v0
	s_waitcnt lgkmcnt(7)
	v_add_f32_e32 v0, v17, v2
	v_add_f32_e32 v1, v16, v1
	v_mul_f32_e32 v2, v71, v0
	v_fma_f32 v2, v70, v1, -v2
	v_mul_f32_e32 v1, v71, v1
	v_fmac_f32_e32 v1, v70, v0
	s_waitcnt lgkmcnt(6)
	v_add_f32_e32 v0, v19, v1
	v_add_f32_e32 v2, v18, v2
	v_mul_f32_e32 v1, v71, v0
	v_fma_f32 v1, v70, v2, -v1
	v_mul_f32_e32 v2, v71, v2
	v_fmac_f32_e32 v2, v70, v0
	s_waitcnt lgkmcnt(5)
	v_add_f32_e32 v0, v21, v2
	v_add_f32_e32 v1, v20, v1
	v_mul_f32_e32 v2, v71, v0
	v_fma_f32 v2, v70, v1, -v2
	v_mul_f32_e32 v1, v71, v1
	v_fmac_f32_e32 v1, v70, v0
	s_waitcnt lgkmcnt(4)
	v_add_f32_e32 v0, v23, v1
	v_add_f32_e32 v2, v22, v2
	v_mul_f32_e32 v1, v71, v0
	v_fma_f32 v1, v70, v2, -v1
	v_mul_f32_e32 v2, v71, v2
	v_fmac_f32_e32 v2, v70, v0
	s_waitcnt lgkmcnt(3)
	v_add_f32_e32 v0, v25, v2
	v_add_f32_e32 v1, v24, v1
	v_mul_f32_e32 v2, v71, v0
	v_fma_f32 v2, v70, v1, -v2
	v_mul_f32_e32 v1, v71, v1
	v_fmac_f32_e32 v1, v70, v0
	s_waitcnt lgkmcnt(2)
	v_add_f32_e32 v0, v27, v1
	v_add_f32_e32 v2, v26, v2
	v_mul_f32_e32 v1, v71, v0
	v_fma_f32 v1, v70, v2, -v1
	v_mul_f32_e32 v2, v71, v2
	v_fmac_f32_e32 v2, v70, v0
	s_waitcnt lgkmcnt(1)
	v_add_f32_e32 v0, v29, v2
	v_add_f32_e32 v1, v28, v1
	v_mul_f32_e32 v2, v71, v0
	v_fma_f32 v2, v70, v1, -v2
	v_mul_f32_e32 v1, v71, v1
	s_waitcnt lgkmcnt(0)
	v_fmac_f32_e32 v1, v70, v0
	s_waitcnt lgkmcnt(0)
	v_add_f32_e32 v2, v30, v2
	v_add_f32_e32 v3, v31, v1
	v_lshl_add_u64 v[0:1], v[62:63], 0, s[0:1]
	s_mov_b32 s0, 1
	global_store_dword v[0:1], v2, off sc1
	global_store_dword v[0:1], v3, off offset:256 sc1
	s_cbranch_vccz .LBB0_1291

; #define LAS __attribute__((address_space(3)))
; __device__ __forceinline__ unsigned pk2(float lo, float hi) { return pg8::cvt_pk_bf16(lo, hi); }
; __device__ __forceinline__ float sigmoidf_(float x) { return __builtin_amdgcn_rcpf(1.0f + __expf(-x)); }
; template <bool FULL> __device__ __forceinline__ void lru_tile(const Args& a, int l, int tile, LAS unsigned char* lds, int tid, int lane, int wave) {
;     ...
;         u32x4 w; w.x = pk2(xc[0], xc[1]); w.y = pk2(xc[2], xc[3]); w.z = pk2(xc[4], xc[5]); w.w = pk2(xc[6], xc[7]);
;         *(LAS u32x4*)(lds + OFF_XC + (t * 264 + c8 * 8) * 2) = w;
;     }
;     __syncthreads();
;     {
;         const int cb = wave & 3, chh = wave >> 2; const bf16* WA = (const bf16*)(wl + WL_WA); const bf16* WX = (const bf16*)(wl + WL_WX);
;         const float* c8t = (const float*)(a.ws + WS_TAB) + (size_t)l * 256;
;         f32x4 av[8], bv[8];
; #pragma unroll
;         for (int et = 0; et < 8; ++et) {
;             const int e0 = chh * 128 + et * 16, nb = e0 >> 6, el = e0 & 63;
;             f32x4 ra = {0.f, 0.f, 0.f, 0.f}, ia = {0.f, 0.f, 0.f, 0.f};
; #pragma unroll
;             for (int ks = 0; ks < 2; ++ks) {
;                 const bf16x8 xv = *(const LAS bf16x8*)(lds + OFF_XC + ((cb * 16 + fr) * 264 + nb * 64 + 32 * ks + 8 * fq) * 2);
;                 const bf16x8 wa = *(const bf16x8*)(WA + (size_t)nb * 4096 + (el + fr) * 64 + 32 * ks + 8 * fq);
;                 const bf16x8 wx = *(const bf16x8*)(WX + (size_t)nb * 4096 + (el + fr) * 64 + 32 * ks + 8 * fq);
;                 MFMA16(wa, xv, ra); MFMA16(wx, xv, ia);
;             }
;             const int c0 = e0 + 4 * fq;
;             const f32x4 ba = *(const f32x4*)(a.in[22] + (size_t)l * 256 + c0), bx = *(const f32x4*)(a.in[24] + (size_t)l * 256 + c0), c8v = *(const f32x4*)(c8t + c0);
;             const u32x2 xr = *(const LAS u32x2*)(lds + OFF_XC + ((cb * 16 + fr) * 264 + c0) * 2);
;             float lav[4];
;             const float xcv[4] = {__uint_as_float(xr.x << 16), __uint_as_float(xr.x & 0xffff0000u), __uint_as_float(xr.y << 16), __uint_as_float(xr.y & 0xffff0000u)};
; #pragma unroll
;             for (int r = 0; r < 4; ++r) {
;                 const float rg = sigmoidf_(ra[r] + ba[r]), ig = sigmoidf_(ia[r] + bx[r]);
;                 const float la = c8v[r] * rg; const float av_ = __expf(la); const float m2 = -expm1f(2.0f * la);
.LBB0_1323:
	s_or_b64 exec, exec, s[0:1]
	s_waitcnt vmcnt(0)
	v_cvt_pk_bf16_f32 v4, v4, v5
	v_cvt_pk_bf16_f32 v5, v6, v7
	v_cvt_pk_bf16_f32 v6, v0, v1
	v_mad_u64_u32 v[0:1], s[0:1], v9, s12, v[8:9]
	s_ashr_i32 s4, s7, 8
	s_add_i32 s0, 0, 0x10000
	s_lshl_b32 s24, s4, 1
	v_lshl_add_u32 v0, v0, 1, s0
	s_bfe_u32 s1, s7, 0x20006
	s_ashr_i32 s25, s24, 31
	v_cvt_pk_bf16_f32 v7, v2, v3
	ds_write_b128 v0, v[4:7]
	v_lshrrev_b32_e32 v0, 4, v66
	s_lshl_b32 s5, s4, 7
	s_lshl_b32 s7, s1, 4
	s_lshl_b64 s[24:25], s[24:25], 13
	v_or_b32_e32 v79, s7, v77
	v_lshlrev_b32_e32 v1, 3, v0
	v_lshlrev_b32_e32 v86, 2, v0
	v_or_b32_e32 v0, s7, v67
	s_add_u32 s40, s57, s24
	v_mad_u32_u24 v50, v79, s12, v1
	v_ashrrev_i32_e32 v1, 31, v0
	s_addc_u32 s41, s58, s25
	v_lshlrev_b64 v[0:1], 11, v[0:1]
	v_lshlrev_b32_e32 v144, 7, v77
	s_add_u32 s42, s59, s24
	v_lshl_add_u64 v[52:53], s[78:79], 0, v[0:1]
	v_add_u32_e32 v2, s5, v50
	v_lshl_add_u64 v[0:1], s[40:41], 0, v[144:145]
	v_and_b32_e32 v68, 48, v66
	v_mov_b32_e32 v69, v145
	s_addc_u32 s43, s60, s25
	v_lshl_add_u64 v[20:21], v[0:1], 0, v[68:69]
	v_lshl_add_u64 v[0:1], s[42:43], 0, v[144:145]
	v_lshl_add_u32 v38, v2, 1, s0
	s_waitcnt lgkmcnt(0)
	s_barrier
	global_load_dwordx4 v[118:121], v[20:21], off
	global_load_dwordx4 v[122:125], v[20:21], off offset:64
	global_load_dwordx4 v[126:129], v[20:21], off offset:2048
	global_load_dwordx4 v[130:133], v[20:21], off offset:2112
	v_lshl_add_u64 v[22:23], v[0:1], 0, v[68:69]
	global_load_dwordx4 v[134:137], v[22:23], off
	global_load_dwordx4 v[138:141], v[22:23], off offset:64
	global_load_dwordx4 v[150:153], v[22:23], off offset:2048
	ds_read_b128 v[0:3], v38
	ds_read_b128 v[12:15], v38 offset:64
	v_or_b32_e32 v54, s5, v86
	v_ashrrev_i32_e32 v55, 31, v54
	v_readlane_b32 s28, v254, 47
	v_readlane_b32 s29, v254, 48
	v_readlane_b32 s16, v254, 45
	v_readlane_b32 s30, v254, 49
	v_readlane_b32 s17, v254, 46
	v_readlane_b32 s31, v254, 50
	v_mad_u32_u24 v24, v79, s12, v54
	v_lshl_add_u32 v51, v24, 1, s0
	v_lshl_add_u64 v[48:49], v[54:55], 1, v[52:53]
	v_or_b32_e32 v60, 0x1000, v144
	v_mov_b32_e32 v61, v145
	v_mov_b32_e32 v71, v145
	s_or_b32 s7, s5, 64
	s_ashr_i32 s24, s7, 6
	s_ashr_i32 s25, s24, 31
	s_lshl_b64 s[24:25], s[24:25], 13
	s_add_u32 s26, s57, s24
	s_addc_u32 s27, s58, s25
	s_add_u32 s24, s59, s24
	s_addc_u32 s25, s60, s25
	s_waitcnt vmcnt(6) lgkmcnt(1)
	v_mfma_f32_16x16x32_bf16 v[4:7], v[118:121], v[0:3], 0
	s_waitcnt vmcnt(2)
	v_mfma_f32_16x16x32_bf16 v[0:3], v[134:137], v[0:3], 0
	ds_read_b64 v[24:25], v51
	s_waitcnt vmcnt(2) lgkmcnt(1)
	v_mfma_f32_16x16x32_bf16 v[8:11], v[122:125], v[12:15], v[4:7]
	s_waitcnt vmcnt(1)
	v_mfma_f32_16x16x32_bf16 v[4:7], v[138:141], v[12:15], v[0:3]
	s_nop 2
	v_lshlrev_b64 v[0:1], 2, v[54:55]
	v_lshl_add_u64 v[40:41], s[28:29], 0, v[0:1]
	global_load_dwordx4 v[16:19], v[40:41], off
	v_lshl_add_u64 v[44:45], s[16:17], 0, v[0:1]
	v_lshl_add_u64 v[46:47], s[30:31], 0, v[0:1]
	global_load_dwordx4 v[0:3], v[44:45], off
	global_load_dwordx4 v[118:121], v[46:47], off
	s_waitcnt vmcnt(2)
	v_add_f32_e32 v8, v8, v16
	v_add_f32_e32 v9, v9, v17
	v_mul_f32_e32 v8, 0xbfb8aa3b, v8
	v_mul_f32_e32 v9, 0xbfb8aa3b, v9
	v_exp_f32_e32 v8, v8
	v_exp_f32_e32 v9, v9
	s_waitcnt vmcnt(0)
	v_add_f32_e32 v4, v4, v118
	v_add_f32_e32 v5, v5, v119
	v_add_f32_e32 v8, 1.0, v8
	v_add_f32_e32 v9, 1.0, v9
	v_rcp_f32_e32 v8, v8
	v_rcp_f32_e32 v9, v9
	s_waitcnt lgkmcnt(0)
	v_lshlrev_b32_e32 v12, 16, v24
	v_and_b32_e32 v13, 0xffff0000, v24
	v_add_f32_e32 v10, v10, v18
	v_pk_mul_f32 v[8:9], v[0:1], v[8:9]
	v_add_f32_e32 v11, v11, v19
	v_pk_add_f32 v[16:17], v[8:9], v[8:9]
	v_mul_f32_e32 v10, 0xbfb8aa3b, v10
	v_mul_f32_e32 v1, 0x3fb8aa3b, v16
	v_rndne_f32_e32 v1, v1
	v_fmamk_f32 v24, v1, 0xbf317218, v16
	v_fmac_f32_e32 v24, 0x3102e308, v1
	v_fmamk_f32 v26, v24, 0x395133b1, v177
	v_cmp_eq_f32_e32 vcc, s2, v1
	v_cvt_i32_f32_e32 v1, v1
	v_fmaak_f32 v26, v24, v26, 0x3c0887f9
	v_fmaak_f32 v26, v24, v26, 0x3d2aaa81
	v_fmaak_f32 v26, v24, v26, 0x3e2aaaab
	v_fma_f32 v26, v24, v26, 0.5
	v_ldexp_f32 v1, 1.0, v1
	v_mul_f32_e32 v26, v24, v26
	v_cndmask_b32_e32 v1, v1, v195, vcc
	v_fmac_f32_e32 v24, v24, v26
	v_add_f32_e32 v26, -1.0, v1
	v_fmac_f32_e32 v26, v1, v24
	v_add_f32_e32 v1, v26, v26
	v_cndmask_b32_e32 v1, v26, v1, vcc
	v_max_f32_e64 v1, -v1, 0
	v_cmp_gt_f32_e32 vcc, s19, v1
	v_mul_f32_e32 v24, 0x4f800000, v1
	v_mul_f32_e32 v11, 0xbfb8aa3b, v11
	v_cndmask_b32_e32 v1, v1, v24, vcc
	v_sqrt_f32_e32 v24, v1
	v_exp_f32_e32 v10, v10
	v_exp_f32_e32 v11, v11
	v_mul_f32_e32 v4, 0xbfb8aa3b, v4
	v_add_u32_e32 v26, -1, v24
	v_fma_f32 v27, -v26, v24, v1
	v_cmp_ge_f32_e64 s[36:37], 0, v27
	v_add_u32_e32 v27, 1, v24
	v_mul_f32_e32 v5, 0xbfb8aa3b, v5
	v_cndmask_b32_e64 v26, v24, v26, s[36:37]
	v_fma_f32 v24, -v27, v24, v1
	v_cmp_lt_f32_e64 s[36:37], 0, v24
	v_exp_f32_e32 v4, v4
	v_exp_f32_e32 v5, v5
	v_cndmask_b32_e64 v24, v26, v27, s[36:37]
	v_mul_f32_e32 v26, 0x37800000, v24
	v_cndmask_b32_e32 v24, v24, v26, vcc
	v_cmp_class_f32_e32 vcc, v1, v178
	v_add_f32_e32 v10, 1.0, v10
	v_add_f32_e32 v11, 1.0, v11
	v_cndmask_b32_e32 v1, v24, v1, vcc
	v_mul_f32_e32 v24, 0x3fb8aa3b, v17
	v_rndne_f32_e32 v24, v24
	v_fmamk_f32 v26, v24, 0xbf317218, v17
	v_fmac_f32_e32 v26, 0x3102e308, v24
	v_fmamk_f32 v27, v26, 0x395133b1, v177
	v_cmp_eq_f32_e32 vcc, s2, v24
	v_cvt_i32_f32_e32 v24, v24
	v_fmaak_f32 v27, v26, v27, 0x3c0887f9
	v_fmaak_f32 v27, v26, v27, 0x3d2aaa81
	v_fmaak_f32 v27, v26, v27, 0x3e2aaaab
	v_fma_f32 v27, v26, v27, 0.5
	v_ldexp_f32 v24, 1.0, v24
	v_mul_f32_e32 v27, v26, v27
	v_cndmask_b32_e32 v24, v24, v195, vcc
	v_fmac_f32_e32 v26, v26, v27
	v_add_f32_e32 v27, -1.0, v24
	v_fmac_f32_e32 v27, v24, v26
; #define LAS __attribute__((address_space(3)))
; __device__ __forceinline__ unsigned pk2(float lo, float hi) { return pg8::cvt_pk_bf16(lo, hi); }
; __device__ __forceinline__ float sigmoidf_(float x) { return __builtin_amdgcn_rcpf(1.0f + __expf(-x)); }
; template <bool FULL> __device__ __forceinline__ void lru_tile(const Args& a, int l, int tile, LAS unsigned char* lds, int tid, int lane, int wave) {
;     ...
;             const int c0 = e0 + 4 * fq;
;             const f32x4 ba = *(const f32x4*)(a.in[22] + (size_t)l * 256 + c0), bx = *(const f32x4*)(a.in[24] + (size_t)l * 256 + c0), c8v = *(const f32x4*)(c8t + c0);
;             const u32x2 xr = *(const LAS u32x2*)(lds + OFF_XC + ((cb * 16 + fr) * 264 + c0) * 2);
;             float lav[4];
;             const float xcv[4] = {__uint_as_float(xr.x << 16), __uint_as_float(xr.x & 0xffff0000u), __uint_as_float(xr.y << 16), __uint_as_float(xr.y & 0xffff0000u)};
; #pragma unroll
;             for (int r = 0; r < 4; ++r) {
;                 const float rg = sigmoidf_(ra[r] + ba[r]), ig = sigmoidf_(ia[r] + bx[r]);
;                 const float la = c8v[r] * rg; const float av_ = __expf(la); const float m2 = -expm1f(2.0f * la);
;                 av[et][r] = av_; bv[et][r] = sqrtf(fmaxf(m2, 0.f)) * ig * xcv[r]; lav[r] = la;
;             }
;             {
;               bf16* yr = Y + (size_t)(t0 + cb * 16 + fr) * DM + c0;
;               u32x2 wl_; wl_.x = pk2(lav[0], lav[1]); wl_.y = pk2(lav[2], lav[3]); *(u32x2*)(yr + 768) = wl_;
;               u32x2 wb_; wb_.x = pk2(bv[et][0], bv[et][1]); wb_.y = pk2(bv[et][2], bv[et][3]); *(u32x2*)(yr + 512) = wb_; }
	v_add_f32_e32 v24, v27, v27
	v_cndmask_b32_e32 v24, v27, v24, vcc
	v_max_f32_e64 v24, -v24, 0
	v_cmp_gt_f32_e32 vcc, s19, v24
	v_mul_f32_e32 v26, 0x4f800000, v24
	v_rcp_f32_e32 v10, v10
	v_cndmask_b32_e32 v24, v24, v26, vcc
	v_sqrt_f32_e32 v26, v24
	v_rcp_f32_e32 v11, v11
	v_add_f32_e32 v4, 1.0, v4
	v_add_f32_e32 v5, 1.0, v5
	v_add_u32_e32 v27, -1, v26
	v_fma_f32 v28, -v27, v26, v24
	v_cmp_ge_f32_e64 s[36:37], 0, v28
	v_add_u32_e32 v28, 1, v26
	v_rcp_f32_e32 v4, v4
	v_cndmask_b32_e64 v27, v26, v27, s[36:37]
	v_fma_f32 v26, -v28, v26, v24
	v_cmp_lt_f32_e64 s[36:37], 0, v26
	v_rcp_f32_e32 v5, v5
	v_pk_mul_f32 v[10:11], v[2:3], v[10:11]
	v_cndmask_b32_e64 v26, v27, v28, s[36:37]
	global_load_dwordx4 v[28:31], v[22:23], off offset:2112
	v_mul_f32_e32 v27, 0x37800000, v26
	v_cndmask_b32_e32 v26, v26, v27, vcc
	v_cmp_class_f32_e32 vcc, v24, v178
	v_add_f32_e32 v6, v6, v120
	v_add_f32_e32 v7, v7, v121
	v_cndmask_b32_e32 v24, v26, v24, vcc
	v_cmp_nlt_f32_e32 vcc, s86, v16
	v_pk_add_f32 v[14:15], v[10:11], v[10:11]
	v_mul_f32_e32 v6, 0xbfb8aa3b, v6
	v_cndmask_b32_e32 v1, 0, v1, vcc
	v_cmp_nlt_f32_e32 vcc, s86, v17
	v_mul_f32_e32 v3, 0x3fb8aa3b, v14
	v_rndne_f32_e32 v3, v3
	v_cndmask_b32_e32 v24, 0, v24, vcc
	v_cmp_ngt_f32_e32 vcc, s56, v17
	v_mul_f32_e32 v7, 0xbfb8aa3b, v7
	v_exp_f32_e32 v6, v6
	v_cndmask_b32_e32 v17, 1.0, v24, vcc
	v_cmp_ngt_f32_e32 vcc, s56, v16
	v_exp_f32_e32 v7, v7
	v_add_f32_e32 v6, 1.0, v6
	v_cndmask_b32_e32 v16, 1.0, v1, vcc
	v_pk_mul_f32 v[4:5], v[4:5], v[16:17]
	v_fmamk_f32 v16, v3, 0xbf317218, v14
	v_fmac_f32_e32 v16, 0x3102e308, v3
	v_fmamk_f32 v17, v16, 0x395133b1, v177
	v_cmp_eq_f32_e32 vcc, s2, v3
	v_cvt_i32_f32_e32 v3, v3
	v_fmaak_f32 v17, v16, v17, 0x3c0887f9
	v_fmaak_f32 v17, v16, v17, 0x3d2aaa81
	v_fmaak_f32 v17, v16, v17, 0x3e2aaaab
	v_fma_f32 v17, v16, v17, 0.5
	v_ldexp_f32 v3, 1.0, v3
	v_mul_f32_e32 v17, v16, v17
	v_cndmask_b32_e32 v3, v3, v195, vcc
	v_fmac_f32_e32 v16, v16, v17
	v_add_f32_e32 v17, -1.0, v3
	v_fmac_f32_e32 v17, v3, v16
	v_add_f32_e32 v3, v17, v17
	v_cndmask_b32_e32 v3, v17, v3, vcc
	v_max_f32_e64 v3, -v3, 0
	v_cmp_gt_f32_e32 vcc, s19, v3
	v_mul_f32_e32 v16, 0x4f800000, v3
	v_add_f32_e32 v7, 1.0, v7
	v_cndmask_b32_e32 v3, v3, v16, vcc
	v_sqrt_f32_e32 v16, v3
	v_rcp_f32_e32 v6, v6
	v_rcp_f32_e32 v7, v7
	v_mul_f32_e32 v0, 0x3fb8aa3b, v8
	v_add_u32_e32 v17, -1, v16
	v_fma_f32 v18, -v17, v16, v3
	v_cmp_ge_f32_e64 s[36:37], 0, v18
	v_add_u32_e32 v18, 1, v16
	v_pk_mul_f32 v[4:5], v[4:5], v[12:13]
	v_cndmask_b32_e64 v17, v16, v17, s[36:37]
	v_fma_f32 v16, -v18, v16, v3
	v_cmp_lt_f32_e64 s[36:37], 0, v16
	v_mul_f32_e32 v1, 0x3fb8aa3b, v9
	v_lshlrev_b32_e32 v12, 16, v25
	v_cndmask_b32_e64 v16, v17, v18, s[36:37]
	v_mul_f32_e32 v17, 0x37800000, v16
	v_cndmask_b32_e32 v16, v16, v17, vcc
	v_cmp_class_f32_e32 vcc, v3, v178
	v_and_b32_e32 v13, 0xffff0000, v25
	v_cvt_pk_bf16_f32 v8, v8, v9
	v_cvt_pk_bf16_f32 v9, v10, v11
	global_store_dwordx2 v[48:49], v[8:9], off offset:1536 sc1
	v_cndmask_b32_e32 v3, v16, v3, vcc
	v_mul_f32_e32 v16, 0x3fb8aa3b, v15
	v_rndne_f32_e32 v16, v16
	v_fmamk_f32 v17, v16, 0xbf317218, v15
	v_fmac_f32_e32 v17, 0x3102e308, v16
	v_fmamk_f32 v18, v17, 0x395133b1, v177
	v_cmp_eq_f32_e32 vcc, s2, v16
	v_cvt_i32_f32_e32 v16, v16
	v_fmaak_f32 v18, v17, v18, 0x3c0887f9
	v_fmaak_f32 v18, v17, v18, 0x3d2aaa81
	v_fmaak_f32 v18, v17, v18, 0x3e2aaaab
	v_fma_f32 v18, v17, v18, 0.5
	v_ldexp_f32 v16, 1.0, v16
	v_mul_f32_e32 v18, v17, v18
	v_cndmask_b32_e32 v16, v16, v195, vcc
	v_fmac_f32_e32 v17, v17, v18
	v_add_f32_e32 v18, -1.0, v16
	v_fmac_f32_e32 v18, v16, v17
	v_add_f32_e32 v16, v18, v18
	v_cndmask_b32_e32 v16, v18, v16, vcc
	v_max_f32_e64 v16, -v16, 0
	v_cmp_gt_f32_e32 vcc, s19, v16
	v_mul_f32_e32 v17, 0x4f800000, v16
	v_cvt_pk_bf16_f32 v8, v4, v5
	v_mul_f32_e32 v2, 0x3fb8aa3b, v10
	v_cndmask_b32_e32 v16, v16, v17, vcc
	v_sqrt_f32_e32 v17, v16
	v_exp_f32_e32 v0, v0
	v_exp_f32_e32 v1, v1
	v_exp_f32_e32 v2, v2
	v_add_u32_e32 v18, -1, v17
	v_fma_f32 v19, -v18, v17, v16
	v_cmp_ge_f32_e64 s[36:37], 0, v19
	v_add_u32_e32 v19, 1, v17
	s_nop 0
	v_cndmask_b32_e64 v18, v17, v18, s[36:37]
	v_fma_f32 v17, -v19, v17, v16
	v_cmp_lt_f32_e64 s[36:37], 0, v17
	s_nop 1
	v_cndmask_b32_e64 v17, v18, v19, s[36:37]
	v_mul_f32_e32 v18, 0x37800000, v17
	v_cndmask_b32_e32 v17, v17, v18, vcc
	v_cmp_class_f32_e32 vcc, v16, v178
	s_nop 1
	v_cndmask_b32_e32 v16, v17, v16, vcc
	v_cmp_nlt_f32_e32 vcc, s86, v14
	s_nop 1
	v_cndmask_b32_e32 v3, 0, v3, vcc
	v_cmp_nlt_f32_e32 vcc, s86, v15
	s_nop 1
	v_cndmask_b32_e32 v16, 0, v16, vcc
	v_cmp_ngt_f32_e32 vcc, s56, v15
	s_nop 1
	v_cndmask_b32_e32 v15, 1.0, v16, vcc
	v_cmp_ngt_f32_e32 vcc, s56, v14
	s_nop 1
	v_cndmask_b32_e32 v14, 1.0, v3, vcc
	v_pk_mul_f32 v[6:7], v[6:7], v[14:15]
	v_mul_f32_e32 v3, 0x3fb8aa3b, v11
	v_pk_mul_f32 v[6:7], v[6:7], v[12:13]
	v_exp_f32_e32 v3, v3
	v_cvt_pk_bf16_f32 v9, v6, v7
	global_store_dwordx2 v[48:49], v[8:9], off offset:1024 sc1
	ds_read_b128 v[8:11], v38
	s_waitcnt vmcnt(0) lgkmcnt(0)
	v_mfma_f32_16x16x32_bf16 v[12:15], v[126:129], v[8:11], 0
	s_waitcnt vmcnt(0)
	v_mfma_f32_16x16x32_bf16 v[8:11], v[150:153], v[8:11], 0
	ds_read_b128 v[16:19], v38 offset:64
	s_waitcnt vmcnt(0) lgkmcnt(0)
	v_mfma_f32_16x16x32_bf16 v[20:23], v[130:133], v[16:19], v[12:15]
	s_waitcnt vmcnt(0)
	v_mfma_f32_16x16x32_bf16 v[12:15], v[28:31], v[16:19], v[8:11]
	global_load_dwordx4 v[24:27], v[40:41], off offset:64
	global_load_dwordx4 v[16:19], v[46:47], off offset:64
	s_nop 0
	global_load_dwordx4 v[8:11], v[44:45], off offset:64
	ds_read_b64 v[28:29], v51 offset:32
	s_waitcnt vmcnt(2)
	v_add_f32_e32 v20, v20, v24
	s_waitcnt vmcnt(1)
; #define LAS __attribute__((address_space(3)))
; __device__ __forceinline__ unsigned pk2(float lo, float hi) { return pg8::cvt_pk_bf16(lo, hi); }
; __device__ __forceinline__ float sigmoidf_(float x) { return __builtin_amdgcn_rcpf(1.0f + __expf(-x)); }
; template <bool FULL> __device__ __forceinline__ void lru_tile(const Args& a, int l, int tile, LAS unsigned char* lds, int tid, int lane, int wave) {
;     ...
;             const int c0 = e0 + 4 * fq;
;             const f32x4 ba = *(const f32x4*)(a.in[22] + (size_t)l * 256 + c0), bx = *(const f32x4*)(a.in[24] + (size_t)l * 256 + c0), c8v = *(const f32x4*)(c8t + c0);
;             const u32x2 xr = *(const LAS u32x2*)(lds + OFF_XC + ((cb * 16 + fr) * 264 + c0) * 2);
;             float lav[4];
;             const float xcv[4] = {__uint_as_float(xr.x << 16), __uint_as_float(xr.x & 0xffff0000u), __uint_as_float(xr.y << 16), __uint_as_float(xr.y & 0xffff0000u)};
; #pragma unroll
;             for (int r = 0; r < 4; ++r) {
;                 const float rg = sigmoidf_(ra[r] + ba[r]), ig = sigmoidf_(ia[r] + bx[r]);
;                 const float la = c8v[r] * rg; const float av_ = __expf(la); const float m2 = -expm1f(2.0f * la);
;                 av[et][r] = av_; bv[et][r] = sqrtf(fmaxf(m2, 0.f)) * ig * xcv[r]; lav[r] = la;
;             }
;             {
;               bf16* yr = Y + (size_t)(t0 + cb * 16 + fr) * DM + c0;
;               u32x2 wl_; wl_.x = pk2(lav[0], lav[1]); wl_.y = pk2(lav[2], lav[3]); *(u32x2*)(yr + 768) = wl_;
;               u32x2 wb_; wb_.x = pk2(bv[et][0], bv[et][1]); wb_.y = pk2(bv[et][2], bv[et][3]); *(u32x2*)(yr + 512) = wb_; }
	v_add_f32_e32 v12, v12, v16
	v_add_f32_e32 v16, v21, v25
	v_mul_f32_e32 v20, 0xbfb8aa3b, v20
	v_mul_f32_e32 v16, 0xbfb8aa3b, v16
	v_exp_f32_e32 v20, v20
	v_exp_f32_e32 v16, v16
	v_add_f32_e32 v13, v13, v17
	s_waitcnt lgkmcnt(0)
	v_lshlrev_b32_e32 v24, 16, v28
	v_add_f32_e32 v20, 1.0, v20
	v_add_f32_e32 v16, 1.0, v16
	v_rcp_f32_e32 v20, v20
	v_rcp_f32_e32 v21, v16
	v_and_b32_e32 v25, 0xffff0000, v28
	v_mul_f32_e32 v12, 0xbfb8aa3b, v12
	v_mul_f32_e32 v13, 0xbfb8aa3b, v13
	s_waitcnt vmcnt(0)
	v_pk_mul_f32 v[16:17], v[8:9], v[20:21]
	v_exp_f32_e32 v12, v12
	v_pk_add_f32 v[20:21], v[16:17], v[16:17]
	v_exp_f32_e32 v13, v13
	v_mul_f32_e32 v9, 0x3fb8aa3b, v20
	v_rndne_f32_e32 v9, v9
	v_fmamk_f32 v28, v9, 0xbf317218, v20
	v_fmac_f32_e32 v28, 0x3102e308, v9
	v_fmamk_f32 v30, v28, 0x395133b1, v177
	v_cmp_eq_f32_e32 vcc, s2, v9
	v_cvt_i32_f32_e32 v9, v9
	v_fmaak_f32 v30, v28, v30, 0x3c0887f9
	v_fmaak_f32 v30, v28, v30, 0x3d2aaa81
	v_fmaak_f32 v30, v28, v30, 0x3e2aaaab
	v_fma_f32 v30, v28, v30, 0.5
	v_ldexp_f32 v9, 1.0, v9
	v_mul_f32_e32 v30, v28, v30
	v_cndmask_b32_e32 v9, v9, v195, vcc
	v_fmac_f32_e32 v28, v28, v30
	v_add_f32_e32 v30, -1.0, v9
	v_fmac_f32_e32 v30, v9, v28
	v_add_f32_e32 v9, v30, v30
	v_cndmask_b32_e32 v9, v30, v9, vcc
	v_max_f32_e64 v9, -v9, 0
	v_cmp_gt_f32_e32 vcc, s19, v9
	v_mul_f32_e32 v28, 0x4f800000, v9
	v_add_f32_e32 v12, 1.0, v12
	v_cndmask_b32_e32 v9, v9, v28, vcc
	v_sqrt_f32_e32 v28, v9
	v_add_f32_e32 v13, 1.0, v13
	v_rcp_f32_e32 v12, v12
	v_rcp_f32_e32 v13, v13
	v_add_u32_e32 v30, -1, v28
	v_fma_f32 v31, -v30, v28, v9
	v_cmp_ge_f32_e64 s[36:37], 0, v31
	v_add_u32_e32 v31, 1, v28
	v_add_f32_e32 v14, v14, v18
	v_cndmask_b32_e64 v30, v28, v30, s[36:37]
	v_fma_f32 v28, -v31, v28, v9
	v_cmp_lt_f32_e64 s[36:37], 0, v28
	v_add_f32_e32 v18, v23, v27
	v_mul_f32_e32 v18, 0xbfb8aa3b, v18
	v_cndmask_b32_e64 v28, v30, v31, s[36:37]
	v_mul_f32_e32 v30, 0x37800000, v28
	v_cndmask_b32_e32 v28, v28, v30, vcc
	v_cmp_class_f32_e32 vcc, v9, v178
	v_exp_f32_e32 v18, v18
	v_add_f32_e32 v15, v15, v19
	v_cndmask_b32_e32 v9, v28, v9, vcc
	v_mul_f32_e32 v28, 0x3fb8aa3b, v21
	v_rndne_f32_e32 v28, v28
	v_fmamk_f32 v30, v28, 0xbf317218, v21
	v_fmac_f32_e32 v30, 0x3102e308, v28
	v_fmamk_f32 v31, v30, 0x395133b1, v177
	v_cmp_eq_f32_e32 vcc, s2, v28
	v_cvt_i32_f32_e32 v28, v28
	v_fmaak_f32 v31, v30, v31, 0x3c0887f9
	v_fmaak_f32 v31, v30, v31, 0x3d2aaa81
	v_fmaak_f32 v31, v30, v31, 0x3e2aaaab
	v_fma_f32 v31, v30, v31, 0.5
	v_ldexp_f32 v28, 1.0, v28
	v_mul_f32_e32 v31, v30, v31
	v_cndmask_b32_e32 v28, v28, v195, vcc
	v_fmac_f32_e32 v30, v30, v31
	v_add_f32_e32 v31, -1.0, v28
	v_fmac_f32_e32 v31, v28, v30
	v_add_f32_e32 v28, v31, v31
	v_cndmask_b32_e32 v28, v31, v28, vcc
	v_max_f32_e64 v28, -v28, 0
	v_cmp_gt_f32_e32 vcc, s19, v28
	v_mul_f32_e32 v30, 0x4f800000, v28
	v_add_f32_e32 v18, 1.0, v18
	v_cndmask_b32_e32 v28, v28, v30, vcc
	v_sqrt_f32_e32 v30, v28
	v_mul_f32_e32 v14, 0xbfb8aa3b, v14
	v_mul_f32_e32 v15, 0xbfb8aa3b, v15
	v_exp_f32_e32 v14, v14
	v_add_u32_e32 v31, -1, v30
	v_fma_f32 v32, -v31, v30, v28
	v_cmp_ge_f32_e64 s[36:37], 0, v32
	v_add_u32_e32 v32, 1, v30
	v_exp_f32_e32 v15, v15
	v_cndmask_b32_e64 v31, v30, v31, s[36:37]
	v_fma_f32 v30, -v32, v30, v28
	v_cmp_lt_f32_e64 s[36:37], 0, v30
	v_add_f32_e32 v14, 1.0, v14
	v_add_f32_e32 v15, 1.0, v15
	v_cndmask_b32_e64 v30, v31, v32, s[36:37]
	v_mul_f32_e32 v31, 0x37800000, v30
	v_cndmask_b32_e32 v30, v30, v31, vcc
	v_cmp_class_f32_e32 vcc, v28, v178
	v_rcp_f32_e32 v14, v14
	v_rcp_f32_e32 v15, v15
	v_cndmask_b32_e32 v28, v30, v28, vcc
	v_cmp_nlt_f32_e32 vcc, s86, v20
	v_mul_f32_e32 v8, 0x3fb8aa3b, v16
	v_and_b32_e32 v19, 0xffff0000, v29
	v_cndmask_b32_e32 v9, 0, v9, vcc
	v_cmp_nlt_f32_e32 vcc, s86, v21
	v_cvt_pk_bf16_f32 v16, v16, v17
	v_exp_f32_e32 v8, v8
	s_nop 0
	v_cndmask_b32_e32 v28, 0, v28, vcc
	v_cmp_ngt_f32_e32 vcc, s56, v21
	s_nop 1
	v_cndmask_b32_e32 v21, 1.0, v28, vcc
	v_cmp_ngt_f32_e32 vcc, s56, v20
	s_nop 1
	v_cndmask_b32_e32 v20, 1.0, v9, vcc
	v_pk_mul_f32 v[12:13], v[12:13], v[20:21]
	v_add_f32_e32 v20, v22, v26
	v_mul_f32_e32 v20, 0xbfb8aa3b, v20
	v_exp_f32_e32 v20, v20
	v_rcp_f32_e32 v21, v18
	v_pk_mul_f32 v[12:13], v[12:13], v[24:25]
	v_mul_f32_e32 v9, 0x3fb8aa3b, v17
	v_add_f32_e32 v20, 1.0, v20
	v_rcp_f32_e32 v20, v20
	v_lshlrev_b32_e32 v18, 16, v29
	v_exp_f32_e32 v9, v9
	v_pk_mul_f32 v[20:21], v[10:11], v[20:21]
	s_nop 0
	v_pk_add_f32 v[22:23], v[20:21], v[20:21]
	v_cvt_pk_bf16_f32 v17, v20, v21
	global_store_dwordx2 v[48:49], v[16:17], off offset:1568 sc1
	v_mul_f32_e32 v11, 0x3fb8aa3b, v22
	v_rndne_f32_e32 v11, v11
	v_fmamk_f32 v24, v11, 0xbf317218, v22
	v_fmac_f32_e32 v24, 0x3102e308, v11
	v_fmamk_f32 v25, v24, 0x395133b1, v177
	v_cmp_eq_f32_e32 vcc, s2, v11
	v_cvt_i32_f32_e32 v11, v11
	v_fmaak_f32 v25, v24, v25, 0x3c0887f9
	v_fmaak_f32 v25, v24, v25, 0x3d2aaa81
	v_fmaak_f32 v25, v24, v25, 0x3e2aaaab
	v_fma_f32 v25, v24, v25, 0.5
	v_ldexp_f32 v11, 1.0, v11
	v_mul_f32_e32 v25, v24, v25
	v_cndmask_b32_e32 v11, v11, v195, vcc
	v_fmac_f32_e32 v24, v24, v25
	v_add_f32_e32 v25, -1.0, v11
	v_fmac_f32_e32 v25, v11, v24
	v_add_f32_e32 v11, v25, v25
	v_cndmask_b32_e32 v11, v25, v11, vcc
	v_max_f32_e64 v11, -v11, 0
	v_cmp_gt_f32_e32 vcc, s19, v11
	v_mul_f32_e32 v24, 0x4f800000, v11
	v_cvt_pk_bf16_f32 v16, v12, v13
	v_mul_f32_e32 v10, 0x3fb8aa3b, v20
	v_cndmask_b32_e32 v11, v11, v24, vcc
	v_sqrt_f32_e32 v24, v11
	v_exp_f32_e32 v10, v10
	v_add_u32_e32 v25, -1, v24
	v_fma_f32 v26, -v25, v24, v11
	v_cmp_ge_f32_e64 s[36:37], 0, v26
	v_add_u32_e32 v26, 1, v24
	s_nop 0
	v_cndmask_b32_e64 v25, v24, v25, s[36:37]
	v_fma_f32 v24, -v26, v24, v11
	v_cmp_lt_f32_e64 s[36:37], 0, v24
	s_nop 1
; #define LAS __attribute__((address_space(3)))
; __device__ __forceinline__ unsigned pk2(float lo, float hi) { return pg8::cvt_pk_bf16(lo, hi); }
; __device__ __forceinline__ float sigmoidf_(float x) { return __builtin_amdgcn_rcpf(1.0f + __expf(-x)); }
; template <bool FULL> __device__ __forceinline__ void lru_tile(const Args& a, int l, int tile, LAS unsigned char* lds, int tid, int lane, int wave) {
;     ...
; #pragma unroll
;         for (int et = 0; et < 8; ++et) {
;             const int e0 = chh * 128 + et * 16, nb = e0 >> 6, el = e0 & 63;
;             f32x4 ra = {0.f, 0.f, 0.f, 0.f}, ia = {0.f, 0.f, 0.f, 0.f};
; #pragma unroll
;             for (int ks = 0; ks < 2; ++ks) {
;                 const bf16x8 xv = *(const LAS bf16x8*)(lds + OFF_XC + ((cb * 16 + fr) * 264 + nb * 64 + 32 * ks + 8 * fq) * 2);
;                 const bf16x8 wa = *(const bf16x8*)(WA + (size_t)nb * 4096 + (el + fr) * 64 + 32 * ks + 8 * fq);
;                 const bf16x8 wx = *(const bf16x8*)(WX + (size_t)nb * 4096 + (el + fr) * 64 + 32 * ks + 8 * fq);
;                 MFMA16(wa, xv, ra); MFMA16(wx, xv, ia);
;     ...
;             const int c0 = e0 + 4 * fq;
;             const f32x4 ba = *(const f32x4*)(a.in[22] + (size_t)l * 256 + c0), bx = *(const f32x4*)(a.in[24] + (size_t)l * 256 + c0), c8v = *(const f32x4*)(c8t + c0);
;             const u32x2 xr = *(const LAS u32x2*)(lds + OFF_XC + ((cb * 16 + fr) * 264 + c0) * 2);
;             float lav[4];
;             const float xcv[4] = {__uint_as_float(xr.x << 16), __uint_as_float(xr.x & 0xffff0000u), __uint_as_float(xr.y << 16), __uint_as_float(xr.y & 0xffff0000u)};
; #pragma unroll
;             for (int r = 0; r < 4; ++r) {
;                 const float rg = sigmoidf_(ra[r] + ba[r]), ig = sigmoidf_(ia[r] + bx[r]);
;                 const float la = c8v[r] * rg; const float av_ = __expf(la); const float m2 = -expm1f(2.0f * la);
;                 av[et][r] = av_; bv[et][r] = sqrtf(fmaxf(m2, 0.f)) * ig * xcv[r]; lav[r] = la;
;             }
;             {
;               bf16* yr = Y + (size_t)(t0 + cb * 16 + fr) * DM + c0;
;               u32x2 wl_; wl_.x = pk2(lav[0], lav[1]); wl_.y = pk2(lav[2], lav[3]); *(u32x2*)(yr + 768) = wl_;
;               u32x2 wb_; wb_.x = pk2(bv[et][0], bv[et][1]); wb_.y = pk2(bv[et][2], bv[et][3]); *(u32x2*)(yr + 512) = wb_; }
	v_cndmask_b32_e64 v24, v25, v26, s[36:37]
	v_mul_f32_e32 v25, 0x37800000, v24
	v_cndmask_b32_e32 v24, v24, v25, vcc
	v_cmp_class_f32_e32 vcc, v11, v178
	s_nop 1
	v_cndmask_b32_e32 v11, v24, v11, vcc
	v_mul_f32_e32 v24, 0x3fb8aa3b, v23
	v_rndne_f32_e32 v24, v24
	v_fmamk_f32 v25, v24, 0xbf317218, v23
	v_fmac_f32_e32 v25, 0x3102e308, v24
	v_fmamk_f32 v26, v25, 0x395133b1, v177
	v_cmp_eq_f32_e32 vcc, s2, v24
	v_cvt_i32_f32_e32 v24, v24
	v_fmaak_f32 v26, v25, v26, 0x3c0887f9
	v_fmaak_f32 v26, v25, v26, 0x3d2aaa81
	v_fmaak_f32 v26, v25, v26, 0x3e2aaaab
	v_fma_f32 v26, v25, v26, 0.5
	v_ldexp_f32 v24, 1.0, v24
	v_mul_f32_e32 v26, v25, v26
	v_cndmask_b32_e32 v24, v24, v195, vcc
	v_fmac_f32_e32 v25, v25, v26
	v_add_f32_e32 v26, -1.0, v24
	v_fmac_f32_e32 v26, v24, v25
	v_add_f32_e32 v24, v26, v26
	v_cndmask_b32_e32 v24, v26, v24, vcc
	v_max_f32_e64 v24, -v24, 0
	v_cmp_gt_f32_e32 vcc, s19, v24
	v_mul_f32_e32 v25, 0x4f800000, v24
	s_nop 0
	v_cndmask_b32_e32 v24, v24, v25, vcc
	v_sqrt_f32_e32 v25, v24
	s_nop 0
	v_add_u32_e32 v26, -1, v25
	v_fma_f32 v27, -v26, v25, v24
	v_cmp_ge_f32_e64 s[36:37], 0, v27
	v_add_u32_e32 v27, 1, v25
	s_nop 0
	v_cndmask_b32_e64 v26, v25, v26, s[36:37]
	v_fma_f32 v25, -v27, v25, v24
	v_cmp_lt_f32_e64 s[36:37], 0, v25
	s_nop 1
	v_cndmask_b32_e64 v25, v26, v27, s[36:37]
	v_mul_f32_e32 v26, 0x37800000, v25
	v_cndmask_b32_e32 v25, v25, v26, vcc
	v_cmp_class_f32_e32 vcc, v24, v178
	s_nop 1
	v_cndmask_b32_e32 v24, v25, v24, vcc
	v_cmp_nlt_f32_e32 vcc, s86, v22
	s_nop 1
	v_cndmask_b32_e32 v11, 0, v11, vcc
	v_cmp_nlt_f32_e32 vcc, s86, v23
	s_nop 1
	v_cndmask_b32_e32 v24, 0, v24, vcc
	v_cmp_ngt_f32_e32 vcc, s56, v23
	s_nop 1
	v_cndmask_b32_e32 v23, 1.0, v24, vcc
	v_cmp_ngt_f32_e32 vcc, s56, v22
	s_nop 1
	v_cndmask_b32_e32 v22, 1.0, v11, vcc
	v_pk_mul_f32 v[14:15], v[14:15], v[22:23]
	v_mul_f32_e32 v11, 0x3fb8aa3b, v21
	v_pk_mul_f32 v[14:15], v[14:15], v[18:19]
	v_exp_f32_e32 v11, v11
	v_cvt_pk_bf16_f32 v17, v14, v15
	global_store_dwordx2 v[48:49], v[16:17], off offset:1056 sc1
	v_lshl_add_u64 v[16:17], s[40:41], 0, v[60:61]
	v_lshl_add_u64 v[28:29], v[16:17], 0, v[68:69]
	global_load_dwordx4 v[118:121], v[28:29], off
	global_load_dwordx4 v[122:125], v[28:29], off offset:64
	v_lshl_add_u64 v[16:17], s[42:43], 0, v[60:61]
	v_lshl_add_u64 v[32:33], v[16:17], 0, v[68:69]
	global_load_dwordx4 v[126:129], v[32:33], off
	global_load_dwordx4 v[130:133], v[32:33], off offset:64
	ds_read_b128 v[16:19], v38
	s_waitcnt vmcnt(3) lgkmcnt(0)
	v_mfma_f32_16x16x32_bf16 v[20:23], v[118:121], v[16:19], 0
	s_waitcnt vmcnt(1)
	v_mfma_f32_16x16x32_bf16 v[16:19], v[126:129], v[16:19], 0
	ds_read_b128 v[24:27], v38 offset:64
	s_nop 0
	s_waitcnt vmcnt(1) lgkmcnt(0)
	v_mfma_f32_16x16x32_bf16 v[28:31], v[122:125], v[24:27], v[20:23]
	s_waitcnt vmcnt(0)
	v_mfma_f32_16x16x32_bf16 v[20:23], v[130:133], v[24:27], v[16:19]
	global_load_dwordx4 v[32:35], v[40:41], off offset:128
	global_load_dwordx4 v[24:27], v[46:47], off offset:128
	s_nop 0
	global_load_dwordx4 v[16:19], v[44:45], off offset:128
	ds_read_b64 v[36:37], v51 offset:64
	s_waitcnt vmcnt(2)
	v_add_f32_e32 v28, v28, v32
	s_waitcnt vmcnt(1)
	v_add_f32_e32 v20, v20, v24
	v_add_f32_e32 v24, v29, v33
	v_mul_f32_e32 v28, 0xbfb8aa3b, v28
	v_mul_f32_e32 v24, 0xbfb8aa3b, v24
	v_exp_f32_e32 v28, v28
	v_exp_f32_e32 v24, v24
	v_add_f32_e32 v21, v21, v25
	s_waitcnt lgkmcnt(0)
	v_lshlrev_b32_e32 v32, 16, v36
	v_add_f32_e32 v28, 1.0, v28
	v_add_f32_e32 v24, 1.0, v24
	v_rcp_f32_e32 v28, v28
	v_rcp_f32_e32 v29, v24
	v_and_b32_e32 v33, 0xffff0000, v36
	v_mul_f32_e32 v20, 0xbfb8aa3b, v20
	v_mul_f32_e32 v21, 0xbfb8aa3b, v21
	s_waitcnt vmcnt(0)
	v_pk_mul_f32 v[24:25], v[16:17], v[28:29]
	v_exp_f32_e32 v20, v20
	v_pk_add_f32 v[28:29], v[24:25], v[24:25]
	v_exp_f32_e32 v21, v21
	v_mul_f32_e32 v17, 0x3fb8aa3b, v28
	v_rndne_f32_e32 v17, v17
	v_fmamk_f32 v36, v17, 0xbf317218, v28
	v_fmac_f32_e32 v36, 0x3102e308, v17
	v_fmamk_f32 v39, v36, 0x395133b1, v177
	v_cmp_eq_f32_e32 vcc, s2, v17
	v_cvt_i32_f32_e32 v17, v17
	v_fmaak_f32 v39, v36, v39, 0x3c0887f9
	v_fmaak_f32 v39, v36, v39, 0x3d2aaa81
	v_fmaak_f32 v39, v36, v39, 0x3e2aaaab
	v_fma_f32 v39, v36, v39, 0.5
	v_ldexp_f32 v17, 1.0, v17
	v_mul_f32_e32 v39, v36, v39
	v_cndmask_b32_e32 v17, v17, v195, vcc
	v_fmac_f32_e32 v36, v36, v39
	v_add_f32_e32 v39, -1.0, v17
	v_fmac_f32_e32 v39, v17, v36
	v_add_f32_e32 v17, v39, v39
	v_cndmask_b32_e32 v17, v39, v17, vcc
	v_max_f32_e64 v17, -v17, 0
	v_cmp_gt_f32_e32 vcc, s19, v17
	v_mul_f32_e32 v36, 0x4f800000, v17
	v_add_f32_e32 v20, 1.0, v20
	v_cndmask_b32_e32 v17, v17, v36, vcc
	v_sqrt_f32_e32 v36, v17
	v_add_f32_e32 v21, 1.0, v21
	v_rcp_f32_e32 v20, v20
	v_rcp_f32_e32 v21, v21
	v_add_u32_e32 v39, -1, v36
	v_fma_f32 v42, -v39, v36, v17
	v_cmp_ge_f32_e64 s[36:37], 0, v42
	v_add_u32_e32 v42, 1, v36
	v_add_f32_e32 v22, v22, v26
	v_cndmask_b32_e64 v39, v36, v39, s[36:37]
	v_fma_f32 v36, -v42, v36, v17
	v_cmp_lt_f32_e64 s[36:37], 0, v36
	v_add_f32_e32 v26, v31, v35
	v_mul_f32_e32 v26, 0xbfb8aa3b, v26
	v_cndmask_b32_e64 v36, v39, v42, s[36:37]
	v_mul_f32_e32 v39, 0x37800000, v36
	v_cndmask_b32_e32 v36, v36, v39, vcc
	v_cmp_class_f32_e32 vcc, v17, v178
	v_exp_f32_e32 v26, v26
	v_add_f32_e32 v23, v23, v27
	v_cndmask_b32_e32 v17, v36, v17, vcc
	v_mul_f32_e32 v36, 0x3fb8aa3b, v29
	v_rndne_f32_e32 v36, v36
	v_fmamk_f32 v39, v36, 0xbf317218, v29
	v_fmac_f32_e32 v39, 0x3102e308, v36
	v_fmamk_f32 v42, v39, 0x395133b1, v177
	v_cmp_eq_f32_e32 vcc, s2, v36
	v_cvt_i32_f32_e32 v36, v36
	v_fmaak_f32 v42, v39, v42, 0x3c0887f9
	v_fmaak_f32 v42, v39, v42, 0x3d2aaa81
	v_fmaak_f32 v42, v39, v42, 0x3e2aaaab
	v_fma_f32 v42, v39, v42, 0.5
	v_ldexp_f32 v36, 1.0, v36
; #define LAS __attribute__((address_space(3)))
; __device__ __forceinline__ unsigned pk2(float lo, float hi) { return pg8::cvt_pk_bf16(lo, hi); }
; __device__ __forceinline__ float sigmoidf_(float x) { return __builtin_amdgcn_rcpf(1.0f + __expf(-x)); }
; template <bool FULL> __device__ __forceinline__ void lru_tile(const Args& a, int l, int tile, LAS unsigned char* lds, int tid, int lane, int wave) {
;     ...
;             const int c0 = e0 + 4 * fq;
;             const f32x4 ba = *(const f32x4*)(a.in[22] + (size_t)l * 256 + c0), bx = *(const f32x4*)(a.in[24] + (size_t)l * 256 + c0), c8v = *(const f32x4*)(c8t + c0);
;             const u32x2 xr = *(const LAS u32x2*)(lds + OFF_XC + ((cb * 16 + fr) * 264 + c0) * 2);
;             float lav[4];
;             const float xcv[4] = {__uint_as_float(xr.x << 16), __uint_as_float(xr.x & 0xffff0000u), __uint_as_float(xr.y << 16), __uint_as_float(xr.y & 0xffff0000u)};
; #pragma unroll
;             for (int r = 0; r < 4; ++r) {
;                 const float rg = sigmoidf_(ra[r] + ba[r]), ig = sigmoidf_(ia[r] + bx[r]);
;                 const float la = c8v[r] * rg; const float av_ = __expf(la); const float m2 = -expm1f(2.0f * la);
;                 av[et][r] = av_; bv[et][r] = sqrtf(fmaxf(m2, 0.f)) * ig * xcv[r]; lav[r] = la;
;             }
;             {
;               bf16* yr = Y + (size_t)(t0 + cb * 16 + fr) * DM + c0;
;               u32x2 wl_; wl_.x = pk2(lav[0], lav[1]); wl_.y = pk2(lav[2], lav[3]); *(u32x2*)(yr + 768) = wl_;
;               u32x2 wb_; wb_.x = pk2(bv[et][0], bv[et][1]); wb_.y = pk2(bv[et][2], bv[et][3]); *(u32x2*)(yr + 512) = wb_; }
	v_mul_f32_e32 v42, v39, v42
	v_cndmask_b32_e32 v36, v36, v195, vcc
	v_fmac_f32_e32 v39, v39, v42
	v_add_f32_e32 v42, -1.0, v36
	v_fmac_f32_e32 v42, v36, v39
	v_add_f32_e32 v36, v42, v42
	v_cndmask_b32_e32 v36, v42, v36, vcc
	v_max_f32_e64 v36, -v36, 0
	v_cmp_gt_f32_e32 vcc, s19, v36
	v_mul_f32_e32 v39, 0x4f800000, v36
	v_add_f32_e32 v26, 1.0, v26
	v_cndmask_b32_e32 v36, v36, v39, vcc
	v_sqrt_f32_e32 v39, v36
	v_mul_f32_e32 v22, 0xbfb8aa3b, v22
	v_mul_f32_e32 v23, 0xbfb8aa3b, v23
	v_exp_f32_e32 v22, v22
	v_add_u32_e32 v42, -1, v39
	v_fma_f32 v43, -v42, v39, v36
	v_cmp_ge_f32_e64 s[36:37], 0, v43
	v_add_u32_e32 v43, 1, v39
	v_exp_f32_e32 v23, v23
	v_cndmask_b32_e64 v42, v39, v42, s[36:37]
	v_fma_f32 v39, -v43, v39, v36
	v_cmp_lt_f32_e64 s[36:37], 0, v39
	v_add_f32_e32 v22, 1.0, v22
	v_add_f32_e32 v23, 1.0, v23
	v_cndmask_b32_e64 v39, v42, v43, s[36:37]
	v_mul_f32_e32 v42, 0x37800000, v39
	v_cndmask_b32_e32 v39, v39, v42, vcc
	v_cmp_class_f32_e32 vcc, v36, v178
	v_rcp_f32_e32 v22, v22
	v_rcp_f32_e32 v23, v23
	v_cndmask_b32_e32 v36, v39, v36, vcc
	v_cmp_nlt_f32_e32 vcc, s86, v28
	v_mul_f32_e32 v16, 0x3fb8aa3b, v24
	v_cvt_pk_bf16_f32 v24, v24, v25
	v_and_b32_e32 v27, 0xffff0000, v37
	v_cndmask_b32_e32 v17, 0, v17, vcc
	v_cmp_nlt_f32_e32 vcc, s86, v29
	v_exp_f32_e32 v16, v16
	s_nop 0
	v_cndmask_b32_e32 v36, 0, v36, vcc
	v_cmp_ngt_f32_e32 vcc, s56, v29
	s_nop 1
	v_cndmask_b32_e32 v29, 1.0, v36, vcc
	v_cmp_ngt_f32_e32 vcc, s56, v28
	s_nop 1
	v_cndmask_b32_e32 v28, 1.0, v17, vcc
	v_pk_mul_f32 v[20:21], v[20:21], v[28:29]
	v_add_f32_e32 v28, v30, v34
	v_mul_f32_e32 v28, 0xbfb8aa3b, v28
	v_exp_f32_e32 v28, v28
	v_rcp_f32_e32 v29, v26
	v_pk_mul_f32 v[20:21], v[20:21], v[32:33]
	v_mul_f32_e32 v17, 0x3fb8aa3b, v25
	v_add_f32_e32 v28, 1.0, v28
	v_rcp_f32_e32 v28, v28
	v_lshlrev_b32_e32 v26, 16, v37
	v_exp_f32_e32 v17, v17
	v_pk_mul_f32 v[28:29], v[18:19], v[28:29]
	s_nop 0
	v_pk_add_f32 v[30:31], v[28:29], v[28:29]
	v_cvt_pk_bf16_f32 v25, v28, v29
	global_store_dwordx2 v[48:49], v[24:25], off offset:1600 sc1
	v_mul_f32_e32 v19, 0x3fb8aa3b, v30
	v_rndne_f32_e32 v19, v19
	v_fmamk_f32 v32, v19, 0xbf317218, v30
	v_fmac_f32_e32 v32, 0x3102e308, v19
	v_fmamk_f32 v33, v32, 0x395133b1, v177
	v_cmp_eq_f32_e32 vcc, s2, v19
	v_cvt_i32_f32_e32 v19, v19
	v_fmaak_f32 v33, v32, v33, 0x3c0887f9
	v_fmaak_f32 v33, v32, v33, 0x3d2aaa81
	v_fmaak_f32 v33, v32, v33, 0x3e2aaaab
	v_fma_f32 v33, v32, v33, 0.5
	v_ldexp_f32 v19, 1.0, v19
	v_mul_f32_e32 v33, v32, v33
	v_cndmask_b32_e32 v19, v19, v195, vcc
	v_fmac_f32_e32 v32, v32, v33
	v_add_f32_e32 v33, -1.0, v19
	v_fmac_f32_e32 v33, v19, v32
	v_add_f32_e32 v19, v33, v33
	v_cndmask_b32_e32 v19, v33, v19, vcc
	v_max_f32_e64 v19, -v19, 0
	v_cmp_gt_f32_e32 vcc, s19, v19
	v_mul_f32_e32 v32, 0x4f800000, v19
	v_cvt_pk_bf16_f32 v24, v20, v21
	v_mul_f32_e32 v18, 0x3fb8aa3b, v28
	v_cndmask_b32_e32 v19, v19, v32, vcc
	v_sqrt_f32_e32 v32, v19
	v_exp_f32_e32 v18, v18
	v_add_u32_e32 v33, -1, v32
	v_fma_f32 v34, -v33, v32, v19
	v_cmp_ge_f32_e64 s[36:37], 0, v34
	v_add_u32_e32 v34, 1, v32
	s_nop 0
	v_cndmask_b32_e64 v33, v32, v33, s[36:37]
	v_fma_f32 v32, -v34, v32, v19
	v_cmp_lt_f32_e64 s[36:37], 0, v32
	s_nop 1
	v_cndmask_b32_e64 v32, v33, v34, s[36:37]
	v_mul_f32_e32 v33, 0x37800000, v32
	v_cndmask_b32_e32 v32, v32, v33, vcc
	v_cmp_class_f32_e32 vcc, v19, v178
	s_nop 1
	v_cndmask_b32_e32 v19, v32, v19, vcc
	v_mul_f32_e32 v32, 0x3fb8aa3b, v31
	v_rndne_f32_e32 v32, v32
	v_fmamk_f32 v33, v32, 0xbf317218, v31
	v_fmac_f32_e32 v33, 0x3102e308, v32
	v_fmamk_f32 v34, v33, 0x395133b1, v177
	v_cmp_eq_f32_e32 vcc, s2, v32
	v_cvt_i32_f32_e32 v32, v32
	v_fmaak_f32 v34, v33, v34, 0x3c0887f9
	v_fmaak_f32 v34, v33, v34, 0x3d2aaa81
	v_fmaak_f32 v34, v33, v34, 0x3e2aaaab
	v_fma_f32 v34, v33, v34, 0.5
	v_ldexp_f32 v32, 1.0, v32
	v_mul_f32_e32 v34, v33, v34
	v_cndmask_b32_e32 v32, v32, v195, vcc
	v_fmac_f32_e32 v33, v33, v34
	v_add_f32_e32 v34, -1.0, v32
	v_fmac_f32_e32 v34, v32, v33
	v_add_f32_e32 v32, v34, v34
	v_cndmask_b32_e32 v32, v34, v32, vcc
	v_max_f32_e64 v32, -v32, 0
	v_cmp_gt_f32_e32 vcc, s19, v32
	v_mul_f32_e32 v33, 0x4f800000, v32
	s_nop 0
	v_cndmask_b32_e32 v32, v32, v33, vcc
	v_sqrt_f32_e32 v33, v32
	s_nop 0
	v_add_u32_e32 v34, -1, v33
	v_fma_f32 v35, -v34, v33, v32
	v_cmp_ge_f32_e64 s[36:37], 0, v35
	v_add_u32_e32 v35, 1, v33
	s_nop 0
	v_cndmask_b32_e64 v34, v33, v34, s[36:37]
	v_fma_f32 v33, -v35, v33, v32
	v_cmp_lt_f32_e64 s[36:37], 0, v33
	s_nop 1
	v_cndmask_b32_e64 v33, v34, v35, s[36:37]
	v_mul_f32_e32 v34, 0x37800000, v33
	v_cndmask_b32_e32 v33, v33, v34, vcc
	v_cmp_class_f32_e32 vcc, v32, v178
	s_nop 1
	v_cndmask_b32_e32 v32, v33, v32, vcc
	v_cmp_nlt_f32_e32 vcc, s86, v30
	s_nop 1
	v_cndmask_b32_e32 v19, 0, v19, vcc
	v_cmp_nlt_f32_e32 vcc, s86, v31
	s_nop 1
	v_cndmask_b32_e32 v32, 0, v32, vcc
	v_cmp_ngt_f32_e32 vcc, s56, v31
	s_nop 1
	v_cndmask_b32_e32 v31, 1.0, v32, vcc
	v_cmp_ngt_f32_e32 vcc, s56, v30
	s_nop 1
	v_cndmask_b32_e32 v30, 1.0, v19, vcc
	v_pk_mul_f32 v[22:23], v[22:23], v[30:31]
	v_mul_f32_e32 v19, 0x3fb8aa3b, v29
	v_pk_mul_f32 v[22:23], v[22:23], v[26:27]
	v_exp_f32_e32 v19, v19
	v_cvt_pk_bf16_f32 v25, v22, v23
	global_store_dwordx2 v[48:49], v[24:25], off offset:1088 sc1
	v_mov_b32_e32 v24, 0x1800
	v_lshl_or_b32 v70, v66, 7, v24
	v_lshl_add_u64 v[24:25], s[40:41], 0, v[70:71]
	v_lshl_add_u64 v[36:37], v[24:25], 0, v[68:69]
	global_load_dwordx4 v[118:121], v[36:37], off
	global_load_dwordx4 v[122:125], v[36:37], off offset:64
	v_lshl_add_u64 v[24:25], s[42:43], 0, v[70:71]
	v_lshl_add_u64 v[42:43], v[24:25], 0, v[68:69]
	global_load_dwordx4 v[126:129], v[42:43], off
	global_load_dwordx4 v[56:59], v[42:43], off offset:64
	ds_read_b128 v[24:27], v38
	s_waitcnt vmcnt(3) lgkmcnt(0)
; #define LAS __attribute__((address_space(3)))
; __device__ __forceinline__ unsigned pk2(float lo, float hi) { return pg8::cvt_pk_bf16(lo, hi); }
; __device__ __forceinline__ float sigmoidf_(float x) { return __builtin_amdgcn_rcpf(1.0f + __expf(-x)); }
; template <bool FULL> __device__ __forceinline__ void lru_tile(const Args& a, int l, int tile, LAS unsigned char* lds, int tid, int lane, int wave) {
;     ...
; #pragma unroll
;         for (int et = 0; et < 8; ++et) {
;             const int e0 = chh * 128 + et * 16, nb = e0 >> 6, el = e0 & 63;
;             f32x4 ra = {0.f, 0.f, 0.f, 0.f}, ia = {0.f, 0.f, 0.f, 0.f};
; #pragma unroll
;             for (int ks = 0; ks < 2; ++ks) {
;                 const bf16x8 xv = *(const LAS bf16x8*)(lds + OFF_XC + ((cb * 16 + fr) * 264 + nb * 64 + 32 * ks + 8 * fq) * 2);
;                 const bf16x8 wa = *(const bf16x8*)(WA + (size_t)nb * 4096 + (el + fr) * 64 + 32 * ks + 8 * fq);
;                 const bf16x8 wx = *(const bf16x8*)(WX + (size_t)nb * 4096 + (el + fr) * 64 + 32 * ks + 8 * fq);
;                 MFMA16(wa, xv, ra); MFMA16(wx, xv, ia);
;             }
;             const int c0 = e0 + 4 * fq;
;             const f32x4 ba = *(const f32x4*)(a.in[22] + (size_t)l * 256 + c0), bx = *(const f32x4*)(a.in[24] + (size_t)l * 256 + c0), c8v = *(const f32x4*)(c8t + c0);
;             const u32x2 xr = *(const LAS u32x2*)(lds + OFF_XC + ((cb * 16 + fr) * 264 + c0) * 2);
;             float lav[4];
;             const float xcv[4] = {__uint_as_float(xr.x << 16), __uint_as_float(xr.x & 0xffff0000u), __uint_as_float(xr.y << 16), __uint_as_float(xr.y & 0xffff0000u)};
; #pragma unroll
;             for (int r = 0; r < 4; ++r) {
;                 const float rg = sigmoidf_(ra[r] + ba[r]), ig = sigmoidf_(ia[r] + bx[r]);
;                 const float la = c8v[r] * rg; const float av_ = __expf(la); const float m2 = -expm1f(2.0f * la);
;                 av[et][r] = av_; bv[et][r] = sqrtf(fmaxf(m2, 0.f)) * ig * xcv[r]; lav[r] = la;
;             }
;             {
;               bf16* yr = Y + (size_t)(t0 + cb * 16 + fr) * DM + c0;
;               u32x2 wl_; wl_.x = pk2(lav[0], lav[1]); wl_.y = pk2(lav[2], lav[3]); *(u32x2*)(yr + 768) = wl_;
;               u32x2 wb_; wb_.x = pk2(bv[et][0], bv[et][1]); wb_.y = pk2(bv[et][2], bv[et][3]); *(u32x2*)(yr + 512) = wb_; }
	v_mfma_f32_16x16x32_bf16 v[28:31], v[118:121], v[24:27], 0
	s_waitcnt vmcnt(1)
	v_mfma_f32_16x16x32_bf16 v[24:27], v[126:129], v[24:27], 0
	ds_read_b128 v[32:35], v38 offset:64
	s_nop 0
	global_load_dwordx4 v[40:43], v[40:41], off offset:192
	s_waitcnt vmcnt(2) lgkmcnt(0)
	v_mfma_f32_16x16x32_bf16 v[36:39], v[122:125], v[32:35], v[28:31]
	s_waitcnt vmcnt(1)
	v_mfma_f32_16x16x32_bf16 v[28:31], v[56:59], v[32:35], v[24:27]
	s_nop 0
	global_load_dwordx4 v[32:35], v[46:47], off offset:192
	global_load_dwordx4 v[24:27], v[44:45], off offset:192
	ds_read_b64 v[44:45], v51 offset:96
	v_or_b32_e32 v56, s7, v86
	v_mad_u32_u24 v56, v79, s12, v56
	v_lshl_add_u32 v56, v56, 1, s0
	s_waitcnt vmcnt(2)
	v_add_f32_e32 v36, v36, v40
	s_waitcnt vmcnt(1)
	v_add_f32_e32 v28, v28, v32
	v_add_f32_e32 v32, v37, v41
	v_mul_f32_e32 v36, 0xbfb8aa3b, v36
	v_mul_f32_e32 v32, 0xbfb8aa3b, v32
	v_exp_f32_e32 v36, v36
	v_exp_f32_e32 v32, v32
	v_add_f32_e32 v29, v29, v33
	s_waitcnt lgkmcnt(0)
	v_lshlrev_b32_e32 v40, 16, v44
	v_add_f32_e32 v36, 1.0, v36
	v_add_f32_e32 v32, 1.0, v32
	v_rcp_f32_e32 v36, v36
	v_rcp_f32_e32 v37, v32
	v_and_b32_e32 v41, 0xffff0000, v44
	v_mul_f32_e32 v28, 0xbfb8aa3b, v28
	v_mul_f32_e32 v29, 0xbfb8aa3b, v29
	s_waitcnt vmcnt(0)
	v_pk_mul_f32 v[32:33], v[24:25], v[36:37]
	v_exp_f32_e32 v28, v28
	v_pk_add_f32 v[36:37], v[32:33], v[32:33]
	v_exp_f32_e32 v29, v29
	v_mul_f32_e32 v25, 0x3fb8aa3b, v36
	v_rndne_f32_e32 v25, v25
	v_fmamk_f32 v44, v25, 0xbf317218, v36
	v_fmac_f32_e32 v44, 0x3102e308, v25
	v_fmamk_f32 v46, v44, 0x395133b1, v177
	v_cmp_eq_f32_e32 vcc, s2, v25
	v_cvt_i32_f32_e32 v25, v25
	v_fmaak_f32 v46, v44, v46, 0x3c0887f9
	v_fmaak_f32 v46, v44, v46, 0x3d2aaa81
	v_fmaak_f32 v46, v44, v46, 0x3e2aaaab
	v_fma_f32 v46, v44, v46, 0.5
	v_ldexp_f32 v25, 1.0, v25
	v_mul_f32_e32 v46, v44, v46
	v_cndmask_b32_e32 v25, v25, v195, vcc
	v_fmac_f32_e32 v44, v44, v46
	v_add_f32_e32 v46, -1.0, v25
	v_fmac_f32_e32 v46, v25, v44
	v_add_f32_e32 v25, v46, v46
	v_cndmask_b32_e32 v25, v46, v25, vcc
	v_max_f32_e64 v25, -v25, 0
	v_cmp_gt_f32_e32 vcc, s19, v25
	v_mul_f32_e32 v44, 0x4f800000, v25
	v_add_f32_e32 v28, 1.0, v28
	v_cndmask_b32_e32 v25, v25, v44, vcc
	v_sqrt_f32_e32 v44, v25
	v_add_f32_e32 v29, 1.0, v29
	v_rcp_f32_e32 v28, v28
	v_rcp_f32_e32 v29, v29
	v_add_u32_e32 v46, -1, v44
	v_fma_f32 v47, -v46, v44, v25
	v_cmp_ge_f32_e64 s[36:37], 0, v47
	v_add_u32_e32 v47, 1, v44
	v_add_f32_e32 v30, v30, v34
	v_cndmask_b32_e64 v46, v44, v46, s[36:37]
	v_fma_f32 v44, -v47, v44, v25
	v_cmp_lt_f32_e64 s[36:37], 0, v44
	v_add_f32_e32 v34, v39, v43
	v_mul_f32_e32 v34, 0xbfb8aa3b, v34
	v_cndmask_b32_e64 v44, v46, v47, s[36:37]
	v_mul_f32_e32 v46, 0x37800000, v44
	v_cndmask_b32_e32 v44, v44, v46, vcc
	v_cmp_class_f32_e32 vcc, v25, v178
	v_exp_f32_e32 v34, v34
	v_add_f32_e32 v31, v31, v35
	v_cndmask_b32_e32 v25, v44, v25, vcc
	v_mul_f32_e32 v44, 0x3fb8aa3b, v37
	v_rndne_f32_e32 v44, v44
	v_fmamk_f32 v46, v44, 0xbf317218, v37
	v_fmac_f32_e32 v46, 0x3102e308, v44
	v_fmamk_f32 v47, v46, 0x395133b1, v177
	v_cmp_eq_f32_e32 vcc, s2, v44
	v_cvt_i32_f32_e32 v44, v44
	v_fmaak_f32 v47, v46, v47, 0x3c0887f9
	v_fmaak_f32 v47, v46, v47, 0x3d2aaa81
	v_fmaak_f32 v47, v46, v47, 0x3e2aaaab
	v_fma_f32 v47, v46, v47, 0.5
	v_ldexp_f32 v44, 1.0, v44
	v_mul_f32_e32 v47, v46, v47
	v_cndmask_b32_e32 v44, v44, v195, vcc
	v_fmac_f32_e32 v46, v46, v47
	v_add_f32_e32 v47, -1.0, v44
	v_fmac_f32_e32 v47, v44, v46
	v_add_f32_e32 v44, v47, v47
	v_cndmask_b32_e32 v44, v47, v44, vcc
	v_max_f32_e64 v44, -v44, 0
	v_cmp_gt_f32_e32 vcc, s19, v44
	v_mul_f32_e32 v46, 0x4f800000, v44
	v_add_f32_e32 v34, 1.0, v34
	v_cndmask_b32_e32 v44, v44, v46, vcc
	v_sqrt_f32_e32 v46, v44
	v_mul_f32_e32 v30, 0xbfb8aa3b, v30
	v_mul_f32_e32 v31, 0xbfb8aa3b, v31
	v_exp_f32_e32 v30, v30
	v_add_u32_e32 v47, -1, v46
	v_fma_f32 v51, -v47, v46, v44
	v_cmp_ge_f32_e64 s[36:37], 0, v51
	v_add_u32_e32 v51, 1, v46
	v_exp_f32_e32 v31, v31
	v_cndmask_b32_e64 v47, v46, v47, s[36:37]
	v_fma_f32 v46, -v51, v46, v44
	v_cmp_lt_f32_e64 s[36:37], 0, v46
	v_add_f32_e32 v30, 1.0, v30
	v_add_f32_e32 v31, 1.0, v31
	v_cndmask_b32_e64 v46, v47, v51, s[36:37]
	v_mul_f32_e32 v47, 0x37800000, v46
	v_cndmask_b32_e32 v46, v46, v47, vcc
	v_cmp_class_f32_e32 vcc, v44, v178
	v_rcp_f32_e32 v30, v30
	v_rcp_f32_e32 v31, v31
	v_cndmask_b32_e32 v44, v46, v44, vcc
	v_cmp_nlt_f32_e32 vcc, s86, v36
	v_mul_f32_e32 v24, 0x3fb8aa3b, v32
	v_and_b32_e32 v35, 0xffff0000, v45
	v_cndmask_b32_e32 v25, 0, v25, vcc
	v_cmp_nlt_f32_e32 vcc, s86, v37
	v_cvt_pk_bf16_f32 v32, v32, v33
	v_exp_f32_e32 v24, v24
	s_nop 0
	v_cndmask_b32_e32 v44, 0, v44, vcc
	v_cmp_ngt_f32_e32 vcc, s56, v37
	s_nop 1
	v_cndmask_b32_e32 v37, 1.0, v44, vcc
	v_cmp_ngt_f32_e32 vcc, s56, v36
	s_nop 1
	v_cndmask_b32_e32 v36, 1.0, v25, vcc
	v_pk_mul_f32 v[28:29], v[28:29], v[36:37]
	v_add_f32_e32 v36, v38, v42
	v_mul_f32_e32 v36, 0xbfb8aa3b, v36
	v_exp_f32_e32 v36, v36
	v_rcp_f32_e32 v37, v34
	v_pk_mul_f32 v[28:29], v[28:29], v[40:41]
	v_mul_f32_e32 v25, 0x3fb8aa3b, v33
	v_add_f32_e32 v36, 1.0, v36
	v_rcp_f32_e32 v36, v36
	v_lshlrev_b32_e32 v34, 16, v45
	v_exp_f32_e32 v25, v25
	v_pk_mul_f32 v[36:37], v[26:27], v[36:37]
	s_nop 0
	v_pk_add_f32 v[38:39], v[36:37], v[36:37]
	v_cvt_pk_bf16_f32 v33, v36, v37
	global_store_dwordx2 v[48:49], v[32:33], off offset:1632 sc1
	v_mul_f32_e32 v27, 0x3fb8aa3b, v38
	v_rndne_f32_e32 v27, v27
	v_fmamk_f32 v40, v27, 0xbf317218, v38
	v_fmac_f32_e32 v40, 0x3102e308, v27
	v_fmamk_f32 v41, v40, 0x395133b1, v177
	v_cmp_eq_f32_e32 vcc, s2, v27
	v_cvt_i32_f32_e32 v27, v27
	v_fmaak_f32 v41, v40, v41, 0x3c0887f9
	v_fmaak_f32 v41, v40, v41, 0x3d2aaa81
	v_fmaak_f32 v41, v40, v41, 0x3e2aaaab
; #define LAS __attribute__((address_space(3)))
; __device__ __forceinline__ unsigned pk2(float lo, float hi) { return pg8::cvt_pk_bf16(lo, hi); }
; __device__ __forceinline__ float sigmoidf_(float x) { return __builtin_amdgcn_rcpf(1.0f + __expf(-x)); }
; template <bool FULL> __device__ __forceinline__ void lru_tile(const Args& a, int l, int tile, LAS unsigned char* lds, int tid, int lane, int wave) {
;     ...
; #pragma unroll
;         for (int et = 0; et < 8; ++et) {
;             const int e0 = chh * 128 + et * 16, nb = e0 >> 6, el = e0 & 63;
;             f32x4 ra = {0.f, 0.f, 0.f, 0.f}, ia = {0.f, 0.f, 0.f, 0.f};
; #pragma unroll
;             for (int ks = 0; ks < 2; ++ks) {
;                 const bf16x8 xv = *(const LAS bf16x8*)(lds + OFF_XC + ((cb * 16 + fr) * 264 + nb * 64 + 32 * ks + 8 * fq) * 2);
;                 const bf16x8 wa = *(const bf16x8*)(WA + (size_t)nb * 4096 + (el + fr) * 64 + 32 * ks + 8 * fq);
;                 const bf16x8 wx = *(const bf16x8*)(WX + (size_t)nb * 4096 + (el + fr) * 64 + 32 * ks + 8 * fq);
;                 MFMA16(wa, xv, ra); MFMA16(wx, xv, ia);
;             }
;             const int c0 = e0 + 4 * fq;
;             const f32x4 ba = *(const f32x4*)(a.in[22] + (size_t)l * 256 + c0), bx = *(const f32x4*)(a.in[24] + (size_t)l * 256 + c0), c8v = *(const f32x4*)(c8t + c0);
;             const u32x2 xr = *(const LAS u32x2*)(lds + OFF_XC + ((cb * 16 + fr) * 264 + c0) * 2);
;             float lav[4];
;             const float xcv[4] = {__uint_as_float(xr.x << 16), __uint_as_float(xr.x & 0xffff0000u), __uint_as_float(xr.y << 16), __uint_as_float(xr.y & 0xffff0000u)};
; #pragma unroll
;             for (int r = 0; r < 4; ++r) {
;                 const float rg = sigmoidf_(ra[r] + ba[r]), ig = sigmoidf_(ia[r] + bx[r]);
;                 const float la = c8v[r] * rg; const float av_ = __expf(la); const float m2 = -expm1f(2.0f * la);
;                 av[et][r] = av_; bv[et][r] = sqrtf(fmaxf(m2, 0.f)) * ig * xcv[r]; lav[r] = la;
;             }
;             {
;               bf16* yr = Y + (size_t)(t0 + cb * 16 + fr) * DM + c0;
;               u32x2 wl_; wl_.x = pk2(lav[0], lav[1]); wl_.y = pk2(lav[2], lav[3]); *(u32x2*)(yr + 768) = wl_;
;               u32x2 wb_; wb_.x = pk2(bv[et][0], bv[et][1]); wb_.y = pk2(bv[et][2], bv[et][3]); *(u32x2*)(yr + 512) = wb_; }
	v_fma_f32 v41, v40, v41, 0.5
	v_ldexp_f32 v27, 1.0, v27
	v_mul_f32_e32 v41, v40, v41
	v_cndmask_b32_e32 v27, v27, v195, vcc
	v_fmac_f32_e32 v40, v40, v41
	v_add_f32_e32 v41, -1.0, v27
	v_fmac_f32_e32 v41, v27, v40
	v_add_f32_e32 v27, v41, v41
	v_cndmask_b32_e32 v27, v41, v27, vcc
	v_max_f32_e64 v27, -v27, 0
	v_cmp_gt_f32_e32 vcc, s19, v27
	v_mul_f32_e32 v40, 0x4f800000, v27
	v_cvt_pk_bf16_f32 v32, v28, v29
	v_mul_f32_e32 v26, 0x3fb8aa3b, v36
	v_cndmask_b32_e32 v27, v27, v40, vcc
	v_sqrt_f32_e32 v40, v27
	v_exp_f32_e32 v26, v26
	v_add_u32_e32 v41, -1, v40
	v_fma_f32 v42, -v41, v40, v27
	v_cmp_ge_f32_e64 s[36:37], 0, v42
	v_add_u32_e32 v42, 1, v40
	s_nop 0
	v_cndmask_b32_e64 v41, v40, v41, s[36:37]
	v_fma_f32 v40, -v42, v40, v27
	v_cmp_lt_f32_e64 s[36:37], 0, v40
	s_nop 1
	v_cndmask_b32_e64 v40, v41, v42, s[36:37]
	v_mul_f32_e32 v41, 0x37800000, v40
	v_cndmask_b32_e32 v40, v40, v41, vcc
	v_cmp_class_f32_e32 vcc, v27, v178
	s_nop 1
	v_cndmask_b32_e32 v27, v40, v27, vcc
	v_mul_f32_e32 v40, 0x3fb8aa3b, v39
	v_rndne_f32_e32 v40, v40
	v_fmamk_f32 v41, v40, 0xbf317218, v39
	v_fmac_f32_e32 v41, 0x3102e308, v40
	v_fmamk_f32 v42, v41, 0x395133b1, v177
	v_cmp_eq_f32_e32 vcc, s2, v40
	v_cvt_i32_f32_e32 v40, v40
	v_fmaak_f32 v42, v41, v42, 0x3c0887f9
	v_fmaak_f32 v42, v41, v42, 0x3d2aaa81
	v_fmaak_f32 v42, v41, v42, 0x3e2aaaab
	v_fma_f32 v42, v41, v42, 0.5
	v_ldexp_f32 v40, 1.0, v40
	v_mul_f32_e32 v42, v41, v42
	v_cndmask_b32_e32 v40, v40, v195, vcc
	v_fmac_f32_e32 v41, v41, v42
	v_add_f32_e32 v42, -1.0, v40
	v_fmac_f32_e32 v42, v40, v41
	v_add_f32_e32 v40, v42, v42
	v_cndmask_b32_e32 v40, v42, v40, vcc
	v_max_f32_e64 v40, -v40, 0
	v_cmp_gt_f32_e32 vcc, s19, v40
	v_mul_f32_e32 v41, 0x4f800000, v40
	s_nop 0
	v_cndmask_b32_e32 v40, v40, v41, vcc
	v_sqrt_f32_e32 v41, v40
	s_nop 0
	v_add_u32_e32 v42, -1, v41
	v_fma_f32 v43, -v42, v41, v40
	v_cmp_ge_f32_e64 s[36:37], 0, v43
	v_add_u32_e32 v43, 1, v41
	s_nop 0
	v_cndmask_b32_e64 v42, v41, v42, s[36:37]
	v_fma_f32 v41, -v43, v41, v40
	v_cmp_lt_f32_e64 s[36:37], 0, v41
	s_nop 1
	v_cndmask_b32_e64 v41, v42, v43, s[36:37]
	v_mul_f32_e32 v42, 0x37800000, v41
	v_cndmask_b32_e32 v41, v41, v42, vcc
	v_cmp_class_f32_e32 vcc, v40, v178
	s_nop 1
	v_cndmask_b32_e32 v40, v41, v40, vcc
	v_cmp_nlt_f32_e32 vcc, s86, v38
	s_nop 1
	v_cndmask_b32_e32 v27, 0, v27, vcc
	v_cmp_nlt_f32_e32 vcc, s86, v39
	s_nop 1
	v_cndmask_b32_e32 v40, 0, v40, vcc
	v_cmp_ngt_f32_e32 vcc, s56, v39
	s_nop 1
	v_cndmask_b32_e32 v39, 1.0, v40, vcc
	v_cmp_ngt_f32_e32 vcc, s56, v38
	s_nop 1
	v_cndmask_b32_e32 v38, 1.0, v27, vcc
	v_pk_mul_f32 v[30:31], v[30:31], v[38:39]
	v_mul_f32_e32 v27, 0x3fb8aa3b, v37
	v_pk_mul_f32 v[30:31], v[30:31], v[34:35]
	v_add_u32_e32 v34, s7, v50
	v_cvt_pk_bf16_f32 v33, v30, v31
	global_store_dwordx2 v[48:49], v[32:33], off offset:1120 sc1
	v_lshl_add_u64 v[32:33], s[26:27], 0, v[144:145]
	v_lshl_add_u64 v[48:49], v[32:33], 0, v[68:69]
	global_load_dwordx4 v[118:121], v[48:49], off
	global_load_dwordx4 v[122:125], v[48:49], off offset:64
	v_lshl_add_u64 v[32:33], s[24:25], 0, v[144:145]
	v_lshl_add_u32 v87, v34, 1, s0
	v_lshl_add_u64 v[50:51], v[32:33], 0, v[68:69]
	global_load_dwordx4 v[126:129], v[50:51], off
	global_load_dwordx4 v[130:133], v[50:51], off offset:64
	ds_read_b128 v[32:35], v87
	s_waitcnt vmcnt(3) lgkmcnt(0)
	v_mfma_f32_16x16x32_bf16 v[36:39], v[118:121], v[32:35], 0
	ds_read_b128 v[44:47], v87 offset:64
	s_ashr_i32 s7, s5, 31
	v_mov_b32_e32 v55, s7
	s_waitcnt vmcnt(1)
	v_mfma_f32_16x16x32_bf16 v[32:35], v[126:129], v[32:35], 0
	s_nop 0
	ds_read_b64 v[56:57], v56
	s_or_b32 s7, s5, 0x50
	s_waitcnt vmcnt(1) lgkmcnt(1)
	v_mfma_f32_16x16x32_bf16 v[40:43], v[122:125], v[44:47], v[36:39]
	s_nop 2
	v_lshlrev_b64 v[36:37], 2, v[54:55]
	v_lshl_add_u64 v[84:85], s[30:31], 0, v[36:37]
	v_lshl_add_u64 v[72:73], s[28:29], 0, v[36:37]
	s_waitcnt vmcnt(0)
	v_mfma_f32_16x16x32_bf16 v[32:35], v[130:133], v[44:47], v[32:35]
	global_load_dwordx4 v[44:47], v[84:85], off offset:256
	global_load_dwordx4 v[48:51], v[72:73], off offset:256
	v_lshl_add_u64 v[82:83], s[16:17], 0, v[36:37]
	global_load_dwordx4 v[36:39], v[82:83], off offset:256
	s_ashr_i32 s24, s7, 6
	s_ashr_i32 s25, s24, 31
	s_lshl_b64 s[24:25], s[24:25], 13
	s_add_u32 s26, s57, s24
	v_lshl_add_u64 v[80:81], v[54:55], 1, v[52:53]
	s_addc_u32 s27, s58, s25
	s_add_u32 s24, s59, s24
	s_addc_u32 s25, s60, s25
	v_exp_f32_e32 v27, v27
	s_waitcnt vmcnt(2)
	v_add_f32_e32 v32, v32, v44
	v_mul_f32_e32 v32, 0xbfb8aa3b, v32
	v_exp_f32_e32 v32, v32
	s_waitcnt vmcnt(1)
	v_add_f32_e32 v40, v40, v48
	v_mul_f32_e32 v40, 0xbfb8aa3b, v40
	v_exp_f32_e32 v40, v40
	v_add_f32_e32 v32, 1.0, v32
	v_rcp_f32_e32 v44, v32
	v_add_f32_e32 v32, v41, v49
	v_mul_f32_e32 v32, 0xbfb8aa3b, v32
	v_exp_f32_e32 v32, v32
	v_add_f32_e32 v40, 1.0, v40
	v_rcp_f32_e32 v40, v40
	s_waitcnt lgkmcnt(0)
	v_lshlrev_b32_e32 v48, 16, v56
	v_add_f32_e32 v32, 1.0, v32
	v_rcp_f32_e32 v41, v32
	v_add_f32_e32 v32, v33, v45
	v_and_b32_e32 v49, 0xffff0000, v56
	v_mul_f32_e32 v32, 0xbfb8aa3b, v32
	s_waitcnt vmcnt(0)
; #define LAS __attribute__((address_space(3)))
; __device__ __forceinline__ unsigned pk2(float lo, float hi) { return pg8::cvt_pk_bf16(lo, hi); }
; __device__ __forceinline__ float sigmoidf_(float x) { return __builtin_amdgcn_rcpf(1.0f + __expf(-x)); }
; template <bool FULL> __device__ __forceinline__ void lru_tile(const Args& a, int l, int tile, LAS unsigned char* lds, int tid, int lane, int wave) {
;     ...
;             const int c0 = e0 + 4 * fq;
;             const f32x4 ba = *(const f32x4*)(a.in[22] + (size_t)l * 256 + c0), bx = *(const f32x4*)(a.in[24] + (size_t)l * 256 + c0), c8v = *(const f32x4*)(c8t + c0);
;             const u32x2 xr = *(const LAS u32x2*)(lds + OFF_XC + ((cb * 16 + fr) * 264 + c0) * 2);
;             float lav[4];
;             const float xcv[4] = {__uint_as_float(xr.x << 16), __uint_as_float(xr.x & 0xffff0000u), __uint_as_float(xr.y << 16), __uint_as_float(xr.y & 0xffff0000u)};
; #pragma unroll
;             for (int r = 0; r < 4; ++r) {
;                 const float rg = sigmoidf_(ra[r] + ba[r]), ig = sigmoidf_(ia[r] + bx[r]);
;                 const float la = c8v[r] * rg; const float av_ = __expf(la); const float m2 = -expm1f(2.0f * la);
;                 av[et][r] = av_; bv[et][r] = sqrtf(fmaxf(m2, 0.f)) * ig * xcv[r]; lav[r] = la;
;             }
;             {
;               bf16* yr = Y + (size_t)(t0 + cb * 16 + fr) * DM + c0;
;               u32x2 wl_; wl_.x = pk2(lav[0], lav[1]); wl_.y = pk2(lav[2], lav[3]); *(u32x2*)(yr + 768) = wl_;
;               u32x2 wb_; wb_.x = pk2(bv[et][0], bv[et][1]); wb_.y = pk2(bv[et][2], bv[et][3]); *(u32x2*)(yr + 512) = wb_; }
	v_pk_mul_f32 v[40:41], v[36:37], v[40:41]
	v_exp_f32_e32 v32, v32
	v_pk_add_f32 v[36:37], v[40:41], v[40:41]
	v_add_f32_e32 v42, v42, v50
	v_mul_f32_e32 v33, 0x3fb8aa3b, v36
	v_rndne_f32_e32 v33, v33
	v_fmamk_f32 v56, v33, 0xbf317218, v36
	v_fmac_f32_e32 v56, 0x3102e308, v33
	v_fmamk_f32 v58, v56, 0x395133b1, v177
	v_cmp_eq_f32_e32 vcc, s2, v33
	v_cvt_i32_f32_e32 v33, v33
	v_fmaak_f32 v58, v56, v58, 0x3c0887f9
	v_fmaak_f32 v58, v56, v58, 0x3d2aaa81
	v_fmaak_f32 v58, v56, v58, 0x3e2aaaab
	v_fma_f32 v58, v56, v58, 0.5
	v_ldexp_f32 v33, 1.0, v33
	v_mul_f32_e32 v58, v56, v58
	v_cndmask_b32_e32 v33, v33, v195, vcc
	v_fmac_f32_e32 v56, v56, v58
	v_add_f32_e32 v58, -1.0, v33
	v_fmac_f32_e32 v58, v33, v56
	v_add_f32_e32 v33, v58, v58
	v_cndmask_b32_e32 v33, v58, v33, vcc
	v_max_f32_e64 v33, -v33, 0
	v_cmp_gt_f32_e32 vcc, s19, v33
	v_mul_f32_e32 v56, 0x4f800000, v33
	v_add_f32_e32 v34, v34, v46
	v_cndmask_b32_e32 v33, v33, v56, vcc
	v_sqrt_f32_e32 v56, v33
	v_mul_f32_e32 v42, 0xbfb8aa3b, v42
	v_mul_f32_e32 v34, 0xbfb8aa3b, v34
	v_add_f32_e32 v32, 1.0, v32
	v_add_u32_e32 v58, -1, v56
	v_fma_f32 v59, -v58, v56, v33
	v_cmp_ge_f32_e64 s[36:37], 0, v59
	v_add_u32_e32 v59, 1, v56
	v_exp_f32_e32 v42, v42
	v_cndmask_b32_e64 v58, v56, v58, s[36:37]
	v_fma_f32 v56, -v59, v56, v33
	v_cmp_lt_f32_e64 s[36:37], 0, v56
	v_exp_f32_e32 v34, v34
	v_rcp_f32_e32 v45, v32
	v_cndmask_b32_e64 v56, v58, v59, s[36:37]
	v_mul_f32_e32 v58, 0x37800000, v56
	v_cndmask_b32_e32 v56, v56, v58, vcc
	v_cmp_class_f32_e32 vcc, v33, v178
	v_add_f32_e32 v42, 1.0, v42
	v_add_f32_e32 v34, 1.0, v34
	v_cndmask_b32_e32 v33, v56, v33, vcc
	v_mul_f32_e32 v56, 0x3fb8aa3b, v37
	v_rndne_f32_e32 v56, v56
	v_fmamk_f32 v58, v56, 0xbf317218, v37
	v_fmac_f32_e32 v58, 0x3102e308, v56
	v_fmamk_f32 v59, v58, 0x395133b1, v177
	v_cmp_eq_f32_e32 vcc, s2, v56
	v_cvt_i32_f32_e32 v56, v56
	v_fmaak_f32 v59, v58, v59, 0x3c0887f9
	v_fmaak_f32 v59, v58, v59, 0x3d2aaa81
	v_fmaak_f32 v59, v58, v59, 0x3e2aaaab
	v_fma_f32 v59, v58, v59, 0.5
	v_ldexp_f32 v56, 1.0, v56
	v_mul_f32_e32 v59, v58, v59
	v_cndmask_b32_e32 v56, v56, v195, vcc
	v_fmac_f32_e32 v58, v58, v59
	v_add_f32_e32 v59, -1.0, v56
	v_fmac_f32_e32 v59, v56, v58
	v_add_f32_e32 v56, v59, v59
	v_cndmask_b32_e32 v56, v59, v56, vcc
	v_max_f32_e64 v56, -v56, 0
	v_cmp_gt_f32_e32 vcc, s19, v56
	v_mul_f32_e32 v58, 0x4f800000, v56
	v_mul_f32_e32 v32, 0x3fb8aa3b, v40
	v_cndmask_b32_e32 v56, v56, v58, vcc
	v_sqrt_f32_e32 v58, v56
	v_lshlrev_b32_e32 v46, 16, v57
	v_cvt_pk_bf16_f32 v40, v40, v41
	v_exp_f32_e32 v32, v32
	v_add_u32_e32 v59, -1, v58
	v_fma_f32 v62, -v59, v58, v56
	v_cmp_ge_f32_e64 s[36:37], 0, v62
	v_add_u32_e32 v62, 1, v58
	s_nop 0
	v_cndmask_b32_e64 v59, v58, v59, s[36:37]
	v_fma_f32 v58, -v62, v58, v56
	v_cmp_lt_f32_e64 s[36:37], 0, v58
	s_nop 1
	v_cndmask_b32_e64 v58, v59, v62, s[36:37]
	v_mul_f32_e32 v59, 0x37800000, v58
	v_cndmask_b32_e32 v58, v58, v59, vcc
	v_cmp_class_f32_e32 vcc, v56, v178
	v_or_b32_e32 v62, s7, v86
	v_mad_u32_u24 v62, v79, s12, v62
	v_cndmask_b32_e32 v56, v58, v56, vcc
	v_cmp_nlt_f32_e32 vcc, s86, v36
	v_lshl_add_u32 v62, v62, 1, s0
	s_or_b32 s7, s5, 0x60
	v_cndmask_b32_e32 v33, 0, v33, vcc
	v_cmp_nlt_f32_e32 vcc, s86, v37
	v_or_b32_e32 v74, s7, v86
	v_mad_u32_u24 v74, v79, s12, v74
	v_cndmask_b32_e32 v56, 0, v56, vcc
	v_cmp_ngt_f32_e32 vcc, s56, v37
	v_lshl_add_u32 v74, v74, 1, s0
	s_nop 0
	v_cndmask_b32_e32 v37, 1.0, v56, vcc
	v_cmp_ngt_f32_e32 vcc, s56, v36
	s_nop 1
	v_cndmask_b32_e32 v36, 1.0, v33, vcc
	v_pk_mul_f32 v[36:37], v[44:45], v[36:37]
	v_rcp_f32_e32 v44, v42
	v_rcp_f32_e32 v42, v34
	v_add_f32_e32 v34, v43, v51
	v_mul_f32_e32 v34, 0xbfb8aa3b, v34
	v_exp_f32_e32 v34, v34
	v_pk_mul_f32 v[36:37], v[36:37], v[48:49]
	v_mul_f32_e32 v33, 0x3fb8aa3b, v41
	v_exp_f32_e32 v33, v33
	v_add_f32_e32 v34, 1.0, v34
	v_rcp_f32_e32 v45, v34
	v_add_f32_e32 v34, v35, v47
	v_mul_f32_e32 v34, 0xbfb8aa3b, v34
	v_exp_f32_e32 v34, v34
	v_pk_mul_f32 v[44:45], v[38:39], v[44:45]
	v_and_b32_e32 v47, 0xffff0000, v57
	v_pk_add_f32 v[38:39], v[44:45], v[44:45]
	v_add_f32_e32 v34, 1.0, v34
	v_mul_f32_e32 v35, 0x3fb8aa3b, v38
	v_rndne_f32_e32 v35, v35
	v_fmamk_f32 v48, v35, 0xbf317218, v38
	v_fmac_f32_e32 v48, 0x3102e308, v35
	v_fmamk_f32 v49, v48, 0x395133b1, v177
	v_cmp_eq_f32_e32 vcc, s2, v35
	v_cvt_i32_f32_e32 v35, v35
	v_fmaak_f32 v49, v48, v49, 0x3c0887f9
	v_fmaak_f32 v49, v48, v49, 0x3d2aaa81
	v_fmaak_f32 v49, v48, v49, 0x3e2aaaab
	v_fma_f32 v49, v48, v49, 0.5
	v_ldexp_f32 v35, 1.0, v35
	v_mul_f32_e32 v49, v48, v49
	v_cndmask_b32_e32 v35, v35, v195, vcc
	v_fmac_f32_e32 v48, v48, v49
	v_add_f32_e32 v49, -1.0, v35
	v_fmac_f32_e32 v49, v35, v48
	v_add_f32_e32 v35, v49, v49
	v_cndmask_b32_e32 v35, v49, v35, vcc
	v_max_f32_e64 v35, -v35, 0
	v_cmp_gt_f32_e32 vcc, s19, v35
	v_mul_f32_e32 v48, 0x4f800000, v35
	v_rcp_f32_e32 v43, v34
	v_cndmask_b32_e32 v35, v35, v48, vcc
	v_sqrt_f32_e32 v48, v35
	v_cvt_pk_bf16_f32 v41, v44, v45
	global_store_dwordx2 v[80:81], v[40:41], off offset:1664 sc1
	v_cvt_pk_bf16_f32 v40, v36, v37
	v_add_u32_e32 v49, -1, v48
	v_fma_f32 v50, -v49, v48, v35
	v_cmp_ge_f32_e64 s[36:37], 0, v50
	v_add_u32_e32 v50, 1, v48
	v_mul_f32_e32 v34, 0x3fb8aa3b, v44
	v_cndmask_b32_e64 v49, v48, v49, s[36:37]
	v_fma_f32 v48, -v50, v48, v35
	v_cmp_lt_f32_e64 s[36:37], 0, v48
	v_exp_f32_e32 v34, v34
	s_nop 0
	v_cndmask_b32_e64 v48, v49, v50, s[36:37]
	v_mul_f32_e32 v49, 0x37800000, v48
	v_cndmask_b32_e32 v48, v48, v49, vcc
	v_cmp_class_f32_e32 vcc, v35, v178
	s_nop 1
	v_cndmask_b32_e32 v35, v48, v35, vcc
	v_mul_f32_e32 v48, 0x3fb8aa3b, v39
	v_rndne_f32_e32 v48, v48
	v_fmamk_f32 v49, v48, 0xbf317218, v39
	v_fmac_f32_e32 v49, 0x3102e308, v48
; #define LAS __attribute__((address_space(3)))
; __device__ __forceinline__ unsigned pk2(float lo, float hi) { return pg8::cvt_pk_bf16(lo, hi); }
; __device__ __forceinline__ float sigmoidf_(float x) { return __builtin_amdgcn_rcpf(1.0f + __expf(-x)); }
; template <bool FULL> __device__ __forceinline__ void lru_tile(const Args& a, int l, int tile, LAS unsigned char* lds, int tid, int lane, int wave) {
;     ...
; #pragma unroll
;         for (int et = 0; et < 8; ++et) {
;             const int e0 = chh * 128 + et * 16, nb = e0 >> 6, el = e0 & 63;
;             f32x4 ra = {0.f, 0.f, 0.f, 0.f}, ia = {0.f, 0.f, 0.f, 0.f};
; #pragma unroll
;             for (int ks = 0; ks < 2; ++ks) {
;                 const bf16x8 xv = *(const LAS bf16x8*)(lds + OFF_XC + ((cb * 16 + fr) * 264 + nb * 64 + 32 * ks + 8 * fq) * 2);
;                 const bf16x8 wa = *(const bf16x8*)(WA + (size_t)nb * 4096 + (el + fr) * 64 + 32 * ks + 8 * fq);
;                 const bf16x8 wx = *(const bf16x8*)(WX + (size_t)nb * 4096 + (el + fr) * 64 + 32 * ks + 8 * fq);
;                 MFMA16(wa, xv, ra); MFMA16(wx, xv, ia);
;     ...
;             const int c0 = e0 + 4 * fq;
;             const f32x4 ba = *(const f32x4*)(a.in[22] + (size_t)l * 256 + c0), bx = *(const f32x4*)(a.in[24] + (size_t)l * 256 + c0), c8v = *(const f32x4*)(c8t + c0);
;             const u32x2 xr = *(const LAS u32x2*)(lds + OFF_XC + ((cb * 16 + fr) * 264 + c0) * 2);
;             float lav[4];
;             const float xcv[4] = {__uint_as_float(xr.x << 16), __uint_as_float(xr.x & 0xffff0000u), __uint_as_float(xr.y << 16), __uint_as_float(xr.y & 0xffff0000u)};
; #pragma unroll
;             for (int r = 0; r < 4; ++r) {
;                 const float rg = sigmoidf_(ra[r] + ba[r]), ig = sigmoidf_(ia[r] + bx[r]);
;                 const float la = c8v[r] * rg; const float av_ = __expf(la); const float m2 = -expm1f(2.0f * la);
;                 av[et][r] = av_; bv[et][r] = sqrtf(fmaxf(m2, 0.f)) * ig * xcv[r]; lav[r] = la;
;             }
;             {
;               bf16* yr = Y + (size_t)(t0 + cb * 16 + fr) * DM + c0;
;               u32x2 wl_; wl_.x = pk2(lav[0], lav[1]); wl_.y = pk2(lav[2], lav[3]); *(u32x2*)(yr + 768) = wl_;
;               u32x2 wb_; wb_.x = pk2(bv[et][0], bv[et][1]); wb_.y = pk2(bv[et][2], bv[et][3]); *(u32x2*)(yr + 512) = wb_; }
	v_fmamk_f32 v50, v49, 0x395133b1, v177
	v_cmp_eq_f32_e32 vcc, s2, v48
	v_cvt_i32_f32_e32 v48, v48
	v_fmaak_f32 v50, v49, v50, 0x3c0887f9
	v_fmaak_f32 v50, v49, v50, 0x3d2aaa81
	v_fmaak_f32 v50, v49, v50, 0x3e2aaaab
	v_fma_f32 v50, v49, v50, 0.5
	v_ldexp_f32 v48, 1.0, v48
	v_mul_f32_e32 v50, v49, v50
	v_cndmask_b32_e32 v48, v48, v195, vcc
	v_fmac_f32_e32 v49, v49, v50
	v_add_f32_e32 v50, -1.0, v48
	v_fmac_f32_e32 v50, v48, v49
	v_add_f32_e32 v48, v50, v50
	v_cndmask_b32_e32 v48, v50, v48, vcc
	v_max_f32_e64 v48, -v48, 0
	v_cmp_gt_f32_e32 vcc, s19, v48
	v_mul_f32_e32 v49, 0x4f800000, v48
	s_nop 0
	v_cndmask_b32_e32 v48, v48, v49, vcc
	v_sqrt_f32_e32 v49, v48
	s_nop 0
	v_add_u32_e32 v50, -1, v49
	v_fma_f32 v51, -v50, v49, v48
	v_cmp_ge_f32_e64 s[36:37], 0, v51
	v_add_u32_e32 v51, 1, v49
	s_nop 0
	v_cndmask_b32_e64 v50, v49, v50, s[36:37]
	v_fma_f32 v49, -v51, v49, v48
	v_cmp_lt_f32_e64 s[36:37], 0, v49
	s_nop 1
	v_cndmask_b32_e64 v49, v50, v51, s[36:37]
	v_mul_f32_e32 v50, 0x37800000, v49
	v_cndmask_b32_e32 v49, v49, v50, vcc
	v_cmp_class_f32_e32 vcc, v48, v178
	s_nop 1
	v_cndmask_b32_e32 v48, v49, v48, vcc
	v_cmp_nlt_f32_e32 vcc, s86, v38
	s_nop 1
	v_cndmask_b32_e32 v35, 0, v35, vcc
	v_cmp_nlt_f32_e32 vcc, s86, v39
	s_nop 1
	v_cndmask_b32_e32 v48, 0, v48, vcc
	v_cmp_ngt_f32_e32 vcc, s56, v39
	s_nop 1
	v_cndmask_b32_e32 v39, 1.0, v48, vcc
	v_cmp_ngt_f32_e32 vcc, s56, v38
	s_nop 1
	v_cndmask_b32_e32 v38, 1.0, v35, vcc
	v_pk_mul_f32 v[38:39], v[42:43], v[38:39]
	v_mul_f32_e32 v35, 0x3fb8aa3b, v45
	v_pk_mul_f32 v[38:39], v[38:39], v[46:47]
	v_exp_f32_e32 v35, v35
	v_cvt_pk_bf16_f32 v41, v38, v39
	global_store_dwordx2 v[80:81], v[40:41], off offset:1152 sc1
	v_lshl_add_u64 v[40:41], s[26:27], 0, v[144:145]
	v_lshl_add_u64 v[52:53], v[40:41], 0, v[68:69]
	global_load_dwordx4 v[118:121], v[52:53], off offset:2048
	global_load_dwordx4 v[122:125], v[52:53], off offset:2112
	v_lshl_add_u64 v[40:41], s[24:25], 0, v[144:145]
	v_lshl_add_u64 v[56:57], v[40:41], 0, v[68:69]
	global_load_dwordx4 v[126:129], v[56:57], off offset:2048
	global_load_dwordx4 v[130:133], v[56:57], off offset:2112
	ds_read_b128 v[40:43], v87
	s_waitcnt vmcnt(3) lgkmcnt(0)
	v_mfma_f32_16x16x32_bf16 v[44:47], v[118:121], v[40:43], 0
	s_ashr_i32 s24, s7, 6
	s_ashr_i32 s25, s24, 31
	s_lshl_b64 s[24:25], s[24:25], 13
	s_waitcnt vmcnt(1)
	v_mfma_f32_16x16x32_bf16 v[40:43], v[126:129], v[40:43], 0
	ds_read_b128 v[48:51], v87 offset:64
	s_nop 0
	s_add_u32 s26, s57, s24
	s_waitcnt vmcnt(1) lgkmcnt(0)
	v_mfma_f32_16x16x32_bf16 v[52:55], v[122:125], v[48:51], v[44:47]
	s_addc_u32 s27, s58, s25
	s_add_u32 s24, s59, s24
	s_addc_u32 s25, s60, s25
	s_waitcnt vmcnt(0)
	v_mfma_f32_16x16x32_bf16 v[44:47], v[130:133], v[48:51], v[40:43]
	global_load_dwordx4 v[56:59], v[72:73], off offset:320
	global_load_dwordx4 v[48:51], v[84:85], off offset:320
	s_nop 0
	global_load_dwordx4 v[40:43], v[82:83], off offset:320
	ds_read_b64 v[62:63], v62
	s_or_b32 s5, s5, 0x70
	v_or_b32_e32 v86, s5, v86
	v_mad_u32_u24 v79, v79, s12, v86
	v_lshl_add_u32 v79, v79, 1, s0
	s_waitcnt vmcnt(2)
	v_add_f32_e32 v52, v52, v56
	s_waitcnt vmcnt(1)
	v_add_f32_e32 v44, v44, v48
	v_add_f32_e32 v48, v53, v57
	v_mul_f32_e32 v52, 0xbfb8aa3b, v52
	v_mul_f32_e32 v48, 0xbfb8aa3b, v48
	v_exp_f32_e32 v52, v52
	v_exp_f32_e32 v48, v48
	v_add_f32_e32 v45, v45, v49
	s_waitcnt lgkmcnt(0)
	v_lshlrev_b32_e32 v56, 16, v62
	v_add_f32_e32 v52, 1.0, v52
	v_add_f32_e32 v48, 1.0, v48
	v_rcp_f32_e32 v52, v52
	v_rcp_f32_e32 v53, v48
	v_and_b32_e32 v57, 0xffff0000, v62
	v_mul_f32_e32 v44, 0xbfb8aa3b, v44
	v_mul_f32_e32 v45, 0xbfb8aa3b, v45
	s_waitcnt vmcnt(0)
	v_pk_mul_f32 v[48:49], v[40:41], v[52:53]
	v_exp_f32_e32 v44, v44
	v_pk_add_f32 v[52:53], v[48:49], v[48:49]
	v_exp_f32_e32 v45, v45
	v_mul_f32_e32 v41, 0x3fb8aa3b, v52
	v_rndne_f32_e32 v41, v41
	v_fmamk_f32 v62, v41, 0xbf317218, v52
	v_fmac_f32_e32 v62, 0x3102e308, v41
	v_fmamk_f32 v64, v62, 0x395133b1, v177
	v_cmp_eq_f32_e32 vcc, s2, v41
	v_cvt_i32_f32_e32 v41, v41
	v_fmaak_f32 v64, v62, v64, 0x3c0887f9
	v_fmaak_f32 v64, v62, v64, 0x3d2aaa81
	v_fmaak_f32 v64, v62, v64, 0x3e2aaaab
	v_fma_f32 v64, v62, v64, 0.5
	v_ldexp_f32 v41, 1.0, v41
	v_mul_f32_e32 v64, v62, v64
	v_cndmask_b32_e32 v41, v41, v195, vcc
	v_fmac_f32_e32 v62, v62, v64
	v_add_f32_e32 v64, -1.0, v41
	v_fmac_f32_e32 v64, v41, v62
	v_add_f32_e32 v41, v64, v64
	v_cndmask_b32_e32 v41, v64, v41, vcc
	v_max_f32_e64 v41, -v41, 0
	v_cmp_gt_f32_e32 vcc, s19, v41
	v_mul_f32_e32 v62, 0x4f800000, v41
	v_add_f32_e32 v44, 1.0, v44
	v_cndmask_b32_e32 v41, v41, v62, vcc
	v_sqrt_f32_e32 v62, v41
	v_add_f32_e32 v45, 1.0, v45
	v_rcp_f32_e32 v44, v44
	v_rcp_f32_e32 v45, v45
	v_add_u32_e32 v64, -1, v62
	v_fma_f32 v65, -v64, v62, v41
	v_cmp_ge_f32_e64 s[36:37], 0, v65
	v_add_u32_e32 v65, 1, v62
	v_add_f32_e32 v46, v46, v50
	v_cndmask_b32_e64 v64, v62, v64, s[36:37]
	v_fma_f32 v62, -v65, v62, v41
	v_cmp_lt_f32_e64 s[36:37], 0, v62
	v_add_f32_e32 v50, v55, v59
	v_mul_f32_e32 v50, 0xbfb8aa3b, v50
	v_cndmask_b32_e64 v62, v64, v65, s[36:37]
	v_mul_f32_e32 v64, 0x37800000, v62
	v_cndmask_b32_e32 v62, v62, v64, vcc
	v_cmp_class_f32_e32 vcc, v41, v178
	v_exp_f32_e32 v50, v50
	v_add_f32_e32 v47, v47, v51
	v_cndmask_b32_e32 v41, v62, v41, vcc
	v_mul_f32_e32 v62, 0x3fb8aa3b, v53
	v_rndne_f32_e32 v62, v62
	v_fmamk_f32 v64, v62, 0xbf317218, v53
	v_fmac_f32_e32 v64, 0x3102e308, v62
	v_fmamk_f32 v65, v64, 0x395133b1, v177
	v_cmp_eq_f32_e32 vcc, s2, v62
	v_cvt_i32_f32_e32 v62, v62
	v_fmaak_f32 v65, v64, v65, 0x3c0887f9
	v_fmaak_f32 v65, v64, v65, 0x3d2aaa81
	v_fmaak_f32 v65, v64, v65, 0x3e2aaaab
	v_fma_f32 v65, v64, v65, 0.5
	v_ldexp_f32 v62, 1.0, v62
; #define LAS __attribute__((address_space(3)))
; __device__ __forceinline__ unsigned pk2(float lo, float hi) { return pg8::cvt_pk_bf16(lo, hi); }
; __device__ __forceinline__ float sigmoidf_(float x) { return __builtin_amdgcn_rcpf(1.0f + __expf(-x)); }
; template <bool FULL> __device__ __forceinline__ void lru_tile(const Args& a, int l, int tile, LAS unsigned char* lds, int tid, int lane, int wave) {
;     ...
;         for (int et = 0; et < 8; ++et) {
;             const int e0 = chh * 128 + et * 16, nb = e0 >> 6, el = e0 & 63;
;             f32x4 ra = {0.f, 0.f, 0.f, 0.f}, ia = {0.f, 0.f, 0.f, 0.f};
; #pragma unroll
;             for (int ks = 0; ks < 2; ++ks) {
;                 const bf16x8 xv = *(const LAS bf16x8*)(lds + OFF_XC + ((cb * 16 + fr) * 264 + nb * 64 + 32 * ks + 8 * fq) * 2);
;                 const bf16x8 wa = *(const bf16x8*)(WA + (size_t)nb * 4096 + (el + fr) * 64 + 32 * ks + 8 * fq);
;                 const bf16x8 wx = *(const bf16x8*)(WX + (size_t)nb * 4096 + (el + fr) * 64 + 32 * ks + 8 * fq);
;                 MFMA16(wa, xv, ra); MFMA16(wx, xv, ia);
;             }
;             const int c0 = e0 + 4 * fq;
;             const f32x4 ba = *(const f32x4*)(a.in[22] + (size_t)l * 256 + c0), bx = *(const f32x4*)(a.in[24] + (size_t)l * 256 + c0), c8v = *(const f32x4*)(c8t + c0);
;             const u32x2 xr = *(const LAS u32x2*)(lds + OFF_XC + ((cb * 16 + fr) * 264 + c0) * 2);
;             float lav[4];
;             const float xcv[4] = {__uint_as_float(xr.x << 16), __uint_as_float(xr.x & 0xffff0000u), __uint_as_float(xr.y << 16), __uint_as_float(xr.y & 0xffff0000u)};
; #pragma unroll
;             for (int r = 0; r < 4; ++r) {
;                 const float rg = sigmoidf_(ra[r] + ba[r]), ig = sigmoidf_(ia[r] + bx[r]);
;                 const float la = c8v[r] * rg; const float av_ = __expf(la); const float m2 = -expm1f(2.0f * la);
;                 av[et][r] = av_; bv[et][r] = sqrtf(fmaxf(m2, 0.f)) * ig * xcv[r]; lav[r] = la;
;             }
;             {
;               bf16* yr = Y + (size_t)(t0 + cb * 16 + fr) * DM + c0;
;               u32x2 wl_; wl_.x = pk2(lav[0], lav[1]); wl_.y = pk2(lav[2], lav[3]); *(u32x2*)(yr + 768) = wl_;
;               u32x2 wb_; wb_.x = pk2(bv[et][0], bv[et][1]); wb_.y = pk2(bv[et][2], bv[et][3]); *(u32x2*)(yr + 512) = wb_; }
;             if ((et & 3) == 3) asm volatile("" ::: "memory");
;         }
	v_mul_f32_e32 v65, v64, v65
	v_cndmask_b32_e32 v62, v62, v195, vcc
	v_fmac_f32_e32 v64, v64, v65
	v_add_f32_e32 v65, -1.0, v62
	v_fmac_f32_e32 v65, v62, v64
	v_add_f32_e32 v62, v65, v65
	v_cndmask_b32_e32 v62, v65, v62, vcc
	v_max_f32_e64 v62, -v62, 0
	v_cmp_gt_f32_e32 vcc, s19, v62
	v_mul_f32_e32 v64, 0x4f800000, v62
	v_add_f32_e32 v50, 1.0, v50
	v_cndmask_b32_e32 v62, v62, v64, vcc
	v_sqrt_f32_e32 v64, v62
	v_mul_f32_e32 v46, 0xbfb8aa3b, v46
	v_mul_f32_e32 v47, 0xbfb8aa3b, v47
	v_exp_f32_e32 v46, v46
	v_add_u32_e32 v65, -1, v64
	v_fma_f32 v66, -v65, v64, v62
	v_cmp_ge_f32_e64 s[36:37], 0, v66
	v_add_u32_e32 v66, 1, v64
	v_exp_f32_e32 v47, v47
	v_cndmask_b32_e64 v65, v64, v65, s[36:37]
	v_fma_f32 v64, -v66, v64, v62
	v_cmp_lt_f32_e64 s[36:37], 0, v64
	v_add_f32_e32 v46, 1.0, v46
	v_add_f32_e32 v47, 1.0, v47
	v_cndmask_b32_e64 v64, v65, v66, s[36:37]
	v_mul_f32_e32 v65, 0x37800000, v64
	v_cndmask_b32_e32 v64, v64, v65, vcc
	v_cmp_class_f32_e32 vcc, v62, v178
	v_rcp_f32_e32 v46, v46
	v_rcp_f32_e32 v47, v47
	v_cndmask_b32_e32 v62, v64, v62, vcc
	v_cmp_nlt_f32_e32 vcc, s86, v52
	v_mul_f32_e32 v40, 0x3fb8aa3b, v48
	v_and_b32_e32 v51, 0xffff0000, v63
	v_cndmask_b32_e32 v41, 0, v41, vcc
	v_cmp_nlt_f32_e32 vcc, s86, v53
	v_cvt_pk_bf16_f32 v48, v48, v49
	v_exp_f32_e32 v40, v40
	s_nop 0
	v_cndmask_b32_e32 v62, 0, v62, vcc
	v_cmp_ngt_f32_e32 vcc, s56, v53
	s_nop 1
	v_cndmask_b32_e32 v53, 1.0, v62, vcc
	v_cmp_ngt_f32_e32 vcc, s56, v52
	s_nop 1
	v_cndmask_b32_e32 v52, 1.0, v41, vcc
	v_pk_mul_f32 v[44:45], v[44:45], v[52:53]
	v_add_f32_e32 v52, v54, v58
	v_mul_f32_e32 v52, 0xbfb8aa3b, v52
	v_exp_f32_e32 v52, v52
	v_rcp_f32_e32 v53, v50
	v_pk_mul_f32 v[44:45], v[44:45], v[56:57]
	v_mul_f32_e32 v41, 0x3fb8aa3b, v49
	v_add_f32_e32 v52, 1.0, v52
	v_rcp_f32_e32 v52, v52
	v_lshlrev_b32_e32 v50, 16, v63
	v_exp_f32_e32 v41, v41
	v_pk_mul_f32 v[52:53], v[42:43], v[52:53]
	s_nop 0
	v_pk_add_f32 v[54:55], v[52:53], v[52:53]
	v_cvt_pk_bf16_f32 v49, v52, v53
	global_store_dwordx2 v[80:81], v[48:49], off offset:1696 sc1
	v_mul_f32_e32 v43, 0x3fb8aa3b, v54
	v_rndne_f32_e32 v43, v43
	v_fmamk_f32 v56, v43, 0xbf317218, v54
	v_fmac_f32_e32 v56, 0x3102e308, v43
	v_fmamk_f32 v57, v56, 0x395133b1, v177
	v_cmp_eq_f32_e32 vcc, s2, v43
	v_cvt_i32_f32_e32 v43, v43
	v_fmaak_f32 v57, v56, v57, 0x3c0887f9
	v_fmaak_f32 v57, v56, v57, 0x3d2aaa81
	v_fmaak_f32 v57, v56, v57, 0x3e2aaaab
	v_fma_f32 v57, v56, v57, 0.5
	v_ldexp_f32 v43, 1.0, v43
	v_mul_f32_e32 v57, v56, v57
	v_cndmask_b32_e32 v43, v43, v195, vcc
	v_fmac_f32_e32 v56, v56, v57
	v_add_f32_e32 v57, -1.0, v43
	v_fmac_f32_e32 v57, v43, v56
	v_add_f32_e32 v43, v57, v57
	v_cndmask_b32_e32 v43, v57, v43, vcc
	v_max_f32_e64 v43, -v43, 0
	v_cmp_gt_f32_e32 vcc, s19, v43
	v_mul_f32_e32 v56, 0x4f800000, v43
	v_cvt_pk_bf16_f32 v48, v44, v45
	v_mul_f32_e32 v42, 0x3fb8aa3b, v52
	v_cndmask_b32_e32 v43, v43, v56, vcc
	v_sqrt_f32_e32 v56, v43
	v_exp_f32_e32 v42, v42
	v_add_u32_e32 v57, -1, v56
	v_fma_f32 v58, -v57, v56, v43
	v_cmp_ge_f32_e64 s[36:37], 0, v58
	v_add_u32_e32 v58, 1, v56
	s_nop 0
	v_cndmask_b32_e64 v57, v56, v57, s[36:37]
	v_fma_f32 v56, -v58, v56, v43
	v_cmp_lt_f32_e64 s[36:37], 0, v56
	s_nop 1
	v_cndmask_b32_e64 v56, v57, v58, s[36:37]
	v_mul_f32_e32 v57, 0x37800000, v56
	v_cndmask_b32_e32 v56, v56, v57, vcc
	v_cmp_class_f32_e32 vcc, v43, v178
	s_nop 1
	v_cndmask_b32_e32 v43, v56, v43, vcc
	v_mul_f32_e32 v56, 0x3fb8aa3b, v55
	v_rndne_f32_e32 v56, v56
	v_fmamk_f32 v57, v56, 0xbf317218, v55
	v_fmac_f32_e32 v57, 0x3102e308, v56
	v_fmamk_f32 v58, v57, 0x395133b1, v177
	v_cmp_eq_f32_e32 vcc, s2, v56
	v_cvt_i32_f32_e32 v56, v56
	v_fmaak_f32 v58, v57, v58, 0x3c0887f9
	v_fmaak_f32 v58, v57, v58, 0x3d2aaa81
	v_fmaak_f32 v58, v57, v58, 0x3e2aaaab
	v_fma_f32 v58, v57, v58, 0.5
	v_ldexp_f32 v56, 1.0, v56
	v_mul_f32_e32 v58, v57, v58
	v_cndmask_b32_e32 v56, v56, v195, vcc
	v_fmac_f32_e32 v57, v57, v58
	v_add_f32_e32 v58, -1.0, v56
	v_fmac_f32_e32 v58, v56, v57
	v_add_f32_e32 v56, v58, v58
	v_cndmask_b32_e32 v56, v58, v56, vcc
	v_max_f32_e64 v56, -v56, 0
	v_cmp_gt_f32_e32 vcc, s19, v56
	v_mul_f32_e32 v57, 0x4f800000, v56
	s_nop 0
	v_cndmask_b32_e32 v56, v56, v57, vcc
	v_sqrt_f32_e32 v57, v56
	s_nop 0
	v_add_u32_e32 v58, -1, v57
	v_fma_f32 v59, -v58, v57, v56
	v_cmp_ge_f32_e64 s[36:37], 0, v59
	v_add_u32_e32 v59, 1, v57
	s_nop 0
	v_cndmask_b32_e64 v58, v57, v58, s[36:37]
	v_fma_f32 v57, -v59, v57, v56
	v_cmp_lt_f32_e64 s[36:37], 0, v57
	s_nop 1
	v_cndmask_b32_e64 v57, v58, v59, s[36:37]
	v_mul_f32_e32 v58, 0x37800000, v57
	v_cndmask_b32_e32 v57, v57, v58, vcc
	v_cmp_class_f32_e32 vcc, v56, v178
	s_nop 1
	v_cndmask_b32_e32 v56, v57, v56, vcc
	v_cmp_nlt_f32_e32 vcc, s86, v54
	s_nop 1
	v_cndmask_b32_e32 v43, 0, v43, vcc
	v_cmp_nlt_f32_e32 vcc, s86, v55
	s_nop 1
	v_cndmask_b32_e32 v56, 0, v56, vcc
	v_cmp_ngt_f32_e32 vcc, s56, v55
	s_nop 1
	v_cndmask_b32_e32 v55, 1.0, v56, vcc
	v_cmp_ngt_f32_e32 vcc, s56, v54
	s_nop 1
	v_cndmask_b32_e32 v54, 1.0, v43, vcc
	v_pk_mul_f32 v[46:47], v[46:47], v[54:55]
	v_mul_f32_e32 v43, 0x3fb8aa3b, v53
	v_pk_mul_f32 v[46:47], v[46:47], v[50:51]
	v_exp_f32_e32 v43, v43
	v_cvt_pk_bf16_f32 v49, v46, v47
	global_store_dwordx2 v[80:81], v[48:49], off offset:1184 sc1
	v_lshl_add_u64 v[48:49], s[26:27], 0, v[60:61]
	v_lshl_add_u64 v[62:63], v[48:49], 0, v[68:69]
	global_load_dwordx4 v[118:121], v[62:63], off
	global_load_dwordx4 v[122:125], v[62:63], off offset:64
	v_lshl_add_u64 v[48:49], s[24:25], 0, v[60:61]
	v_lshl_add_u64 v[64:65], v[48:49], 0, v[68:69]
	global_load_dwordx4 v[126:129], v[64:65], off
	global_load_dwordx4 v[130:133], v[64:65], off offset:64
	ds_read_b128 v[48:51], v87
	s_waitcnt vmcnt(3) lgkmcnt(0)
; #define LAS __attribute__((address_space(3)))
; __device__ __forceinline__ unsigned pk2(float lo, float hi) { return pg8::cvt_pk_bf16(lo, hi); }
; __device__ __forceinline__ float sigmoidf_(float x) { return __builtin_amdgcn_rcpf(1.0f + __expf(-x)); }
; template <bool FULL> __device__ __forceinline__ void lru_tile(const Args& a, int l, int tile, LAS unsigned char* lds, int tid, int lane, int wave) {
;     ...
;         for (int et = 0; et < 8; ++et) {
;             const int e0 = chh * 128 + et * 16, nb = e0 >> 6, el = e0 & 63;
;             f32x4 ra = {0.f, 0.f, 0.f, 0.f}, ia = {0.f, 0.f, 0.f, 0.f};
; #pragma unroll
;             for (int ks = 0; ks < 2; ++ks) {
;                 const bf16x8 xv = *(const LAS bf16x8*)(lds + OFF_XC + ((cb * 16 + fr) * 264 + nb * 64 + 32 * ks + 8 * fq) * 2);
;                 const bf16x8 wa = *(const bf16x8*)(WA + (size_t)nb * 4096 + (el + fr) * 64 + 32 * ks + 8 * fq);
;                 const bf16x8 wx = *(const bf16x8*)(WX + (size_t)nb * 4096 + (el + fr) * 64 + 32 * ks + 8 * fq);
;                 MFMA16(wa, xv, ra); MFMA16(wx, xv, ia);
;             }
;             const int c0 = e0 + 4 * fq;
;             const f32x4 ba = *(const f32x4*)(a.in[22] + (size_t)l * 256 + c0), bx = *(const f32x4*)(a.in[24] + (size_t)l * 256 + c0), c8v = *(const f32x4*)(c8t + c0);
;             const u32x2 xr = *(const LAS u32x2*)(lds + OFF_XC + ((cb * 16 + fr) * 264 + c0) * 2);
;             float lav[4];
;             const float xcv[4] = {__uint_as_float(xr.x << 16), __uint_as_float(xr.x & 0xffff0000u), __uint_as_float(xr.y << 16), __uint_as_float(xr.y & 0xffff0000u)};
; #pragma unroll
;             for (int r = 0; r < 4; ++r) {
;                 const float rg = sigmoidf_(ra[r] + ba[r]), ig = sigmoidf_(ia[r] + bx[r]);
;                 const float la = c8v[r] * rg; const float av_ = __expf(la); const float m2 = -expm1f(2.0f * la);
;                 av[et][r] = av_; bv[et][r] = sqrtf(fmaxf(m2, 0.f)) * ig * xcv[r]; lav[r] = la;
;             }
;             {
;               bf16* yr = Y + (size_t)(t0 + cb * 16 + fr) * DM + c0;
;               u32x2 wl_; wl_.x = pk2(lav[0], lav[1]); wl_.y = pk2(lav[2], lav[3]); *(u32x2*)(yr + 768) = wl_;
;               u32x2 wb_; wb_.x = pk2(bv[et][0], bv[et][1]); wb_.y = pk2(bv[et][2], bv[et][3]); *(u32x2*)(yr + 512) = wb_; }
;             if ((et & 3) == 3) asm volatile("" ::: "memory");
;         }
	v_mfma_f32_16x16x32_bf16 v[52:55], v[118:121], v[48:51], 0
	s_ashr_i32 s24, s5, 6
	s_ashr_i32 s25, s24, 31
	s_lshl_b64 s[24:25], s[24:25], 13
	s_waitcnt vmcnt(1)
	v_mfma_f32_16x16x32_bf16 v[48:51], v[126:129], v[48:51], 0
	ds_read_b128 v[56:59], v87 offset:64
	s_nop 0
	s_add_u32 s26, s57, s24
	s_waitcnt vmcnt(1) lgkmcnt(0)
	v_mfma_f32_16x16x32_bf16 v[60:63], v[122:125], v[56:59], v[52:55]
	s_addc_u32 s27, s58, s25
	s_add_u32 s24, s59, s24
	s_addc_u32 s25, s60, s25
	s_waitcnt vmcnt(0)
	v_mfma_f32_16x16x32_bf16 v[52:55], v[130:133], v[56:59], v[48:51]
	global_load_dwordx4 v[64:67], v[72:73], off offset:384
	global_load_dwordx4 v[56:59], v[84:85], off offset:384
	s_nop 0
	global_load_dwordx4 v[48:51], v[82:83], off offset:384
	ds_read_b64 v[74:75], v74
	s_lshl_b32 s1, s1, 14
	s_lshl_b32 s4, s4, 9
	s_add_i32 s1, s1, s4
	s_waitcnt vmcnt(2)
	v_add_f32_e32 v60, v60, v64
	s_waitcnt vmcnt(1)
	v_add_f32_e32 v52, v52, v56
	v_add_f32_e32 v56, v61, v65
	v_mul_f32_e32 v60, 0xbfb8aa3b, v60
	v_mul_f32_e32 v56, 0xbfb8aa3b, v56
	v_exp_f32_e32 v60, v60
	v_exp_f32_e32 v56, v56
	v_add_f32_e32 v53, v53, v57
	s_waitcnt lgkmcnt(0)
	v_lshlrev_b32_e32 v64, 16, v74
	v_add_f32_e32 v60, 1.0, v60
	v_add_f32_e32 v56, 1.0, v56
	v_rcp_f32_e32 v60, v60
	v_rcp_f32_e32 v61, v56
	v_and_b32_e32 v65, 0xffff0000, v74
	v_mul_f32_e32 v52, 0xbfb8aa3b, v52
	v_mul_f32_e32 v53, 0xbfb8aa3b, v53
	s_waitcnt vmcnt(0)
	v_pk_mul_f32 v[56:57], v[48:49], v[60:61]
	v_exp_f32_e32 v52, v52
	v_pk_add_f32 v[60:61], v[56:57], v[56:57]
	v_exp_f32_e32 v53, v53
	v_mul_f32_e32 v49, 0x3fb8aa3b, v60
	v_rndne_f32_e32 v49, v49
	v_fmamk_f32 v74, v49, 0xbf317218, v60
	v_fmac_f32_e32 v74, 0x3102e308, v49
	v_fmamk_f32 v88, v74, 0x395133b1, v177
	v_cmp_eq_f32_e32 vcc, s2, v49
	v_cvt_i32_f32_e32 v49, v49
	v_fmaak_f32 v88, v74, v88, 0x3c0887f9
	v_fmaak_f32 v88, v74, v88, 0x3d2aaa81
	v_fmaak_f32 v88, v74, v88, 0x3e2aaaab
	v_fma_f32 v88, v74, v88, 0.5
	v_ldexp_f32 v49, 1.0, v49
	v_mul_f32_e32 v88, v74, v88
	v_cndmask_b32_e32 v49, v49, v195, vcc
	v_fmac_f32_e32 v74, v74, v88
	v_add_f32_e32 v88, -1.0, v49
	v_fmac_f32_e32 v88, v49, v74
	v_add_f32_e32 v49, v88, v88
	v_cndmask_b32_e32 v49, v88, v49, vcc
	v_max_f32_e64 v49, -v49, 0
	v_cmp_gt_f32_e32 vcc, s19, v49
	v_mul_f32_e32 v74, 0x4f800000, v49
	v_add_f32_e32 v52, 1.0, v52
	v_cndmask_b32_e32 v49, v49, v74, vcc
	v_sqrt_f32_e32 v74, v49
	v_add_f32_e32 v53, 1.0, v53
	v_rcp_f32_e32 v52, v52
	v_rcp_f32_e32 v53, v53
	v_add_u32_e32 v88, -1, v74
	v_fma_f32 v89, -v88, v74, v49
	v_cmp_ge_f32_e64 s[36:37], 0, v89
	v_add_u32_e32 v89, 1, v74
	v_add_f32_e32 v54, v54, v58
	v_cndmask_b32_e64 v88, v74, v88, s[36:37]
	v_fma_f32 v74, -v89, v74, v49
	v_cmp_lt_f32_e64 s[36:37], 0, v74
	v_add_f32_e32 v58, v63, v67
	v_mul_f32_e32 v58, 0xbfb8aa3b, v58
	v_cndmask_b32_e64 v74, v88, v89, s[36:37]
	v_mul_f32_e32 v88, 0x37800000, v74
	v_cndmask_b32_e32 v74, v74, v88, vcc
	v_cmp_class_f32_e32 vcc, v49, v178
	v_exp_f32_e32 v58, v58
	v_add_f32_e32 v55, v55, v59
	v_cndmask_b32_e32 v49, v74, v49, vcc
	v_mul_f32_e32 v74, 0x3fb8aa3b, v61
	v_rndne_f32_e32 v74, v74
	v_fmamk_f32 v88, v74, 0xbf317218, v61
	v_fmac_f32_e32 v88, 0x3102e308, v74
	v_fmamk_f32 v89, v88, 0x395133b1, v177
	v_cmp_eq_f32_e32 vcc, s2, v74
	v_cvt_i32_f32_e32 v74, v74
	v_fmaak_f32 v89, v88, v89, 0x3c0887f9
	v_fmaak_f32 v89, v88, v89, 0x3d2aaa81
	v_fmaak_f32 v89, v88, v89, 0x3e2aaaab
	v_fma_f32 v89, v88, v89, 0.5
	v_ldexp_f32 v74, 1.0, v74
	v_mul_f32_e32 v89, v88, v89
	v_cndmask_b32_e32 v74, v74, v195, vcc
	v_fmac_f32_e32 v88, v88, v89
	v_add_f32_e32 v89, -1.0, v74
	v_fmac_f32_e32 v89, v74, v88
	v_add_f32_e32 v74, v89, v89
	v_cndmask_b32_e32 v74, v89, v74, vcc
	v_max_f32_e64 v74, -v74, 0
	v_cmp_gt_f32_e32 vcc, s19, v74
	v_mul_f32_e32 v88, 0x4f800000, v74
	v_add_f32_e32 v58, 1.0, v58
	v_cndmask_b32_e32 v74, v74, v88, vcc
	v_sqrt_f32_e32 v88, v74
	v_mul_f32_e32 v54, 0xbfb8aa3b, v54
	v_mul_f32_e32 v55, 0xbfb8aa3b, v55
	v_exp_f32_e32 v54, v54
	v_add_u32_e32 v89, -1, v88
	v_fma_f32 v90, -v89, v88, v74
	v_cmp_ge_f32_e64 s[36:37], 0, v90
	v_add_u32_e32 v90, 1, v88
	v_exp_f32_e32 v55, v55
	v_cndmask_b32_e64 v89, v88, v89, s[36:37]
	v_fma_f32 v88, -v90, v88, v74
	v_cmp_lt_f32_e64 s[36:37], 0, v88
	v_add_f32_e32 v54, 1.0, v54
	v_add_f32_e32 v55, 1.0, v55
	v_cndmask_b32_e64 v88, v89, v90, s[36:37]
	v_mul_f32_e32 v89, 0x37800000, v88
	v_cndmask_b32_e32 v88, v88, v89, vcc
	v_cmp_class_f32_e32 vcc, v74, v178
	v_rcp_f32_e32 v54, v54
	v_rcp_f32_e32 v55, v55
	v_cndmask_b32_e32 v74, v88, v74, vcc
	v_cmp_nlt_f32_e32 vcc, s86, v60
	v_mul_f32_e32 v48, 0x3fb8aa3b, v56
	v_and_b32_e32 v59, 0xffff0000, v75
	v_cndmask_b32_e32 v49, 0, v49, vcc
	v_cmp_nlt_f32_e32 vcc, s86, v61
	v_cvt_pk_bf16_f32 v56, v56, v57
	v_exp_f32_e32 v48, v48
	s_nop 0
	v_cndmask_b32_e32 v74, 0, v74, vcc
	v_cmp_ngt_f32_e32 vcc, s56, v61
	s_nop 1
	v_cndmask_b32_e32 v61, 1.0, v74, vcc
	v_cmp_ngt_f32_e32 vcc, s56, v60
	s_nop 1
	v_cndmask_b32_e32 v60, 1.0, v49, vcc
	v_pk_mul_f32 v[52:53], v[52:53], v[60:61]
	v_add_f32_e32 v60, v62, v66
	v_mul_f32_e32 v60, 0xbfb8aa3b, v60
	v_exp_f32_e32 v60, v60
	v_rcp_f32_e32 v61, v58
	v_pk_mul_f32 v[52:53], v[52:53], v[64:65]
	v_mul_f32_e32 v49, 0x3fb8aa3b, v57
	v_add_f32_e32 v60, 1.0, v60
	v_rcp_f32_e32 v60, v60
	v_lshlrev_b32_e32 v58, 16, v75
	v_exp_f32_e32 v49, v49
	v_pk_mul_f32 v[60:61], v[50:51], v[60:61]
	s_nop 0
	v_pk_add_f32 v[62:63], v[60:61], v[60:61]
	v_cvt_pk_bf16_f32 v57, v60, v61
	global_store_dwordx2 v[80:81], v[56:57], off offset:1728 sc1
	v_mul_f32_e32 v51, 0x3fb8aa3b, v62
	v_rndne_f32_e32 v51, v51
	v_fmamk_f32 v64, v51, 0xbf317218, v62
	v_fmac_f32_e32 v64, 0x3102e308, v51
	v_fmamk_f32 v65, v64, 0x395133b1, v177
	v_cmp_eq_f32_e32 vcc, s2, v51
; #define LAS __attribute__((address_space(3)))
; __device__ __forceinline__ unsigned pk2(float lo, float hi) { return pg8::cvt_pk_bf16(lo, hi); }
; __device__ __forceinline__ float sigmoidf_(float x) { return __builtin_amdgcn_rcpf(1.0f + __expf(-x)); }
; template <bool FULL> __device__ __forceinline__ void lru_tile(const Args& a, int l, int tile, LAS unsigned char* lds, int tid, int lane, int wave) {
;     ...
;         for (int et = 0; et < 8; ++et) {
;             const int e0 = chh * 128 + et * 16, nb = e0 >> 6, el = e0 & 63;
;             f32x4 ra = {0.f, 0.f, 0.f, 0.f}, ia = {0.f, 0.f, 0.f, 0.f};
; #pragma unroll
;             for (int ks = 0; ks < 2; ++ks) {
;                 const bf16x8 xv = *(const LAS bf16x8*)(lds + OFF_XC + ((cb * 16 + fr) * 264 + nb * 64 + 32 * ks + 8 * fq) * 2);
;                 const bf16x8 wa = *(const bf16x8*)(WA + (size_t)nb * 4096 + (el + fr) * 64 + 32 * ks + 8 * fq);
;                 const bf16x8 wx = *(const bf16x8*)(WX + (size_t)nb * 4096 + (el + fr) * 64 + 32 * ks + 8 * fq);
;                 MFMA16(wa, xv, ra); MFMA16(wx, xv, ia);
;             }
;             const int c0 = e0 + 4 * fq;
;             const f32x4 ba = *(const f32x4*)(a.in[22] + (size_t)l * 256 + c0), bx = *(const f32x4*)(a.in[24] + (size_t)l * 256 + c0), c8v = *(const f32x4*)(c8t + c0);
;             const u32x2 xr = *(const LAS u32x2*)(lds + OFF_XC + ((cb * 16 + fr) * 264 + c0) * 2);
;             float lav[4];
;             const float xcv[4] = {__uint_as_float(xr.x << 16), __uint_as_float(xr.x & 0xffff0000u), __uint_as_float(xr.y << 16), __uint_as_float(xr.y & 0xffff0000u)};
; #pragma unroll
;             for (int r = 0; r < 4; ++r) {
;                 const float rg = sigmoidf_(ra[r] + ba[r]), ig = sigmoidf_(ia[r] + bx[r]);
;                 const float la = c8v[r] * rg; const float av_ = __expf(la); const float m2 = -expm1f(2.0f * la);
;                 av[et][r] = av_; bv[et][r] = sqrtf(fmaxf(m2, 0.f)) * ig * xcv[r]; lav[r] = la;
;             }
;             {
;               bf16* yr = Y + (size_t)(t0 + cb * 16 + fr) * DM + c0;
;               u32x2 wl_; wl_.x = pk2(lav[0], lav[1]); wl_.y = pk2(lav[2], lav[3]); *(u32x2*)(yr + 768) = wl_;
;               u32x2 wb_; wb_.x = pk2(bv[et][0], bv[et][1]); wb_.y = pk2(bv[et][2], bv[et][3]); *(u32x2*)(yr + 512) = wb_; }
;             if ((et & 3) == 3) asm volatile("" ::: "memory");
;         }
	v_cvt_i32_f32_e32 v51, v51
	v_fmaak_f32 v65, v64, v65, 0x3c0887f9
	v_fmaak_f32 v65, v64, v65, 0x3d2aaa81
	v_fmaak_f32 v65, v64, v65, 0x3e2aaaab
	v_fma_f32 v65, v64, v65, 0.5
	v_ldexp_f32 v51, 1.0, v51
	v_mul_f32_e32 v65, v64, v65
	v_cndmask_b32_e32 v51, v51, v195, vcc
	v_fmac_f32_e32 v64, v64, v65
	v_add_f32_e32 v65, -1.0, v51
	v_fmac_f32_e32 v65, v51, v64
	v_add_f32_e32 v51, v65, v65
	v_cndmask_b32_e32 v51, v65, v51, vcc
	v_max_f32_e64 v51, -v51, 0
	v_cmp_gt_f32_e32 vcc, s19, v51
	v_mul_f32_e32 v64, 0x4f800000, v51
	v_cvt_pk_bf16_f32 v56, v52, v53
	v_mul_f32_e32 v50, 0x3fb8aa3b, v60
	v_cndmask_b32_e32 v51, v51, v64, vcc
	v_sqrt_f32_e32 v64, v51
	v_exp_f32_e32 v50, v50
	v_add_u32_e32 v65, -1, v64
	v_fma_f32 v66, -v65, v64, v51
	v_cmp_ge_f32_e64 s[36:37], 0, v66
	v_add_u32_e32 v66, 1, v64
	s_nop 0
	v_cndmask_b32_e64 v65, v64, v65, s[36:37]
	v_fma_f32 v64, -v66, v64, v51
	v_cmp_lt_f32_e64 s[36:37], 0, v64
	s_nop 1
	v_cndmask_b32_e64 v64, v65, v66, s[36:37]
	v_mul_f32_e32 v65, 0x37800000, v64
	v_cndmask_b32_e32 v64, v64, v65, vcc
	v_cmp_class_f32_e32 vcc, v51, v178
	s_nop 1
	v_cndmask_b32_e32 v51, v64, v51, vcc
	v_mul_f32_e32 v64, 0x3fb8aa3b, v63
	v_rndne_f32_e32 v64, v64
	v_fmamk_f32 v65, v64, 0xbf317218, v63
	v_fmac_f32_e32 v65, 0x3102e308, v64
	v_fmamk_f32 v66, v65, 0x395133b1, v177
	v_cmp_eq_f32_e32 vcc, s2, v64
	v_cvt_i32_f32_e32 v64, v64
	v_fmaak_f32 v66, v65, v66, 0x3c0887f9
	v_fmaak_f32 v66, v65, v66, 0x3d2aaa81
	v_fmaak_f32 v66, v65, v66, 0x3e2aaaab
	v_fma_f32 v66, v65, v66, 0.5
	v_ldexp_f32 v64, 1.0, v64
	v_mul_f32_e32 v66, v65, v66
	v_cndmask_b32_e32 v64, v64, v195, vcc
	v_fmac_f32_e32 v65, v65, v66
	v_add_f32_e32 v66, -1.0, v64
	v_fmac_f32_e32 v66, v64, v65
	v_add_f32_e32 v64, v66, v66
	v_cndmask_b32_e32 v64, v66, v64, vcc
	v_max_f32_e64 v64, -v64, 0
	v_cmp_gt_f32_e32 vcc, s19, v64
	v_mul_f32_e32 v65, 0x4f800000, v64
	s_nop 0
	v_cndmask_b32_e32 v64, v64, v65, vcc
	v_sqrt_f32_e32 v65, v64
	s_nop 0
	v_add_u32_e32 v66, -1, v65
	v_fma_f32 v67, -v66, v65, v64
	v_cmp_ge_f32_e64 s[36:37], 0, v67
	v_add_u32_e32 v67, 1, v65
	s_nop 0
	v_cndmask_b32_e64 v66, v65, v66, s[36:37]
	v_fma_f32 v65, -v67, v65, v64
	v_cmp_lt_f32_e64 s[36:37], 0, v65
	s_nop 1
	v_cndmask_b32_e64 v65, v66, v67, s[36:37]
	v_mul_f32_e32 v66, 0x37800000, v65
	v_cndmask_b32_e32 v65, v65, v66, vcc
	v_cmp_class_f32_e32 vcc, v64, v178
	s_nop 1
	v_cndmask_b32_e32 v64, v65, v64, vcc
	v_cmp_nlt_f32_e32 vcc, s86, v62
	s_nop 1
	v_cndmask_b32_e32 v51, 0, v51, vcc
	v_cmp_nlt_f32_e32 vcc, s86, v63
	s_nop 1
	v_cndmask_b32_e32 v64, 0, v64, vcc
	v_cmp_ngt_f32_e32 vcc, s56, v63
	s_nop 1
	v_cndmask_b32_e32 v63, 1.0, v64, vcc
	v_cmp_ngt_f32_e32 vcc, s56, v62
	s_nop 1
	v_cndmask_b32_e32 v62, 1.0, v51, vcc
	v_pk_mul_f32 v[54:55], v[54:55], v[62:63]
	v_mul_f32_e32 v51, 0x3fb8aa3b, v61
	v_pk_mul_f32 v[54:55], v[54:55], v[58:59]
	v_exp_f32_e32 v51, v51
	v_cvt_pk_bf16_f32 v57, v54, v55
	global_store_dwordx2 v[80:81], v[56:57], off offset:1216 sc1
	v_lshl_add_u64 v[56:57], s[26:27], 0, v[70:71]
	v_lshl_add_u64 v[74:75], v[56:57], 0, v[68:69]
	global_load_dwordx4 v[118:121], v[74:75], off
	global_load_dwordx4 v[122:125], v[74:75], off offset:64
	v_lshl_add_u64 v[56:57], s[24:25], 0, v[70:71]
	v_lshl_add_u64 v[88:89], v[56:57], 0, v[68:69]
	global_load_dwordx4 v[126:129], v[88:89], off
	ds_read_b128 v[56:59], v87
	global_load_dwordx4 v[88:91], v[88:89], off offset:64
	s_waitcnt vmcnt(3) lgkmcnt(0)
	v_mfma_f32_16x16x32_bf16 v[60:63], v[118:121], v[56:59], 0
	s_waitcnt vmcnt(1)
	v_mfma_f32_16x16x32_bf16 v[56:59], v[126:129], v[56:59], 0
	ds_read_b128 v[64:67], v87 offset:64
	global_load_dwordx4 v[72:75], v[72:73], off offset:448
	s_nop 0
	s_waitcnt vmcnt(2) lgkmcnt(0)
	v_mfma_f32_16x16x32_bf16 v[60:63], v[122:125], v[64:67], v[60:63]
	s_waitcnt vmcnt(1)
	v_mfma_f32_16x16x32_bf16 v[56:59], v[88:91], v[64:67], v[56:59]
	s_nop 0
	global_load_dwordx4 v[64:67], v[84:85], off offset:448
	global_load_dwordx4 v[68:71], v[82:83], off offset:448
	ds_read_b64 v[82:83], v79
	s_waitcnt lgkmcnt(0)
	v_lshlrev_b32_e32 v84, 16, v82
	v_and_b32_e32 v85, 0xffff0000, v82
	s_waitcnt vmcnt(2)
	v_add_f32_e32 v60, v60, v72
	s_waitcnt vmcnt(1)
	v_add_f32_e32 v56, v56, v64
	v_mul_f32_e32 v60, 0xbfb8aa3b, v60
	v_mul_f32_e32 v56, 0xbfb8aa3b, v56
	v_exp_f32_e32 v60, v60
	v_exp_f32_e32 v56, v56
	v_add_f32_e32 v62, v62, v74
	v_add_f32_e32 v58, v58, v66
	v_add_f32_e32 v60, 1.0, v60
	v_add_f32_e32 v56, 1.0, v56
	v_rcp_f32_e32 v72, v60
	v_rcp_f32_e32 v60, v56
	v_add_f32_e32 v56, v61, v73
	v_mul_f32_e32 v56, 0xbfb8aa3b, v56
	v_exp_f32_e32 v56, v56
	v_mul_f32_e32 v62, 0xbfb8aa3b, v62
	v_mul_f32_e32 v58, 0xbfb8aa3b, v58
	v_exp_f32_e32 v62, v62
	v_add_f32_e32 v56, 1.0, v56
	v_rcp_f32_e32 v73, v56
	v_add_f32_e32 v56, v57, v65
	v_mul_f32_e32 v56, 0xbfb8aa3b, v56
	v_exp_f32_e32 v56, v56
	s_waitcnt vmcnt(0)
; #define LAS __attribute__((address_space(3)))
; __device__ __forceinline__ unsigned pk2(float lo, float hi) { return pg8::cvt_pk_bf16(lo, hi); }
; __device__ __forceinline__ float sigmoidf_(float x) { return __builtin_amdgcn_rcpf(1.0f + __expf(-x)); }
; template <bool FULL> __device__ __forceinline__ void lru_tile(const Args& a, int l, int tile, LAS unsigned char* lds, int tid, int lane, int wave) {
;     ...
;         for (int et = 0; et < 8; ++et) {
;             const int e0 = chh * 128 + et * 16, nb = e0 >> 6, el = e0 & 63;
;             f32x4 ra = {0.f, 0.f, 0.f, 0.f}, ia = {0.f, 0.f, 0.f, 0.f};
; #pragma unroll
;             for (int ks = 0; ks < 2; ++ks) {
;                 const bf16x8 xv = *(const LAS bf16x8*)(lds + OFF_XC + ((cb * 16 + fr) * 264 + nb * 64 + 32 * ks + 8 * fq) * 2);
;                 const bf16x8 wa = *(const bf16x8*)(WA + (size_t)nb * 4096 + (el + fr) * 64 + 32 * ks + 8 * fq);
;                 const bf16x8 wx = *(const bf16x8*)(WX + (size_t)nb * 4096 + (el + fr) * 64 + 32 * ks + 8 * fq);
;                 MFMA16(wa, xv, ra); MFMA16(wx, xv, ia);
;             }
;             const int c0 = e0 + 4 * fq;
;             const f32x4 ba = *(const f32x4*)(a.in[22] + (size_t)l * 256 + c0), bx = *(const f32x4*)(a.in[24] + (size_t)l * 256 + c0), c8v = *(const f32x4*)(c8t + c0);
;             const u32x2 xr = *(const LAS u32x2*)(lds + OFF_XC + ((cb * 16 + fr) * 264 + c0) * 2);
;             float lav[4];
;             const float xcv[4] = {__uint_as_float(xr.x << 16), __uint_as_float(xr.x & 0xffff0000u), __uint_as_float(xr.y << 16), __uint_as_float(xr.y & 0xffff0000u)};
; #pragma unroll
;             for (int r = 0; r < 4; ++r) {
;                 const float rg = sigmoidf_(ra[r] + ba[r]), ig = sigmoidf_(ia[r] + bx[r]);
;                 const float la = c8v[r] * rg; const float av_ = __expf(la); const float m2 = -expm1f(2.0f * la);
;                 av[et][r] = av_; bv[et][r] = sqrtf(fmaxf(m2, 0.f)) * ig * xcv[r]; lav[r] = la;
;             }
;             {
;               bf16* yr = Y + (size_t)(t0 + cb * 16 + fr) * DM + c0;
;               u32x2 wl_; wl_.x = pk2(lav[0], lav[1]); wl_.y = pk2(lav[2], lav[3]); *(u32x2*)(yr + 768) = wl_;
;               u32x2 wb_; wb_.x = pk2(bv[et][0], bv[et][1]); wb_.y = pk2(bv[et][2], bv[et][3]); *(u32x2*)(yr + 512) = wb_; }
;             if ((et & 3) == 3) asm volatile("" ::: "memory");
;         }
	v_pk_mul_f32 v[64:65], v[68:69], v[72:73]
	v_exp_f32_e32 v58, v58
	v_pk_add_f32 v[68:69], v[64:65], v[64:65]
	v_add_f32_e32 v56, 1.0, v56
	v_mul_f32_e32 v57, 0x3fb8aa3b, v68
	v_rndne_f32_e32 v57, v57
	v_fmamk_f32 v72, v57, 0xbf317218, v68
	v_fmac_f32_e32 v72, 0x3102e308, v57
	v_fmamk_f32 v73, v72, 0x395133b1, v177
	v_cmp_eq_f32_e32 vcc, s2, v57
	v_cvt_i32_f32_e32 v57, v57
	v_fmaak_f32 v73, v72, v73, 0x3c0887f9
	v_fmaak_f32 v73, v72, v73, 0x3d2aaa81
	v_fmaak_f32 v73, v72, v73, 0x3e2aaaab
	v_fma_f32 v73, v72, v73, 0.5
	v_ldexp_f32 v57, 1.0, v57
	v_mul_f32_e32 v73, v72, v73
	v_cndmask_b32_e32 v57, v57, v195, vcc
	v_fmac_f32_e32 v72, v72, v73
	v_add_f32_e32 v73, -1.0, v57
	v_fmac_f32_e32 v73, v57, v72
	v_add_f32_e32 v57, v73, v73
	v_cndmask_b32_e32 v57, v73, v57, vcc
	v_max_f32_e64 v57, -v57, 0
	v_cmp_gt_f32_e32 vcc, s19, v57
	v_mul_f32_e32 v72, 0x4f800000, v57
	v_rcp_f32_e32 v61, v56
	v_cndmask_b32_e32 v57, v57, v72, vcc
	v_sqrt_f32_e32 v72, v57
	v_add_f32_e32 v62, 1.0, v62
	v_add_f32_e32 v58, 1.0, v58
	v_mul_f32_e32 v56, 0x3fb8aa3b, v64
	v_add_u32_e32 v73, -1, v72
	v_fma_f32 v79, -v73, v72, v57
	v_cmp_ge_f32_e64 s[36:37], 0, v79
	v_add_u32_e32 v79, 1, v72
	v_cvt_pk_bf16_f32 v64, v64, v65
	v_lshlrev_b32_e32 v66, 16, v83
	v_cndmask_b32_e64 v73, v72, v73, s[36:37]
	v_fma_f32 v72, -v79, v72, v57
	v_cmp_lt_f32_e64 s[36:37], 0, v72
	v_exp_f32_e32 v56, v56
	s_nop 0
	v_cndmask_b32_e64 v72, v73, v79, s[36:37]
	v_mul_f32_e32 v73, 0x37800000, v72
	v_cndmask_b32_e32 v72, v72, v73, vcc
	v_cmp_class_f32_e32 vcc, v57, v178
	s_nop 1
	v_cndmask_b32_e32 v57, v72, v57, vcc
	v_mul_f32_e32 v72, 0x3fb8aa3b, v69
	v_rndne_f32_e32 v72, v72
	v_fmamk_f32 v73, v72, 0xbf317218, v69
	v_fmac_f32_e32 v73, 0x3102e308, v72
	v_fmamk_f32 v79, v73, 0x395133b1, v177
	v_cmp_eq_f32_e32 vcc, s2, v72
	v_cvt_i32_f32_e32 v72, v72
	v_fmaak_f32 v79, v73, v79, 0x3c0887f9
	v_fmaak_f32 v79, v73, v79, 0x3d2aaa81
	v_fmaak_f32 v79, v73, v79, 0x3e2aaaab
	v_fma_f32 v79, v73, v79, 0.5
	v_ldexp_f32 v72, 1.0, v72
	v_mul_f32_e32 v79, v73, v79
	v_cndmask_b32_e32 v72, v72, v195, vcc
	v_fmac_f32_e32 v73, v73, v79
	v_add_f32_e32 v79, -1.0, v72
	v_fmac_f32_e32 v79, v72, v73
	v_add_f32_e32 v72, v79, v79
	v_cndmask_b32_e32 v72, v79, v72, vcc
	v_max_f32_e64 v72, -v72, 0
	v_cmp_gt_f32_e32 vcc, s19, v72
	v_mul_f32_e32 v73, 0x4f800000, v72
	s_nop 0
	v_cndmask_b32_e32 v72, v72, v73, vcc
	v_sqrt_f32_e32 v73, v72
	s_nop 0
	v_add_u32_e32 v79, -1, v73
	v_fma_f32 v82, -v79, v73, v72
	v_cmp_ge_f32_e64 s[36:37], 0, v82
	v_add_u32_e32 v82, 1, v73
	s_nop 0
	v_cndmask_b32_e64 v79, v73, v79, s[36:37]
	v_fma_f32 v73, -v82, v73, v72
	v_cmp_lt_f32_e64 s[36:37], 0, v73
	s_nop 1
	v_cndmask_b32_e64 v73, v79, v82, s[36:37]
	v_mul_f32_e32 v79, 0x37800000, v73
	v_cndmask_b32_e32 v73, v73, v79, vcc
	v_cmp_class_f32_e32 vcc, v72, v178
	s_nop 1
	v_cndmask_b32_e32 v72, v73, v72, vcc
	v_cmp_nlt_f32_e32 vcc, s86, v68
	s_nop 1
	v_cndmask_b32_e32 v57, 0, v57, vcc
	v_cmp_nlt_f32_e32 vcc, s86, v69
	s_nop 1
	v_cndmask_b32_e32 v72, 0, v72, vcc
	v_cmp_ngt_f32_e32 vcc, s56, v69
	s_nop 1
	v_cndmask_b32_e32 v69, 1.0, v72, vcc
	v_cmp_ngt_f32_e32 vcc, s56, v68
	s_nop 1
	v_cndmask_b32_e32 v68, 1.0, v57, vcc
	v_pk_mul_f32 v[60:61], v[60:61], v[68:69]
	v_rcp_f32_e32 v68, v62
	v_rcp_f32_e32 v62, v58
	v_add_f32_e32 v58, v63, v75
	v_mul_f32_e32 v58, 0xbfb8aa3b, v58
	v_exp_f32_e32 v58, v58
	v_pk_mul_f32 v[60:61], v[60:61], v[84:85]
	v_mul_f32_e32 v57, 0x3fb8aa3b, v65
	v_exp_f32_e32 v57, v57
	v_add_f32_e32 v58, 1.0, v58
	v_rcp_f32_e32 v69, v58
	v_add_f32_e32 v58, v59, v67
	v_mul_f32_e32 v58, 0xbfb8aa3b, v58
	v_exp_f32_e32 v58, v58
	v_pk_mul_f32 v[68:69], v[70:71], v[68:69]
	v_and_b32_e32 v67, 0xffff0000, v83
	v_pk_add_f32 v[70:71], v[68:69], v[68:69]
	v_add_f32_e32 v58, 1.0, v58
	v_mul_f32_e32 v59, 0x3fb8aa3b, v70
	v_rndne_f32_e32 v59, v59
	v_fmamk_f32 v72, v59, 0xbf317218, v70
	v_fmac_f32_e32 v72, 0x3102e308, v59
	v_fmamk_f32 v73, v72, 0x395133b1, v177
	v_cmp_eq_f32_e32 vcc, s2, v59
	v_cvt_i32_f32_e32 v59, v59
	v_fmaak_f32 v73, v72, v73, 0x3c0887f9
	v_fmaak_f32 v73, v72, v73, 0x3d2aaa81
	v_fmaak_f32 v73, v72, v73, 0x3e2aaaab
	v_fma_f32 v73, v72, v73, 0.5
	v_ldexp_f32 v59, 1.0, v59
	v_mul_f32_e32 v73, v72, v73
	v_cndmask_b32_e32 v59, v59, v195, vcc
	v_fmac_f32_e32 v72, v72, v73
	v_add_f32_e32 v73, -1.0, v59
	v_fmac_f32_e32 v73, v59, v72
	v_add_f32_e32 v59, v73, v73
	v_cndmask_b32_e32 v59, v73, v59, vcc
	v_max_f32_e64 v59, -v59, 0
	v_cmp_gt_f32_e32 vcc, s19, v59
	v_mul_f32_e32 v72, 0x4f800000, v59
	v_rcp_f32_e32 v63, v58
	v_cndmask_b32_e32 v59, v59, v72, vcc
	v_sqrt_f32_e32 v72, v59
	v_cvt_pk_bf16_f32 v65, v68, v69
	global_store_dwordx2 v[80:81], v[64:65], off offset:1760 sc1
	v_cvt_pk_bf16_f32 v64, v60, v61
	v_add_u32_e32 v73, -1, v72
	v_fma_f32 v74, -v73, v72, v59
	v_cmp_ge_f32_e64 s[36:37], 0, v74
	v_add_u32_e32 v74, 1, v72
	v_mul_f32_e32 v58, 0x3fb8aa3b, v68
	v_cndmask_b32_e64 v73, v72, v73, s[36:37]
	v_fma_f32 v72, -v74, v72, v59
	v_cmp_lt_f32_e64 s[36:37], 0, v72
	v_exp_f32_e32 v58, v58
	s_nop 0
	v_cndmask_b32_e64 v72, v73, v74, s[36:37]
	v_mul_f32_e32 v73, 0x37800000, v72
	v_cndmask_b32_e32 v72, v72, v73, vcc
	v_cmp_class_f32_e32 vcc, v59, v178
	s_nop 1
	v_cndmask_b32_e32 v59, v72, v59, vcc
	v_mul_f32_e32 v72, 0x3fb8aa3b, v71
	v_rndne_f32_e32 v72, v72
	v_fmamk_f32 v73, v72, 0xbf317218, v71
	v_fmac_f32_e32 v73, 0x3102e308, v72
	v_fmamk_f32 v74, v73, 0x395133b1, v177
	v_cmp_eq_f32_e32 vcc, s2, v72
	v_cvt_i32_f32_e32 v72, v72
	v_fmaak_f32 v74, v73, v74, 0x3c0887f9
	v_fmaak_f32 v74, v73, v74, 0x3d2aaa81
	v_fmaak_f32 v74, v73, v74, 0x3e2aaaab
	v_fma_f32 v74, v73, v74, 0.5
	v_ldexp_f32 v72, 1.0, v72
	v_mul_f32_e32 v74, v73, v74
	v_cndmask_b32_e32 v72, v72, v195, vcc
; #define LAS __attribute__((address_space(3)))
; __device__ __forceinline__ unsigned pk2(float lo, float hi) { return pg8::cvt_pk_bf16(lo, hi); }
; template <bool FULL> __device__ __forceinline__ void lru_tile(const Args& a, int l, int tile, LAS unsigned char* lds, int tid, int lane, int wave) {
;     ...
;               bf16* yr = Y + (size_t)(t0 + cb * 16 + fr) * DM + c0;
;               u32x2 wl_; wl_.x = pk2(lav[0], lav[1]); wl_.y = pk2(lav[2], lav[3]); *(u32x2*)(yr + 768) = wl_;
;               u32x2 wb_; wb_.x = pk2(bv[et][0], bv[et][1]); wb_.y = pk2(bv[et][2], bv[et][3]); *(u32x2*)(yr + 512) = wb_; }
;             if ((et & 3) == 3) asm volatile("" ::: "memory");
;         }
;         __syncthreads();
; #pragma unroll
;         for (int et = 0; et < 8; ++et) { const int c0 = chh * 128 + et * 16 + 4 * fq, t = cb * 16 + fr;
;             *(LAS f32x4*)(lds + OFF_LA + (t * 256 + c0) * 4) = av[et]; *(LAS f32x4*)(lds + OFF_LB + (t * 256 + c0) * 4) = bv[et]; }
;     }
;     }
;     __syncthreads();
;     float* AE = (float*)(a.ws + WS_LRUC); float* HE = AE + 2 * 128 * 256;
;     if (tid < 256) {
;         LAS float* A = (LAS float*)(lds + OFF_LA) + tid; LAS float* B = (LAS float*)(lds + OFF_LB) + tid;
;         float h = FULL ? HE[(size_t)tile * 256 + tid] : 0.f, P = 1.f;
;         for (int tb = 0; tb < 64; tb += 16) {
;             float av_[16], bv_[16];
; #pragma unroll
;             for (int j = 0; j < 16; ++j) { av_[j] = A[(tb + j) * 256]; bv_[j] = B[(tb + j) * 256]; }
; #pragma unroll
;             for (int j = 0; j < 16; ++j) { h = fmaf(av_[j], h, bv_[j]); if (FULL) bv_[j] = h; else P *= av_[j]; }
	v_fmac_f32_e32 v73, v73, v74
	v_add_f32_e32 v74, -1.0, v72
	v_fmac_f32_e32 v74, v72, v73
	v_add_f32_e32 v72, v74, v74
	v_cndmask_b32_e32 v72, v74, v72, vcc
	v_max_f32_e64 v72, -v72, 0
	v_cmp_gt_f32_e32 vcc, s19, v72
	v_mul_f32_e32 v73, 0x4f800000, v72
	s_nop 0
	v_cndmask_b32_e32 v72, v72, v73, vcc
	v_sqrt_f32_e32 v73, v72
	s_nop 0
	v_add_u32_e32 v74, -1, v73
	v_fma_f32 v75, -v74, v73, v72
	v_cmp_ge_f32_e64 s[36:37], 0, v75
	v_add_u32_e32 v75, 1, v73
	s_nop 0
	v_cndmask_b32_e64 v74, v73, v74, s[36:37]
	v_fma_f32 v73, -v75, v73, v72
	v_cmp_lt_f32_e64 s[36:37], 0, v73
	s_nop 1
	v_cndmask_b32_e64 v73, v74, v75, s[36:37]
	v_mul_f32_e32 v74, 0x37800000, v73
	v_cndmask_b32_e32 v73, v73, v74, vcc
	v_cmp_class_f32_e32 vcc, v72, v178
	s_nop 1
	v_cndmask_b32_e32 v72, v73, v72, vcc
	v_cmp_nlt_f32_e32 vcc, s86, v70
	s_nop 1
	v_cndmask_b32_e32 v59, 0, v59, vcc
	v_cmp_nlt_f32_e32 vcc, s86, v71
	s_nop 1
	v_cndmask_b32_e32 v72, 0, v72, vcc
	v_cmp_ngt_f32_e32 vcc, s56, v71
	s_nop 1
	v_cndmask_b32_e32 v71, 1.0, v72, vcc
	v_cmp_ngt_f32_e32 vcc, s56, v70
	s_nop 1
	v_cndmask_b32_e32 v70, 1.0, v59, vcc
	v_pk_mul_f32 v[62:63], v[62:63], v[70:71]
	v_mul_f32_e32 v59, 0x3fb8aa3b, v69
	v_pk_mul_f32 v[62:63], v[62:63], v[66:67]
	v_exp_f32_e32 v59, v59
	v_cvt_pk_bf16_f32 v65, v62, v63
	global_store_dwordx2 v[80:81], v[64:65], off offset:1248 sc1
	v_lshl_or_b32 v64, v77, 10, v78
	v_add_u32_e32 v64, s1, v64
	v_add_u32_e32 v65, 0, v64
	s_barrier
	ds_write_b128 v65, v[0:3]
	v_add_u32_e32 v0, s0, v64
	s_movk_i32 s0, 0x100
	v_cmp_gt_i32_e32 vcc, s0, v76
	ds_write_b128 v0, v[4:7]
	ds_write_b128 v65, v[8:11] offset:64
	ds_write_b128 v0, v[12:15] offset:64
	ds_write_b128 v65, v[16:19] offset:128
	ds_write_b128 v0, v[20:23] offset:128
	ds_write_b128 v65, v[24:27] offset:192
	ds_write_b128 v0, v[28:31] offset:192
	ds_write_b128 v65, v[32:35] offset:256
	ds_write_b128 v0, v[36:39] offset:256
	ds_write_b128 v65, v[40:43] offset:320
	ds_write_b128 v0, v[44:47] offset:320
	ds_write_b128 v65, v[48:51] offset:384
	ds_write_b128 v0, v[52:55] offset:384
	ds_write_b128 v65, v[56:59] offset:448
	ds_write_b128 v0, v[60:63] offset:448
	s_waitcnt lgkmcnt(0)
	s_barrier
	s_and_saveexec_b64 s[0:1], vcc
	s_cbranch_execz .LBB0_1256
	v_lshl_add_u32 v34, v76, 2, 0
	v_add_u32_e32 v35, 0x10000, v34
	ds_read2st64_b32 v[0:1], v34 offset1:4
	ds_read2st64_b32 v[2:3], v35 offset1:4
	ds_read2st64_b32 v[4:5], v34 offset0:8 offset1:12
	ds_read2st64_b32 v[6:7], v35 offset0:8 offset1:12
	ds_read2st64_b32 v[8:9], v34 offset0:16 offset1:20
	ds_read2st64_b32 v[10:11], v35 offset0:16 offset1:20
	ds_read2st64_b32 v[12:13], v34 offset0:24 offset1:28
	ds_read2st64_b32 v[14:15], v35 offset0:24 offset1:28
	ds_read2st64_b32 v[16:17], v34 offset0:32 offset1:36
	ds_read2st64_b32 v[18:19], v35 offset0:32 offset1:36
	ds_read2st64_b32 v[20:21], v34 offset0:40 offset1:44
	ds_read2st64_b32 v[22:23], v35 offset0:40 offset1:44
	ds_read2st64_b32 v[24:25], v34 offset0:48 offset1:52
	ds_read2st64_b32 v[26:27], v35 offset0:48 offset1:52
	ds_read2st64_b32 v[28:29], v34 offset0:56 offset1:60
	ds_read2st64_b32 v[30:31], v35 offset0:56 offset1:60
	s_waitcnt lgkmcnt(14)
	v_fma_f32 v2, 0, v0, v2
	v_fmac_f32_e32 v3, v1, v2
	v_mul_f32_e32 v0, v0, v1
	s_waitcnt lgkmcnt(12)
	v_fma_f32 v1, v4, v3, v6
	v_mul_f32_e32 v0, v0, v4
	v_fmac_f32_e32 v7, v5, v1
	v_mul_f32_e32 v0, v0, v5
	s_waitcnt lgkmcnt(10)
	v_fma_f32 v1, v8, v7, v10
	v_mul_f32_e32 v0, v0, v8
	v_fmac_f32_e32 v11, v9, v1
	v_mul_f32_e32 v0, v0, v9
	s_waitcnt lgkmcnt(8)
	v_fma_f32 v1, v12, v11, v14
	v_mul_f32_e32 v0, v0, v12
	v_fmac_f32_e32 v15, v13, v1
	v_mul_f32_e32 v0, v0, v13
	s_waitcnt lgkmcnt(6)
	v_fma_f32 v1, v16, v15, v18
	v_mul_f32_e32 v0, v0, v16
	v_fmac_f32_e32 v19, v17, v1
	v_mul_f32_e32 v0, v0, v17
	s_waitcnt lgkmcnt(4)
	v_fma_f32 v1, v20, v19, v22
	v_mul_f32_e32 v0, v0, v20
	v_fmac_f32_e32 v23, v21, v1
	v_mul_f32_e32 v0, v0, v21
	s_waitcnt lgkmcnt(2)
	v_fma_f32 v1, v24, v23, v26
	v_mul_f32_e32 v0, v0, v24
	v_fmac_f32_e32 v27, v25, v1
	v_mul_f32_e32 v0, v0, v25
	s_waitcnt lgkmcnt(0)
	v_fma_f32 v1, v28, v27, v30
	v_mul_f32_e32 v0, v0, v28
	v_fmac_f32_e32 v31, v29, v1
	v_mul_f32_e32 v30, v0, v29
	ds_read2st64_b32 v[0:1], v34 offset0:64 offset1:68
	ds_read2st64_b32 v[2:3], v35 offset0:64 offset1:68
	ds_read2st64_b32 v[4:5], v34 offset0:72 offset1:76
	ds_read2st64_b32 v[6:7], v35 offset0:72 offset1:76
	ds_read2st64_b32 v[8:9], v34 offset0:80 offset1:84
	ds_read2st64_b32 v[10:11], v35 offset0:80 offset1:84
	ds_read2st64_b32 v[12:13], v34 offset0:88 offset1:92
	ds_read2st64_b32 v[14:15], v35 offset0:88 offset1:92
	ds_read2st64_b32 v[16:17], v34 offset0:96 offset1:100
	ds_read2st64_b32 v[18:19], v35 offset0:96 offset1:100
	ds_read2st64_b32 v[20:21], v34 offset0:104 offset1:108
	ds_read2st64_b32 v[22:23], v35 offset0:104 offset1:108
	ds_read2st64_b32 v[24:25], v34 offset0:112 offset1:116
	ds_read2st64_b32 v[26:27], v35 offset0:112 offset1:116
	ds_read2st64_b32 v[28:29], v34 offset0:120 offset1:124
	ds_read2st64_b32 v[32:33], v35 offset0:120 offset1:124
	s_waitcnt lgkmcnt(14)
	v_fma_f32 v2, v0, v31, v2
	v_mul_f32_e32 v0, v30, v0
	v_fmac_f32_e32 v3, v1, v2
	v_mul_f32_e32 v0, v0, v1
	s_waitcnt lgkmcnt(12)
; template <bool FULL> __device__ __forceinline__ void lru_tile(const Args& a, int l, int tile, LAS unsigned char* lds, int tid, int lane, int wave) {
;     ...
;         for (int tb = 0; tb < 64; tb += 16) {
;             float av_[16], bv_[16];
; #pragma unroll
;             for (int j = 0; j < 16; ++j) { av_[j] = A[(tb + j) * 256]; bv_[j] = B[(tb + j) * 256]; }
; #pragma unroll
;             for (int j = 0; j < 16; ++j) { h = fmaf(av_[j], h, bv_[j]); if (FULL) bv_[j] = h; else P *= av_[j]; }
;             if (FULL) {
; #pragma unroll
;                 for (int j = 0; j < 16; ++j) B[(tb + j) * 256] = bv_[j];
;             }
;         }
;         if (!FULL) { AE[(size_t)tile * 256 + tid] = P; HE[(size_t)tile * 256 + tid] = h; }
	v_fma_f32 v1, v4, v3, v6
	v_mul_f32_e32 v0, v0, v4
	v_fmac_f32_e32 v7, v5, v1
	v_mul_f32_e32 v0, v0, v5
	s_waitcnt lgkmcnt(10)
	v_fma_f32 v1, v8, v7, v10
	v_mul_f32_e32 v0, v0, v8
	v_fmac_f32_e32 v11, v9, v1
	v_mul_f32_e32 v0, v0, v9
	s_waitcnt lgkmcnt(8)
	v_fma_f32 v1, v12, v11, v14
	v_mul_f32_e32 v0, v0, v12
	v_fmac_f32_e32 v15, v13, v1
	v_mul_f32_e32 v0, v0, v13
	s_waitcnt lgkmcnt(6)
	v_fma_f32 v1, v16, v15, v18
	v_mul_f32_e32 v0, v0, v16
	v_fmac_f32_e32 v19, v17, v1
	v_mul_f32_e32 v0, v0, v17
	s_waitcnt lgkmcnt(4)
	v_fma_f32 v1, v20, v19, v22
	v_mul_f32_e32 v0, v0, v20
	v_fmac_f32_e32 v23, v21, v1
	v_mul_f32_e32 v0, v0, v21
	s_waitcnt lgkmcnt(2)
	v_fma_f32 v1, v24, v23, v26
	v_mul_f32_e32 v0, v0, v24
	v_fmac_f32_e32 v27, v25, v1
	v_mul_f32_e32 v0, v0, v25
	s_waitcnt lgkmcnt(0)
	v_fma_f32 v1, v28, v27, v32
	v_mul_f32_e32 v0, v0, v28
	v_fmac_f32_e32 v33, v29, v1
	v_mul_f32_e32 v32, v0, v29
	ds_read2st64_b32 v[0:1], v34 offset0:128 offset1:132
	ds_read2st64_b32 v[2:3], v35 offset0:128 offset1:132
	ds_read2st64_b32 v[4:5], v34 offset0:136 offset1:140
	ds_read2st64_b32 v[6:7], v35 offset0:136 offset1:140
	ds_read2st64_b32 v[8:9], v34 offset0:144 offset1:148
	ds_read2st64_b32 v[10:11], v35 offset0:144 offset1:148
	ds_read2st64_b32 v[12:13], v34 offset0:152 offset1:156
	ds_read2st64_b32 v[14:15], v35 offset0:152 offset1:156
	ds_read2st64_b32 v[16:17], v34 offset0:160 offset1:164
	ds_read2st64_b32 v[18:19], v35 offset0:160 offset1:164
	ds_read2st64_b32 v[20:21], v34 offset0:168 offset1:172
	ds_read2st64_b32 v[22:23], v35 offset0:168 offset1:172
	ds_read2st64_b32 v[24:25], v34 offset0:176 offset1:180
	ds_read2st64_b32 v[26:27], v35 offset0:176 offset1:180
	ds_read2st64_b32 v[28:29], v34 offset0:184 offset1:188
	ds_read2st64_b32 v[30:31], v35 offset0:184 offset1:188
	s_waitcnt lgkmcnt(14)
	v_fma_f32 v2, v0, v33, v2
	v_mul_f32_e32 v0, v32, v0
	v_fmac_f32_e32 v3, v1, v2
	v_mul_f32_e32 v0, v0, v1
	s_waitcnt lgkmcnt(12)
	v_fma_f32 v1, v4, v3, v6
	v_mul_f32_e32 v0, v0, v4
	v_fmac_f32_e32 v7, v5, v1
	v_mul_f32_e32 v0, v0, v5
	s_waitcnt lgkmcnt(10)
	v_fma_f32 v1, v8, v7, v10
	v_mul_f32_e32 v0, v0, v8
	v_fmac_f32_e32 v11, v9, v1
	v_mul_f32_e32 v0, v0, v9
	s_waitcnt lgkmcnt(8)
	v_fma_f32 v1, v12, v11, v14
	v_mul_f32_e32 v0, v0, v12
	v_fmac_f32_e32 v15, v13, v1
	v_mul_f32_e32 v0, v0, v13
	s_waitcnt lgkmcnt(6)
	v_fma_f32 v1, v16, v15, v18
	v_mul_f32_e32 v0, v0, v16
	v_fmac_f32_e32 v19, v17, v1
	v_mul_f32_e32 v0, v0, v17
	s_waitcnt lgkmcnt(4)
	v_fma_f32 v1, v20, v19, v22
	v_mul_f32_e32 v0, v0, v20
	v_fmac_f32_e32 v23, v21, v1
	v_mul_f32_e32 v0, v0, v21
	s_waitcnt lgkmcnt(2)
	v_fma_f32 v1, v24, v23, v26
	v_mul_f32_e32 v0, v0, v24
	v_fmac_f32_e32 v27, v25, v1
	v_mul_f32_e32 v0, v0, v25
	s_waitcnt lgkmcnt(0)
	v_fma_f32 v1, v28, v27, v30
	v_mul_f32_e32 v0, v0, v28
	v_fmac_f32_e32 v31, v29, v1
	v_mul_f32_e32 v30, v0, v29
	ds_read2st64_b32 v[0:1], v34 offset0:192 offset1:196
	ds_read2st64_b32 v[2:3], v35 offset0:192 offset1:196
	ds_read2st64_b32 v[4:5], v34 offset0:200 offset1:204
	ds_read2st64_b32 v[6:7], v35 offset0:200 offset1:204
	ds_read2st64_b32 v[8:9], v34 offset0:208 offset1:212
	ds_read2st64_b32 v[10:11], v35 offset0:208 offset1:212
	ds_read2st64_b32 v[12:13], v34 offset0:216 offset1:220
	ds_read2st64_b32 v[14:15], v35 offset0:216 offset1:220
	ds_read2st64_b32 v[16:17], v34 offset0:224 offset1:228
	ds_read2st64_b32 v[18:19], v35 offset0:224 offset1:228
	ds_read2st64_b32 v[20:21], v34 offset0:232 offset1:236
	ds_read2st64_b32 v[22:23], v35 offset0:232 offset1:236
	ds_read2st64_b32 v[24:25], v34 offset0:240 offset1:244
	ds_read2st64_b32 v[26:27], v35 offset0:240 offset1:244
	ds_read2st64_b32 v[28:29], v34 offset0:248 offset1:252
	ds_read2st64_b32 v[32:33], v35 offset0:248 offset1:252
	s_waitcnt lgkmcnt(14)
	v_fma_f32 v2, v0, v31, v2
	v_mul_f32_e32 v0, v30, v0
	v_fmac_f32_e32 v3, v1, v2
	v_mul_f32_e32 v0, v0, v1
	s_waitcnt lgkmcnt(12)
	v_fma_f32 v1, v4, v3, v6
	v_mul_f32_e32 v0, v0, v4
	v_fmac_f32_e32 v7, v5, v1
	v_mul_f32_e32 v0, v0, v5
	s_waitcnt lgkmcnt(10)
	v_fma_f32 v1, v8, v7, v10
	v_mul_f32_e32 v0, v0, v8
	v_fmac_f32_e32 v11, v9, v1
	v_mul_f32_e32 v0, v0, v9
	s_waitcnt lgkmcnt(8)
	v_fma_f32 v1, v12, v11, v14
	v_mul_f32_e32 v0, v0, v12
	v_fmac_f32_e32 v15, v13, v1
	v_mul_f32_e32 v0, v0, v13
	s_waitcnt lgkmcnt(6)
	v_fma_f32 v1, v16, v15, v18
	v_mul_f32_e32 v0, v0, v16
	v_fmac_f32_e32 v19, v17, v1
	v_mul_f32_e32 v0, v0, v17
	s_waitcnt lgkmcnt(4)
	v_fma_f32 v1, v20, v19, v22
	v_mul_f32_e32 v0, v0, v20
	v_fmac_f32_e32 v23, v21, v1
	v_mul_f32_e32 v0, v0, v21
	s_waitcnt lgkmcnt(2)
	v_fma_f32 v1, v24, v23, v26
	v_mul_f32_e32 v0, v0, v24
	v_fmac_f32_e32 v27, v25, v1
	v_mul_f32_e32 v0, v0, v25
	s_ashr_i32 s39, s38, 31
	s_waitcnt lgkmcnt(0)
	v_fma_f32 v1, v28, v27, v32
	v_mul_f32_e32 v0, v0, v28
	s_lshl_b64 s[4:5], s[38:39], 8
	v_ashrrev_i32_e32 v77, 31, v76
	v_fmac_f32_e32 v33, v29, v1
	v_mul_f32_e32 v4, v0, v29
	v_lshl_add_u64 v[0:1], s[4:5], 0, v[76:77]
	v_readlane_b32 s4, v252, 56
	v_lshlrev_b64 v[0:1], 2, v[0:1]
	v_readlane_b32 s5, v252, 57
	s_nop 1
	v_lshl_add_u64 v[2:3], s[4:5], 0, v[0:1]
	v_readlane_b32 s4, v252, 54
	v_readlane_b32 s5, v252, 55
	global_store_dword v[2:3], v4, off sc1
	s_nop 0
	v_lshl_add_u64 v[0:1], s[4:5], 0, v[0:1]
	global_store_dword v[0:1], v33, off sc1
	s_branch .LBB0_1256
